# fast logf (v_log_f32 * ln2), hazard-checked nop trimming, hgrn_pass_c state loads issued together, hand-written hgrn_pass_b for the latent half (8-deep load ring), rb1 loads moved into the MFMA shadow
# speedup vs baseline: 1.1210x; 1.0129x over previous
.LBB0_22:
	v_lshl_add_u64 v[4:5], s[8:9], 0, v[2:3]
	global_load_dword v8, v[4:5], off
	v_add_co_u32_e32 v4, vcc, 0x1000, v4
	v_add_u32_e32 v1, s74, v1
	s_nop 0
	v_addc_co_u32_e32 v5, vcc, 0, v5, vcc
	global_load_dword v9, v[4:5], off
	v_cmp_lt_i32_e32 vcc, s26, v1
	s_or_b64 s[24:25], vcc, s[24:25]
	v_lshl_add_u64 v[4:5], s[2:3], 0, v[2:3]
	v_lshl_add_u64 v[2:3], v[2:3], 0, s[4:5]
	s_waitcnt vmcnt(0)
	v_sub_f32_e32 v8, v9, v8
	v_mul_f32_e32 v8, 0x3fb8aa3b, v8
	v_exp_f32_e32 v8, v8
	s_nop 0
	v_add_f32_e32 v8, 1.0, v8
	v_rcp_f32_e32 v8, v8
	global_store_dword v[4:5], v8, off
	s_andn2_b64 exec, exec, s[24:25]
	s_cbranch_execnz .LBB0_22

.LBB0_299:
	v_add_u32_e32 v2, s10, v4
	v_mul_hi_i32 v3, v2, s30
	v_lshrrev_b32_e32 v6, 31, v3
	v_ashrrev_i32_e32 v3, 5, v3
	v_add_u32_e32 v3, v3, v6
	v_mad_u64_u32 v[6:7], s[2:3], v3, s47, v[2:3]
	v_mul_lo_u32 v3, v3, s48
	v_add_u32_e32 v9, 0, v5
	v_add3_u32 v3, 0, v3, v8
	ds_read_u16 v7, v9
	ds_read_u16 v12, v9 offset:384
	ds_read2st64_b32 v[10:11], v3 offset0:99 offset1:102
	ds_read_u16 v13, v9 offset:768
	ds_read_b32 v14, v3 offset:26880
	s_waitcnt lgkmcnt(4)
	v_lshlrev_b32_e32 v7, 16, v7
	s_waitcnt lgkmcnt(3)
	v_lshlrev_b32_e32 v3, 16, v12
	s_waitcnt lgkmcnt(2)
	v_mul_f32_e32 v3, v11, v3
	v_fmac_f32_e32 v3, v10, v7
	s_waitcnt lgkmcnt(1)
	v_lshlrev_b32_e32 v7, 16, v13
	s_waitcnt lgkmcnt(0)
	v_fmac_f32_e32 v3, v14, v7
	v_cmp_lt_i32_e32 vcc, 63, v6
	s_and_saveexec_b64 s[2:3], vcc
	s_xor_b64 s[2:3], exec, s[2:3]
	s_cbranch_execz .LBB0_303
	v_cmp_lt_u32_e32 vcc, s49, v6
	s_and_saveexec_b64 s[4:5], vcc
	s_cbranch_execz .LBB0_302
	v_mul_f32_e32 v3, 0xbfb8aa3b, v3
	v_exp_f32_e32 v3, v3
	s_nop 0
	v_add_f32_e32 v3, 1.0, v3
	v_rcp_f32_e32 v3, v3
.LBB0_302:
	s_or_b64 exec, exec, s[4:5]

.LBB0_305:
	s_or_b64 exec, exec, s[2:3]
	v_cvt_pk_bf16_f32 v3, v3, v3
	v_add_u32_e32 v6, 0x200, v2
	global_store_short v[0:1], v3, off offset:-3072
	v_mul_hi_i32 v3, v6, s30
	v_lshrrev_b32_e32 v7, 31, v3
	v_ashrrev_i32_e32 v3, 5, v3
	v_add_u32_e32 v3, v3, v7
	v_mad_u64_u32 v[6:7], s[2:3], v3, s47, v[6:7]
	v_mul_lo_u32 v3, v3, s48
	v_add3_u32 v3, 0, v3, v8
	ds_read_u16 v7, v9 offset:1024
	ds_read_u16 v12, v9 offset:1408
	ds_read2st64_b32 v[10:11], v3 offset0:107 offset1:110
	ds_read_b32 v13, v3 offset:28928
	ds_read_u16 v14, v9 offset:1792
	s_waitcnt lgkmcnt(4)
	v_lshlrev_b32_e32 v7, 16, v7
	s_waitcnt lgkmcnt(3)
	v_lshlrev_b32_e32 v3, 16, v12
	s_waitcnt lgkmcnt(2)
	v_mul_f32_e32 v3, v11, v3
	v_fmac_f32_e32 v3, v10, v7
	s_waitcnt lgkmcnt(0)
	v_lshlrev_b32_e32 v7, 16, v14
	v_fmac_f32_e32 v3, v13, v7
	v_cmp_lt_i32_e32 vcc, 63, v6
	s_and_saveexec_b64 s[2:3], vcc
	s_xor_b64 s[2:3], exec, s[2:3]
	s_cbranch_execz .LBB0_309
	v_cmp_lt_u32_e32 vcc, s49, v6
	s_and_saveexec_b64 s[4:5], vcc
	s_cbranch_execz .LBB0_308
	v_mul_f32_e32 v3, 0xbfb8aa3b, v3
	v_exp_f32_e32 v3, v3
	s_nop 0
	v_add_f32_e32 v3, 1.0, v3
	v_rcp_f32_e32 v3, v3
.LBB0_308:
	s_or_b64 exec, exec, s[4:5]

.LBB0_311:
	s_or_b64 exec, exec, s[2:3]
	v_cvt_pk_bf16_f32 v3, v3, v3
	v_add_u32_e32 v6, 0x400, v2
	global_store_short v[0:1], v3, off offset:-2048
	v_mul_hi_i32 v3, v6, s30
	v_lshrrev_b32_e32 v7, 31, v3
	v_ashrrev_i32_e32 v3, 5, v3
	v_add_u32_e32 v3, v3, v7
	v_mad_u64_u32 v[6:7], s[2:3], v3, s47, v[6:7]
	v_mul_lo_u32 v3, v3, s48
	v_add3_u32 v3, 0, v3, v8
	ds_read_u16 v7, v9 offset:2048
	ds_read_u16 v12, v9 offset:2432
	ds_read2st64_b32 v[10:11], v3 offset0:115 offset1:118
	ds_read_b32 v13, v3 offset:30976
	ds_read_u16 v14, v9 offset:2816
	s_waitcnt lgkmcnt(4)
	v_lshlrev_b32_e32 v7, 16, v7
	s_waitcnt lgkmcnt(3)
	v_lshlrev_b32_e32 v3, 16, v12
	s_waitcnt lgkmcnt(2)
	v_mul_f32_e32 v3, v11, v3
	v_fmac_f32_e32 v3, v10, v7
	s_waitcnt lgkmcnt(0)
	v_lshlrev_b32_e32 v7, 16, v14
	v_fmac_f32_e32 v3, v13, v7
	v_cmp_lt_i32_e32 vcc, 63, v6
	s_and_saveexec_b64 s[2:3], vcc
	s_xor_b64 s[2:3], exec, s[2:3]
	s_cbranch_execz .LBB0_315
	v_cmp_lt_u32_e32 vcc, s49, v6
	s_and_saveexec_b64 s[4:5], vcc
	s_cbranch_execz .LBB0_314
	v_mul_f32_e32 v3, 0xbfb8aa3b, v3
	v_exp_f32_e32 v3, v3
	s_nop 0
	v_add_f32_e32 v3, 1.0, v3
	v_rcp_f32_e32 v3, v3
.LBB0_314:
	s_or_b64 exec, exec, s[4:5]

.LBB0_317:
	s_or_b64 exec, exec, s[2:3]
	v_cvt_pk_bf16_f32 v3, v3, v3
	v_add_u32_e32 v2, 0x600, v2
	global_store_short v[0:1], v3, off offset:-1024
	v_mul_hi_i32 v3, v2, s30
	v_lshrrev_b32_e32 v6, 31, v3
	v_ashrrev_i32_e32 v3, 5, v3
	v_add_u32_e32 v6, v3, v6
	v_mad_u64_u32 v[2:3], s[2:3], v6, s47, v[2:3]
	v_mul_lo_u32 v3, v6, s48
	v_add3_u32 v3, 0, v3, v8
	ds_read_u16 v10, v9 offset:3072
	ds_read_u16 v11, v9 offset:3456
	ds_read2st64_b32 v[6:7], v3 offset0:123 offset1:126
	ds_read_b32 v12, v3 offset:33024
	ds_read_u16 v9, v9 offset:3840
	s_waitcnt lgkmcnt(4)
	v_lshlrev_b32_e32 v10, 16, v10
	s_waitcnt lgkmcnt(3)
	v_lshlrev_b32_e32 v3, 16, v11
	s_waitcnt lgkmcnt(2)
	v_mul_f32_e32 v3, v7, v3
	v_fmac_f32_e32 v3, v6, v10
	s_waitcnt lgkmcnt(0)
	v_lshlrev_b32_e32 v6, 16, v9
	v_fmac_f32_e32 v3, v12, v6
	v_cmp_lt_i32_e32 vcc, 63, v2
	s_and_saveexec_b64 s[2:3], vcc
	s_xor_b64 s[2:3], exec, s[2:3]
	s_cbranch_execz .LBB0_321
	v_cmp_lt_u32_e32 vcc, s49, v2
	s_and_saveexec_b64 s[4:5], vcc
	s_cbranch_execz .LBB0_320
	v_mul_f32_e32 v2, 0xbfb8aa3b, v3
	v_exp_f32_e32 v2, v2
	s_nop 0
	v_add_f32_e32 v2, 1.0, v2
	v_rcp_f32_e32 v3, v2
.LBB0_320:
	s_or_b64 exec, exec, s[4:5]

.LBB0_428:
	s_or_b64 exec, exec, s[0:1]
	s_movk_i32 s0, 0x100
	v_ashrrev_i32_e32 v158, 6, v150
	v_cmp_gt_u32_e64 s[38:39], s0, v150
	s_movk_i32 s0, 0xff
	v_and_b32_e32 v154, 3, v158
	s_waitcnt lgkmcnt(0)
	s_barrier
	v_cmp_lt_u32_e64 s[40:41], s0, v150
	s_lshl_b32 s0, s50, 6
	v_lshlrev_b32_e32 v155, 2, v152
	v_or_b32_e32 v0, s0, v149
	v_lshlrev_b32_e32 v153, 4, v154
	v_lshlrev_b32_e32 v2, 2, v0
	v_lshlrev_b32_e32 v164, 1, v149
	v_or_b32_e32 v151, v153, v149
	v_or_b32_e32 v148, v153, v155
	v_lshl_add_u32 v157, v149, 2, 0
	v_add_lshl_u32 v159, v149, s0, 2
	s_and_saveexec_b64 s[0:1], s[40:41]
	s_xor_b64 s[42:43], exec, s[0:1]
	s_cbranch_execz .LBB0_430
	v_readlane_b32 s80, v252, 18
	v_readlane_b32 s94, v252, 32
	v_readlane_b32 s95, v252, 33
	v_mul_u32_u24_e32 v0, 0x190, v151
	v_and_b32_e32 v3, 48, v150
	v_readlane_b32 s0, v254, 52
	v_readlane_b32 s81, v252, 19
	v_readlane_b32 s82, v252, 20
	global_load_dword v74, v2, s[94:95]
	v_readlane_b32 s83, v252, 21
	v_readlane_b32 s84, v252, 22
	v_readlane_b32 s85, v252, 23
	v_readlane_b32 s86, v252, 24
	v_readlane_b32 s87, v252, 25
	v_readlane_b32 s88, v252, 26
	v_readlane_b32 s89, v252, 27
	v_readlane_b32 s90, v252, 28
	v_readlane_b32 s91, v252, 29
	v_readlane_b32 s92, v252, 30
	v_readlane_b32 s93, v252, 31
	v_add3_u32 v0, s0, v0, v3
	s_mov_b64 s[62:63], s[94:95]
	v_readlane_b32 s80, v252, 35
	ds_read_b128 v[64:67], v0 offset:128
	v_readlane_b32 s84, v252, 39
	v_readlane_b32 s85, v252, 40
	v_readlane_b32 s86, v252, 41
	v_readlane_b32 s87, v252, 42
	v_readlane_b32 s88, v252, 43
	v_readlane_b32 s89, v252, 44
	v_readlane_b32 s90, v252, 45
	v_readlane_b32 s91, v252, 46
	v_readlane_b32 s92, v252, 47
	v_readlane_b32 s93, v252, 48
	s_mov_b64 s[52:53], s[84:85]
	s_mov_b64 s[54:55], s[86:87]
	global_load_dword v0, v2, s[52:53]
	global_load_dword v76, v2, s[54:55]
	v_mul_u32_u24_e32 v3, 0x300, v148
	v_add_u32_e32 v100, 0xc400, v157
	v_add_u32_e32 v102, 0xcc00, v157
	v_add_u32_e32 v103, 0xd000, v157
	v_add3_u32 v117, 0, v3, v164
	ds_read2_b32 v[72:73], v100 offset0:192 offset1:208
	ds_read2_b32 v[78:79], v102 offset0:64 offset1:80
	ds_read2_b32 v[84:85], v103 offset0:192 offset1:208
	ds_read_u16 v87, v117 offset:896
	ds_read_u16 v93, v117 offset:1664
	ds_read_u16 v3, v117 offset:2432
	ds_read_u16 v95, v117 offset:3200
	ds_read_u16 v99, v117 offset:3968
	s_waitcnt lgkmcnt(8)
	v_mfma_f32_16x16x32_bf16 v[68:71], v[64:67], v[24:27], 0
	s_waitcnt lgkmcnt(5)
	v_mov_b32_e32 v168, v85
	s_waitcnt lgkmcnt(2)
	v_lshlrev_b32_e32 v86, 16, v3
	v_lshlrev_b32_e32 v142, 16, v93
	s_waitcnt lgkmcnt(1)
	v_lshlrev_b32_e32 v143, 16, v95
	s_mov_b32 s4, 0x2b8cbccc
	s_mov_b32 s10, 0x45800000
	v_readlane_b32 s81, v252, 36
	v_readlane_b32 s82, v252, 37
	v_readlane_b32 s83, v252, 38
	v_readlane_b32 s94, v252, 49
	v_readlane_b32 s95, v252, 50
	s_mov_b64 s[56:57], s[88:89]
	s_mov_b64 s[58:59], s[90:91]
	s_mov_b64 s[60:61], s[92:93]
	s_waitcnt vmcnt(2)
	v_add_f32_e32 v2, v74, v68
	v_add_f32_e32 v3, v74, v69
	v_mul_f32_e32 v2, 0xbfb8aa3b, v2
	v_mul_f32_e32 v3, 0xbfb8aa3b, v3
	v_exp_f32_e32 v2, v2
	v_exp_f32_e32 v3, v3
	s_nop 0
	v_pk_add_f32 v[2:3], v[2:3], 1.0 op_sel_hi:[1,0]
	v_rcp_f32_e32 v3, v3
	v_div_scale_f32 v68, s[0:1], v2, v2, 1.0
	v_rcp_f32_e32 v69, v68
	s_nop 0
	v_fma_f32 v75, -v68, v69, 1.0
	v_fmac_f32_e32 v69, v75, v69
	v_div_scale_f32 v75, vcc, 1.0, v2, 1.0
	v_mul_f32_e32 v77, v75, v69
	v_fma_f32 v80, -v68, v77, v75
	v_fmac_f32_e32 v77, v80, v69
	global_load_dword v81, v159, s[62:63] offset:64
	global_load_dword v92, v159, s[52:53] offset:64
	global_load_dword v80, v159, s[54:55] offset:64
	v_fma_f32 v68, -v68, v77, v75
	v_div_fmas_f32 v68, v68, v69, v77
	v_div_fixup_f32 v2, v68, v2, 1.0
	v_pk_add_f32 v[68:69], v[2:3], -1.0 op_sel_hi:[1,0]
	ds_read_u16 v109, v117 offset:128
	ds_read_u16 v113, v117 offset:160
	ds_read_u16 v115, v117 offset:928
	ds_read_u16 v118, v117 offset:1696
	s_waitcnt vmcnt(3)
	v_pk_fma_f32 v[88:89], v[76:77], v[68:69], 1.0 op_sel_hi:[0,1,0]
	v_add_f32_e32 v68, v74, v70
	v_add_f32_e32 v69, v74, v71
	v_mul_f32_e32 v68, 0xbfb8aa3b, v68
	v_mul_f32_e32 v69, 0xbfb8aa3b, v69
	v_exp_f32_e32 v68, v68
	v_exp_f32_e32 v69, v69
	ds_read_u16 v82, v117 offset:2464
	ds_read_u16 v119, v117 offset:3232
	ds_read_u16 v120, v117 offset:4000
	v_pk_add_f32 v[68:69], v[68:69], 1.0 op_sel_hi:[1,0]
	s_waitcnt lgkmcnt(3)
	v_lshlrev_b32_e32 v140, 16, v118
	s_waitcnt lgkmcnt(2)
	v_lshlrev_b32_e32 v94, 16, v82
	s_waitcnt lgkmcnt(1)
	v_lshlrev_b32_e32 v141, 16, v119
	v_rcp_f32_e32 v75, v69
	v_div_scale_f32 v69, s[0:1], v68, v68, 1.0
	v_rcp_f32_e32 v70, v69
	s_nop 0
	v_fma_f32 v71, -v69, v70, 1.0
	v_fmac_f32_e32 v70, v71, v70
	v_div_scale_f32 v71, vcc, 1.0, v68, 1.0
	v_mul_f32_e32 v74, v71, v70
	v_fma_f32 v77, -v69, v74, v71
	v_fmac_f32_e32 v74, v77, v70
	v_fma_f32 v69, -v69, v74, v71
	v_div_fmas_f32 v69, v69, v70, v74
	v_div_fixup_f32 v74, v69, v68, 1.0
	v_pk_add_f32 v[68:69], v[74:75], -1.0 op_sel_hi:[1,0]
	v_pk_fma_f32 v[76:77], v[76:77], v[68:69], 1.0 op_sel_hi:[0,1,0]
	v_mfma_f32_16x16x32_bf16 v[68:71], v[64:67], v[32:35], 0
	s_waitcnt vmcnt(2)
	s_nop 6
	v_add_f32_e32 v68, v81, v68
	v_add_f32_e32 v69, v81, v69
	v_mul_f32_e32 v68, 0xbfb8aa3b, v68
	v_mul_f32_e32 v69, 0xbfb8aa3b, v69
	v_exp_f32_e32 v68, v68
	v_exp_f32_e32 v69, v69
	s_nop 0
	v_pk_add_f32 v[68:69], v[68:69], 1.0 op_sel_hi:[1,0]
	v_rcp_f32_e32 v91, v69
	v_rcp_f32_e32 v90, v68
	s_nop 0
	v_pk_add_f32 v[68:69], v[90:91], -1.0 op_sel_hi:[1,0]
	s_waitcnt vmcnt(0)
	v_pk_fma_f32 v[96:97], v[80:81], v[68:69], 1.0 op_sel_hi:[0,1,0]
	v_add_f32_e32 v68, v81, v70
	v_add_f32_e32 v69, v81, v71
	v_mul_f32_e32 v68, 0xbfb8aa3b, v68
	v_mul_f32_e32 v69, 0xbfb8aa3b, v69
	v_exp_f32_e32 v68, v68
	v_exp_f32_e32 v69, v69
	s_nop 0
	v_pk_add_f32 v[68:69], v[68:69], 1.0 op_sel_hi:[1,0]
	v_rcp_f32_e32 v107, v69
	v_div_scale_f32 v69, s[0:1], v68, v68, 1.0
	v_rcp_f32_e32 v70, v69
	s_nop 0
	v_fma_f32 v71, -v69, v70, 1.0
	v_fmac_f32_e32 v70, v71, v70
	v_div_scale_f32 v71, vcc, 1.0, v68, 1.0
	v_mul_f32_e32 v81, v71, v70
	v_fma_f32 v82, -v69, v81, v71
	v_fmac_f32_e32 v81, v82, v70
	global_load_dword v83, v159, s[62:63] offset:128
	global_load_dword v98, v159, s[52:53] offset:128
	global_load_dword v82, v159, s[54:55] offset:128
	v_fma_f32 v69, -v69, v81, v71
	v_div_fmas_f32 v69, v69, v70, v81
	v_div_fixup_f32 v106, v69, v68, 1.0
	v_pk_add_f32 v[68:69], v[106:107], -1.0 op_sel_hi:[1,0]
	ds_read2_b32 v[100:101], v100 offset0:224 offset1:240
	ds_read2_b32 v[104:105], v102 offset0:96 offset1:112
	ds_read2_b32 v[102:103], v103 offset0:224 offset1:240
	ds_read_u16 v145, v117 offset:192
	ds_read_u16 v164, v117 offset:960
	ds_read_u16 v121, v117 offset:1728
	v_pk_fma_f32 v[80:81], v[80:81], v[68:69], 1.0 op_sel_hi:[0,1,0]
	v_mfma_f32_16x16x32_bf16 v[68:71], v[64:67], v[48:51], 0
	ds_read_u16 v108, v117 offset:2496
	ds_read_u16 v133, v117 offset:3264
	ds_read_u16 v134, v117 offset:4032
	v_mfma_f32_16x16x32_bf16 v[64:67], v[64:67], v[56:59], 0
	s_waitcnt lgkmcnt(6)
	v_mov_b32_e32 v144, v103
	s_waitcnt lgkmcnt(2)
	v_lshlrev_b32_e32 v108, 16, v108
	s_waitcnt lgkmcnt(1)
	v_lshlrev_b32_e32 v133, 16, v133
	s_waitcnt lgkmcnt(0)
	v_lshlrev_b32_e32 v135, 16, v134
	v_mov_b32_e32 v134, v133
	s_waitcnt vmcnt(2)
	v_add_f32_e32 v68, v83, v68
	v_add_f32_e32 v69, v83, v69
	v_mul_f32_e32 v68, 0xbfb8aa3b, v68
	v_mul_f32_e32 v69, 0xbfb8aa3b, v69
	v_exp_f32_e32 v68, v68
	v_exp_f32_e32 v69, v69
	v_add_f32_e32 v70, v83, v70
	v_add_f32_e32 v71, v83, v71
	v_mul_f32_e32 v70, 0xbfb8aa3b, v70
	v_pk_add_f32 v[68:69], v[68:69], 1.0 op_sel_hi:[1,0]
	v_mul_f32_e32 v71, 0xbfb8aa3b, v71
	v_exp_f32_e32 v70, v70
	v_exp_f32_e32 v71, v71
	v_rcp_f32_e32 v69, v69
	v_pk_add_f32 v[70:71], v[70:71], 1.0 op_sel_hi:[1,0]
	v_rcp_f32_e32 v68, v68
	s_nop 0
	v_pk_add_f32 v[110:111], v[68:69], -1.0 op_sel_hi:[1,0]
	s_waitcnt vmcnt(0)
	v_pk_fma_f32 v[110:111], v[82:83], v[110:111], 1.0 op_sel_hi:[0,1,0]
	v_rcp_f32_e32 v71, v71
	v_div_scale_f32 v83, s[0:1], v70, v70, 1.0
	v_rcp_f32_e32 v112, v83
	s_nop 0
	v_fma_f32 v114, -v83, v112, 1.0
	v_fmac_f32_e32 v112, v114, v112
	v_div_scale_f32 v114, vcc, 1.0, v70, 1.0
	v_mul_f32_e32 v116, v114, v112
	v_fma_f32 v122, -v83, v116, v114
	v_fmac_f32_e32 v116, v122, v112
	v_fma_f32 v83, -v83, v116, v114
	v_div_fmas_f32 v83, v83, v112, v116
	global_load_dword v128, v159, s[62:63] offset:192
	global_load_dword v112, v159, s[52:53] offset:192
	global_load_dword v116, v159, s[54:55] offset:192
	v_div_fixup_f32 v70, v83, v70, 1.0
	v_pk_add_f32 v[122:123], v[70:71], -1.0 op_sel_hi:[1,0]
	ds_read_u16 v159, v117 offset:224
	ds_read_u16 v165, v117 offset:992
	ds_read_u16 v130, v117 offset:1760
	v_pk_fma_f32 v[82:83], v[82:83], v[122:123], 1.0 op_sel_hi:[0,1,0]
	ds_read_u16 v114, v117 offset:2528
	ds_read_u16 v132, v117 offset:3296
	s_waitcnt lgkmcnt(1)
	v_lshlrev_b32_e32 v114, 16, v114
	s_waitcnt vmcnt(2)
	v_add_f32_e32 v64, v128, v64
	v_add_f32_e32 v65, v128, v65
	v_mul_f32_e32 v64, 0xbfb8aa3b, v64
	v_mul_f32_e32 v65, 0xbfb8aa3b, v65
	v_exp_f32_e32 v64, v64
	v_exp_f32_e32 v65, v65
	s_nop 0
	v_pk_add_f32 v[64:65], v[64:65], 1.0 op_sel_hi:[1,0]
	v_rcp_f32_e32 v127, v65
	v_rcp_f32_e32 v126, v64
	s_nop 0
	v_pk_add_f32 v[64:65], v[126:127], -1.0 op_sel_hi:[1,0]
	s_waitcnt vmcnt(0)
	v_pk_fma_f32 v[122:123], v[116:117], v[64:65], 1.0 op_sel_hi:[0,1,0]
	v_add_f32_e32 v64, v128, v66
	v_add_f32_e32 v65, v128, v67
	v_mul_f32_e32 v64, 0xbfb8aa3b, v64
	v_mul_f32_e32 v65, 0xbfb8aa3b, v65
	v_exp_f32_e32 v64, v64
	v_exp_f32_e32 v65, v65
	ds_read_u16 v117, v117 offset:4064
	v_pk_add_f32 v[64:65], v[64:65], 1.0 op_sel_hi:[1,0]
	v_rcp_f32_e32 v129, v65
	v_and_b32_e32 v67, 64, v179
	v_xor_b32_e32 v66, 1, v179
	v_add_u32_e32 v67, 64, v67
	v_cmp_lt_i32_e32 vcc, v66, v67
	v_rcp_f32_e32 v128, v64
	s_nop 0
	v_pk_add_f32 v[64:65], v[128:129], -1.0 op_sel_hi:[1,0]
	v_cndmask_b32_e32 v66, v179, v66, vcc
	v_lshlrev_b32_e32 v169, 2, v66
	v_xor_b32_e32 v66, 2, v179
	v_cmp_lt_i32_e32 vcc, v66, v67
	s_waitcnt lgkmcnt(0)
	v_pk_fma_f32 v[64:65], v[116:117], v[64:65], 1.0 op_sel_hi:[0,1,0]
	v_lshlrev_b32_e32 v116, 16, v130
	v_cndmask_b32_e32 v66, v179, v66, vcc
	v_lshlrev_b32_e32 v170, 2, v66
	v_xor_b32_e32 v66, 4, v179
	v_cmp_lt_i32_e32 vcc, v66, v67
	v_lshlrev_b32_e32 v131, 16, v117
	v_lshlrev_b32_e32 v117, 16, v132
	v_cndmask_b32_e32 v66, v179, v66, vcc
	v_lshlrev_b32_e32 v171, 2, v66
	v_xor_b32_e32 v66, 8, v179
	v_cmp_lt_i32_e32 vcc, v66, v67
	v_mov_b32_e32 v67, v105
	v_mov_b32_e32 v130, v117
	v_cndmask_b32_e32 v66, v179, v66, vcc
	v_lshlrev_b32_e32 v172, 2, v66
	v_mov_b32_e32 v66, v101
	v_pk_mul_f32 v[136:137], v[66:67], v[114:115] op_sel:[1,0] op_sel_hi:[0,0]
	v_pk_fma_f32 v[66:67], v[66:67], v[116:117], v[136:137]
	v_lshlrev_b32_e32 v132, 16, v121
	v_pk_fma_f32 v[66:67], v[144:145], v[130:131], v[66:67] op_sel_hi:[0,1,1]
	v_pk_mul_f32 v[64:65], v[64:65], v[66:67]
	v_pk_mul_f32 v[130:131], v[112:113], v[66:67] op_sel_hi:[0,1]
	v_mov_b32_e32 v66, v100
	v_mov_b32_e32 v67, v104
	v_pk_mul_f32 v[136:137], v[66:67], v[108:109] op_sel:[1,0] op_sel_hi:[0,0]
	v_pk_fma_f32 v[66:67], v[66:67], v[132:133], v[136:137]
	v_lshlrev_b32_e32 v121, 16, v120
	v_pk_fma_f32 v[134:135], v[102:103], v[134:135], v[66:67] op_sel_hi:[0,1,1]
	v_pk_mul_f32 v[66:67], v[82:83], v[134:135]
	v_mov_b32_e32 v82, v73
	v_mov_b32_e32 v83, v79
	v_pk_mul_f32 v[118:119], v[82:83], v[94:95] op_sel:[1,0] op_sel_hi:[0,0]
	v_mov_b32_e32 v120, v141
	v_pk_fma_f32 v[82:83], v[82:83], v[140:141], v[118:119]
	v_pk_mul_f32 v[166:167], v[98:99], v[134:135] op_sel_hi:[0,1]
	v_pk_fma_f32 v[82:83], v[168:169], v[120:121], v[82:83] op_sel_hi:[0,1,1]
	v_pk_mul_f32 v[120:121], v[92:93], v[82:83] op_sel_hi:[0,1]
	v_pk_mul_f32 v[118:119], v[80:81], v[82:83]
	v_mov_b32_e32 v82, v72
	v_mov_b32_e32 v83, v78
	v_pk_mul_f32 v[136:137], v[82:83], v[86:87] op_sel:[1,0] op_sel_hi:[0,0]
	v_lshlrev_b32_e32 v135, 16, v99
	v_mov_b32_e32 v134, v143
	v_pk_fma_f32 v[82:83], v[82:83], v[142:143], v[136:137]
	v_pk_mul_f32 v[80:81], v[120:121], v[120:121]
	v_pk_fma_f32 v[82:83], v[84:85], v[134:135], v[82:83] op_sel_hi:[0,1,1]
	v_pk_mul_f32 v[138:139], v[0:1], v[82:83] op_sel_hi:[0,1]
	v_pk_mul_f32 v[136:137], v[76:77], v[82:83]
	v_pk_fma_f32 v[76:77], v[138:139], v[138:139], v[80:81]
	v_mov_b32_e32 v117, v114
	v_pk_fma_f32 v[76:77], v[166:167], v[166:167], v[76:77]
	v_mov_b32_e32 v114, v105
	v_pk_fma_f32 v[76:77], v[130:131], v[130:131], v[76:77]
	ds_bpermute_b32 v80, v169, v76
	ds_bpermute_b32 v81, v169, v77
	v_mov_b32_e32 v133, v108
	v_mov_b32_e32 v141, v94
	v_mov_b32_e32 v94, v73
	v_mov_b32_e32 v143, v86
	s_waitcnt lgkmcnt(0)
	v_pk_add_f32 v[76:77], v[76:77], v[80:81]
	ds_bpermute_b32 v80, v170, v76
	ds_bpermute_b32 v81, v170, v77
	s_waitcnt lgkmcnt(0)
	v_pk_add_f32 v[76:77], v[76:77], v[80:81]
	ds_bpermute_b32 v80, v171, v76
	ds_bpermute_b32 v81, v171, v77
	s_waitcnt lgkmcnt(0)
	v_pk_add_f32 v[76:77], v[76:77], v[80:81]
	ds_bpermute_b32 v80, v172, v76
	ds_bpermute_b32 v81, v172, v77
	s_waitcnt lgkmcnt(0)
	v_pk_add_f32 v[76:77], v[76:77], v[80:81]
	s_nop 0
	v_pk_add_f32 v[76:77], v[76:77], s[4:5] op_sel_hi:[1,0]
	s_nop 0
	v_mul_f32_e32 v80, 0x4b800000, v76
	v_cmp_gt_f32_e64 s[0:1], s29, v76
	v_cmp_gt_f32_e32 vcc, s29, v77
	s_nop 0
	v_cndmask_b32_e64 v76, v76, v80, s[0:1]
	v_mul_f32_e32 v80, 0x4b800000, v77
	v_cndmask_b32_e32 v77, v77, v80, vcc
	v_rsq_f32_e32 v76, v76
	v_rsq_f32_e32 v77, v77
	s_nop 0
	v_pk_mul_f32 v[80:81], v[76:77], s[10:11] op_sel_hi:[1,0]
	s_nop 0
	v_cndmask_b32_e32 v135, v77, v81, vcc
	v_cndmask_b32_e64 v134, v76, v80, s[0:1]
	v_pk_mul_f32 v[80:81], v[138:139], v[134:135]
	v_pk_mul_f32 v[76:77], v[166:167], v[134:135]
	v_pk_mul_f32 v[138:139], v[74:75], v[80:81]
	v_pk_mul_f32 v[74:75], v[70:71], v[76:77]
	v_lshlrev_b32_e32 v71, 16, v165
	v_lshlrev_b32_e32 v70, 16, v159
	v_pk_mul_f32 v[82:83], v[120:121], v[134:135]
	v_pk_mov_b32 v[166:167], v[70:71], v[116:117] op_sel:[1,0]
	v_pk_mul_f32 v[120:121], v[106:107], v[82:83]
	v_mov_b32_e32 v106, v101
	v_pk_mul_f32 v[166:167], v[114:115], v[166:167] op_sel_hi:[0,1]
	v_pk_fma_f32 v[70:71], v[106:107], v[70:71], v[166:167] op_sel_hi:[0,1,1]
	v_pk_fma_f32 v[106:107], v[144:145], v[116:117], v[70:71] op_sel_hi:[0,1,1]
	v_lshlrev_b32_e32 v117, 16, v164
	v_lshlrev_b32_e32 v116, 16, v145
	v_pk_mul_f32 v[70:71], v[122:123], v[106:107]
	v_pk_mov_b32 v[122:123], v[116:117], v[132:133] op_sel:[1,0]
	v_pk_mul_f32 v[106:107], v[112:113], v[106:107] op_sel_hi:[0,1]
	v_pk_mul_f32 v[104:105], v[104:105], v[122:123] op_sel_hi:[0,1]
	v_pk_fma_f32 v[100:101], v[100:101], v[116:117], v[104:105] op_sel_hi:[0,1,1]
	v_pk_fma_f32 v[100:101], v[102:103], v[132:133], v[100:101] op_sel_hi:[0,1,1]
	v_pk_mul_f32 v[116:117], v[110:111], v[100:101]
	v_pk_mul_f32 v[98:99], v[98:99], v[100:101] op_sel_hi:[0,1]
	v_lshlrev_b32_e32 v101, 16, v115
	v_lshlrev_b32_e32 v100, 16, v113
	v_mov_b32_e32 v102, v79
	v_pk_mov_b32 v[104:105], v[100:101], v[140:141] op_sel:[1,0]
	s_nop 0
	v_pk_mul_f32 v[102:103], v[102:103], v[104:105] op_sel_hi:[0,1]
	v_pk_fma_f32 v[94:95], v[94:95], v[100:101], v[102:103] op_sel_hi:[0,1,1]
	v_pk_fma_f32 v[94:95], v[168:169], v[140:141], v[94:95] op_sel_hi:[0,1,1]
	v_pk_mul_f32 v[132:133], v[96:97], v[94:95]
	v_lshlrev_b32_e32 v97, 16, v87
	v_lshlrev_b32_e32 v96, 16, v109
	v_pk_mov_b32 v[86:87], v[96:97], v[142:143] op_sel:[1,0]
	v_pk_mul_f32 v[92:93], v[92:93], v[94:95] op_sel_hi:[0,1]
	v_pk_mul_f32 v[78:79], v[78:79], v[86:87] op_sel_hi:[0,1]
	v_pk_fma_f32 v[72:73], v[72:73], v[96:97], v[78:79] op_sel_hi:[0,1,1]
	v_pk_fma_f32 v[72:73], v[84:85], v[142:143], v[72:73] op_sel_hi:[0,1,1]
	v_pk_mul_f32 v[94:95], v[92:93], v[92:93]
	v_pk_mul_f32 v[78:79], v[0:1], v[72:73] op_sel_hi:[0,1]
	v_pk_mul_f32 v[142:143], v[88:89], v[72:73]
	v_pk_fma_f32 v[72:73], v[78:79], v[78:79], v[94:95]
	s_nop 0
	v_pk_fma_f32 v[72:73], v[98:99], v[98:99], v[72:73]
	s_nop 0
	v_pk_fma_f32 v[72:73], v[106:107], v[106:107], v[72:73]
	ds_bpermute_b32 v84, v169, v72
	ds_bpermute_b32 v85, v169, v73
	s_waitcnt lgkmcnt(0)
	v_pk_add_f32 v[72:73], v[72:73], v[84:85]
	ds_bpermute_b32 v84, v170, v72
	ds_bpermute_b32 v85, v170, v73
	s_waitcnt lgkmcnt(0)
	v_pk_add_f32 v[72:73], v[72:73], v[84:85]
	ds_bpermute_b32 v84, v171, v72
	ds_bpermute_b32 v85, v171, v73
	s_waitcnt lgkmcnt(0)
	v_pk_add_f32 v[72:73], v[72:73], v[84:85]
	ds_bpermute_b32 v84, v172, v72
	ds_bpermute_b32 v85, v172, v73
	s_waitcnt lgkmcnt(0)
	v_pk_add_f32 v[72:73], v[72:73], v[84:85]
	s_nop 0
	v_pk_add_f32 v[72:73], v[72:73], s[4:5] op_sel_hi:[1,0]
	s_nop 0
	v_mul_f32_e32 v0, 0x4b800000, v72
	v_cmp_gt_f32_e64 s[0:1], s29, v72
	v_cmp_gt_f32_e32 vcc, s29, v73
	s_nop 0
	v_cndmask_b32_e64 v0, v72, v0, s[0:1]
	v_rsq_f32_e32 v72, v0
	v_mul_f32_e32 v0, 0x4b800000, v73
	v_cndmask_b32_e32 v0, v73, v0, vcc
	v_rsq_f32_e32 v73, v0
	s_nop 0
	v_pk_mul_f32 v[84:85], v[72:73], s[10:11] op_sel_hi:[1,0]
	s_nop 0
	v_cndmask_b32_e32 v73, v73, v85, vcc
	v_cndmask_b32_e64 v72, v72, v84, s[0:1]
	v_pk_mul_f32 v[84:85], v[78:79], v[72:73]
	v_pk_mul_f32 v[78:79], v[98:99], v[72:73]
	v_pk_mul_f32 v[86:87], v[92:93], v[72:73]
	v_pk_mul_f32 v[122:123], v[68:69], v[78:79]
	v_pk_mul_f32 v[112:113], v[106:107], v[72:73]
	v_pk_mul_f32 v[68:69], v[130:131], v[134:135]
	v_pk_mul_f32 v[144:145], v[2:3], v[84:85]
	v_pk_mul_f32 v[140:141], v[90:91], v[86:87]
	v_pk_mul_f32 v[114:115], v[126:127], v[112:113]
	v_pk_mul_f32 v[72:73], v[128:129], v[68:69]
.LBB0_430:
	s_or_saveexec_b64 s[0:1], s[42:43]
	v_mov_b32_e32 v130, 0
	v_mov_b32_e32 v131, 0
	v_mov_b32_e32 v126, 0
	v_mov_b32_e32 v127, 0
	v_mov_b32_e32 v108, 0
	v_mov_b32_e32 v109, 0
	v_mov_b32_e32 v104, 0
	v_mov_b32_e32 v105, 0
	v_mov_b32_e32 v100, 0
	v_mov_b32_e32 v101, 0
	v_mov_b32_e32 v96, 0
	v_mov_b32_e32 v97, 0
	v_mov_b32_e32 v92, 0
	v_mov_b32_e32 v93, 0
	v_mov_b32_e32 v88, 0
	v_mov_b32_e32 v89, 0
	v_mov_b32_e32 v134, 0
	v_mov_b32_e32 v135, 0
	v_mov_b32_e32 v128, 0
	v_mov_b32_e32 v129, 0
	v_mov_b32_e32 v110, 0
	v_mov_b32_e32 v111, 0
	v_mov_b32_e32 v106, 0
	v_mov_b32_e32 v107, 0
	v_mov_b32_e32 v102, 0
	v_mov_b32_e32 v103, 0
	v_mov_b32_e32 v98, 0
	v_mov_b32_e32 v99, 0
	v_mov_b32_e32 v94, 0
	v_mov_b32_e32 v95, 0
	v_mov_b32_e32 v90, 0
	v_mov_b32_e32 v91, 0
	s_xor_b64 exec, exec, s[0:1]
	s_cbranch_execz .LBB0_432
	v_lshlrev_b32_e32 v0, 4, v158
	v_readlane_b32 s80, v252, 18
	v_or_b32_e32 v3, v0, v149
	v_readlane_b32 s88, v252, 26
	v_readlane_b32 s89, v252, 27
	v_mul_lo_u32 v3, v3, s6
	v_lshlrev_b32_e32 v64, 4, v152
	v_readlane_b32 s4, v254, 52
	v_readlane_b32 s90, v252, 28
	v_readlane_b32 s91, v252, 29
	s_mov_b64 s[56:57], s[88:89]
	v_add3_u32 v3, s4, v3, v64
	s_mov_b64 s[58:59], s[90:91]
	ds_read_b128 v[64:67], v3
	ds_read_b128 v[68:71], v3 offset:64
	global_load_dword v92, v2, s[58:59]
	global_load_dword v94, v2, s[58:59] offset:2048
	s_waitcnt lgkmcnt(1)
	v_mfma_f32_16x16x32_bf16 v[72:75], v[64:67], v[24:27], 0
	s_mov_b32 s6, 0xbf1b4598
	v_or_b32_e32 v0, v155, v0
	v_mul_lo_u32 v0, v0, s13
	s_waitcnt lgkmcnt(0)
	v_mfma_f32_16x16x32_bf16 v[76:79], v[68:71], v[20:23], 0
	v_add_u32_e32 v104, 0xc800, v157
	v_add_u32_e32 v105, 0xcc00, v157
	v_add_u32_e32 v106, 0xd400, v157
	v_add3_u32 v0, 0, v0, v164
	ds_read2_b32 v[2:3], v104 offset1:16
	ds_read2_b32 v[82:83], v105 offset0:128 offset1:144
	ds_read2_b32 v[86:87], v106 offset1:16
	v_readlane_b32 s81, v252, 19
	v_readlane_b32 s82, v252, 20
	v_readlane_b32 s83, v252, 21
	v_readlane_b32 s84, v252, 22
	v_readlane_b32 s85, v252, 23
	v_readlane_b32 s86, v252, 24
	v_readlane_b32 s87, v252, 25
	v_readlane_b32 s92, v252, 30
	v_readlane_b32 s93, v252, 31
	v_readlane_b32 s94, v252, 32
	v_readlane_b32 s95, v252, 33
	s_waitcnt vmcnt(1)
	v_add_f32_e32 v72, v72, v92
	v_mul_f32_e32 v72, 0xbfb8aa3b, v72
	v_exp_f32_e32 v81, v72
	s_waitcnt vmcnt(0)
	v_add_f32_e32 v72, v76, v94
	v_mul_f32_e32 v72, 0xbfb8aa3b, v72
	v_exp_f32_e32 v85, v72
	v_add_f32_e32 v72, v73, v92
	v_mul_f32_e32 v72, 0xbfb8aa3b, v72
	v_exp_f32_e32 v80, v72
	s_nop 0
	v_pk_add_f32 v[72:73], v[80:81], 1.0 op_sel_hi:[1,0]
	v_rcp_f32_e32 v73, v73
	v_rcp_f32_e32 v72, v72
	s_nop 0
	v_pk_mul_f32 v[88:89], v[72:73], s[6:7] op_sel_hi:[1,0]
	v_add_f32_e32 v72, v77, v94
	v_mul_f32_e32 v72, 0xbfb8aa3b, v72
	v_exp_f32_e32 v84, v72
	s_nop 0
	v_pk_add_f32 v[72:73], v[84:85], 1.0 op_sel_hi:[1,0]
	v_rcp_f32_e32 v73, v73
	v_rcp_f32_e32 v72, v72
	s_nop 0
	v_pk_mul_f32 v[90:91], v[72:73], s[6:7] op_sel_hi:[1,0]
	v_add_f32_e32 v72, v74, v92
	v_mul_f32_e32 v72, 0xbfb8aa3b, v72
	v_exp_f32_e32 v73, v72
	v_add_f32_e32 v72, v78, v94
	v_mul_f32_e32 v72, 0xbfb8aa3b, v72
	v_exp_f32_e32 v77, v72
	v_add_f32_e32 v72, v75, v92
	v_mul_f32_e32 v72, 0xbfb8aa3b, v72
	v_exp_f32_e32 v72, v72
	s_nop 0
	v_pk_add_f32 v[72:73], v[72:73], 1.0 op_sel_hi:[1,0]
	v_rcp_f32_e32 v73, v73
	v_rcp_f32_e32 v72, v72
	s_nop 0
	v_pk_mul_f32 v[92:93], v[72:73], s[6:7] op_sel_hi:[1,0]
	v_add_f32_e32 v72, v79, v94
	v_mul_f32_e32 v72, 0xbfb8aa3b, v72
	v_exp_f32_e32 v76, v72
	s_nop 0
	v_pk_add_f32 v[72:73], v[76:77], 1.0 op_sel_hi:[1,0]
	v_rcp_f32_e32 v73, v73
	v_rcp_f32_e32 v72, v72
	s_nop 0
	v_pk_mul_f32 v[94:95], v[72:73], s[6:7] op_sel_hi:[1,0]
	ds_read_u16 v72, v0 offset:1792
	ds_read_u16 v73, v0 offset:2560
	ds_read_u16 v74, v0 offset:3328
	ds_read_u16 v75, v0 offset:4096
	s_waitcnt lgkmcnt(3)
	v_lshlrev_b32_e32 v72, 16, v72
	s_waitcnt lgkmcnt(1)
	v_lshlrev_b32_e32 v77, 16, v74
	ds_read_u16 v74, v0 offset:1024
	v_lshlrev_b32_e32 v73, 16, v73
	v_mov_b32_e32 v76, v73
	s_waitcnt lgkmcnt(1)
	v_lshlrev_b32_e32 v75, 16, v75
	s_waitcnt lgkmcnt(0)
	v_lshlrev_b32_e32 v79, 16, v74
	ds_read_u16 v74, v0 offset:256
	ds_read_u16 v107, v0 offset:288
	s_waitcnt lgkmcnt(1)
	v_lshlrev_b32_e32 v78, 16, v74
	v_pk_mov_b32 v[80:81], v[78:79], v[72:73] op_sel:[1,0]
	v_mov_b32_e32 v74, v77
	v_pk_mul_f32 v[80:81], v[82:83], v[80:81] op_sel_hi:[0,1]
	v_pk_fma_f32 v[78:79], v[2:3], v[78:79], v[80:81] op_sel_hi:[0,1,1]
	v_pk_mul_f32 v[76:77], v[82:83], v[76:77] op_sel_hi:[0,1]
	v_pk_fma_f32 v[84:85], v[86:87], v[72:73], v[78:79] op_sel_hi:[0,1,1]
	v_pk_fma_f32 v[72:73], v[2:3], v[72:73], v[76:77] op_sel_hi:[0,1,1]
	global_load_dword v2, v159, s[58:59] offset:64
	global_load_dword v82, v159, s[58:59] offset:2112
	v_pk_fma_f32 v[80:81], v[86:87], v[74:75], v[72:73] op_sel_hi:[0,1,1]
	v_mfma_f32_16x16x32_bf16 v[72:75], v[68:71], v[28:31], 0
	v_mfma_f32_16x16x32_bf16 v[76:79], v[64:67], v[32:35], 0
	s_waitcnt vmcnt(0)
	s_nop 5
	v_add_f32_e32 v72, v72, v82
	v_mul_f32_e32 v72, 0xbfb8aa3b, v72
	v_add_f32_e32 v76, v76, v2
	v_exp_f32_e32 v99, v72
	v_add_f32_e32 v72, v77, v2
	v_mul_f32_e32 v76, 0xbfb8aa3b, v76
	v_mul_f32_e32 v72, 0xbfb8aa3b, v72
	v_exp_f32_e32 v97, v76
	v_exp_f32_e32 v96, v72
	s_nop 0
	v_pk_add_f32 v[76:77], v[96:97], 1.0 op_sel_hi:[1,0]
	v_rcp_f32_e32 v77, v77
	v_rcp_f32_e32 v76, v76
	v_add_f32_e32 v72, v73, v82
	v_mul_f32_e32 v72, 0xbfb8aa3b, v72
	v_exp_f32_e32 v98, v72
	v_pk_mul_f32 v[96:97], v[76:77], s[6:7] op_sel_hi:[1,0]
	v_pk_add_f32 v[72:73], v[98:99], 1.0 op_sel_hi:[1,0]
	v_rcp_f32_e32 v73, v73
	v_rcp_f32_e32 v72, v72
	s_nop 0
	v_pk_mul_f32 v[98:99], v[72:73], s[6:7] op_sel_hi:[1,0]
	v_add_f32_e32 v72, v78, v2
	v_mul_f32_e32 v72, 0xbfb8aa3b, v72
	v_exp_f32_e32 v73, v72
	v_add_f32_e32 v72, v74, v82
	v_add_f32_e32 v2, v79, v2
	v_mul_f32_e32 v72, 0xbfb8aa3b, v72
	v_mul_f32_e32 v2, 0xbfb8aa3b, v2
	v_exp_f32_e32 v77, v72
	v_exp_f32_e32 v72, v2
	s_nop 0
	v_pk_add_f32 v[72:73], v[72:73], 1.0 op_sel_hi:[1,0]
	v_rcp_f32_e32 v73, v73
	v_rcp_f32_e32 v72, v72
	v_add_f32_e32 v2, v75, v82
	v_mul_f32_e32 v2, 0xbfb8aa3b, v2
	v_exp_f32_e32 v76, v2
	v_pk_mul_f32 v[100:101], v[72:73], s[6:7] op_sel_hi:[1,0]
	s_waitcnt lgkmcnt(0)
	v_lshlrev_b32_e32 v78, 16, v107
	v_mov_b32_e32 v82, v83
	v_pk_add_f32 v[72:73], v[76:77], 1.0 op_sel_hi:[1,0]
	v_rcp_f32_e32 v73, v73
	v_rcp_f32_e32 v72, v72
	s_nop 0
	v_pk_mul_f32 v[102:103], v[72:73], s[6:7] op_sel_hi:[1,0]
	ds_read_u16 v2, v0 offset:1824
	ds_read_u16 v73, v0 offset:2592
	s_waitcnt lgkmcnt(1)
	v_lshlrev_b32_e32 v72, 16, v2
	ds_read_u16 v2, v0 offset:3360
	ds_read_u16 v74, v0 offset:4128
	s_waitcnt lgkmcnt(2)
	v_lshlrev_b32_e32 v73, 16, v73
	v_mov_b32_e32 v76, v73
	s_waitcnt lgkmcnt(1)
	v_lshlrev_b32_e32 v77, 16, v2
	ds_read_u16 v2, v0 offset:1056
	s_waitcnt lgkmcnt(1)
	v_lshlrev_b32_e32 v75, 16, v74
	v_mov_b32_e32 v74, v77
	v_pk_mul_f32 v[76:77], v[82:83], v[76:77] op_sel_hi:[0,1]
	s_waitcnt lgkmcnt(0)
	v_lshlrev_b32_e32 v79, 16, v2
	v_pk_mov_b32 v[108:109], v[78:79], v[72:73] op_sel:[1,0]
	v_mov_b32_e32 v2, v3
	v_pk_mul_f32 v[108:109], v[82:83], v[108:109] op_sel_hi:[0,1]
	v_pk_fma_f32 v[78:79], v[2:3], v[78:79], v[108:109] op_sel_hi:[0,1,1]
	v_mov_b32_e32 v108, v87
	v_pk_fma_f32 v[2:3], v[2:3], v[72:73], v[76:77] op_sel_hi:[0,1,1]
	v_pk_fma_f32 v[86:87], v[108:109], v[72:73], v[78:79] op_sel_hi:[0,1,1]
	v_pk_fma_f32 v[82:83], v[108:109], v[74:75], v[2:3] op_sel_hi:[0,1,1]
	global_load_dword v108, v159, s[58:59] offset:128
	global_load_dword v110, v159, s[58:59] offset:2176
	v_mfma_f32_16x16x32_bf16 v[72:75], v[68:71], v[36:39], 0
	ds_read2_b32 v[112:113], v104 offset0:32 offset1:48
	ds_read2_b32 v[114:115], v105 offset0:160 offset1:176
	ds_read2_b32 v[2:3], v106 offset0:32 offset1:48
	v_mfma_f32_16x16x32_bf16 v[76:79], v[64:67], v[48:51], 0
	s_waitcnt vmcnt(0)
	s_nop 2
	v_add_f32_e32 v72, v72, v110
	v_mul_f32_e32 v72, 0xbfb8aa3b, v72
	s_nop 1
	v_add_f32_e32 v76, v76, v108
	v_exp_f32_e32 v107, v72
	v_add_f32_e32 v72, v77, v108
	v_mul_f32_e32 v76, 0xbfb8aa3b, v76
	v_mul_f32_e32 v72, 0xbfb8aa3b, v72
	v_exp_f32_e32 v105, v76
	v_exp_f32_e32 v104, v72
	s_nop 0
	v_pk_add_f32 v[76:77], v[104:105], 1.0 op_sel_hi:[1,0]
	v_rcp_f32_e32 v77, v77
	v_rcp_f32_e32 v76, v76
	v_add_f32_e32 v72, v73, v110
	v_mul_f32_e32 v72, 0xbfb8aa3b, v72
	v_exp_f32_e32 v106, v72
	v_pk_mul_f32 v[104:105], v[76:77], s[6:7] op_sel_hi:[1,0]
	v_pk_add_f32 v[72:73], v[106:107], 1.0 op_sel_hi:[1,0]
	v_rcp_f32_e32 v73, v73
	v_rcp_f32_e32 v72, v72
	s_nop 0
	v_pk_mul_f32 v[106:107], v[72:73], s[6:7] op_sel_hi:[1,0]
	v_add_f32_e32 v72, v78, v108
	v_mul_f32_e32 v72, 0xbfb8aa3b, v72
	v_exp_f32_e32 v73, v72
	v_add_f32_e32 v72, v74, v110
	v_mul_f32_e32 v72, 0xbfb8aa3b, v72
	v_exp_f32_e32 v77, v72
	v_add_f32_e32 v72, v79, v108
	v_mul_f32_e32 v72, 0xbfb8aa3b, v72
	v_exp_f32_e32 v72, v72
	s_nop 0
	v_pk_add_f32 v[72:73], v[72:73], 1.0 op_sel_hi:[1,0]
	v_rcp_f32_e32 v73, v73
	v_rcp_f32_e32 v72, v72
	s_nop 0
	v_pk_mul_f32 v[108:109], v[72:73], s[6:7] op_sel_hi:[1,0]
	v_add_f32_e32 v72, v75, v110
	v_mul_f32_e32 v72, 0xbfb8aa3b, v72
	v_exp_f32_e32 v76, v72
	s_nop 0
	v_pk_add_f32 v[72:73], v[76:77], 1.0 op_sel_hi:[1,0]
	v_rcp_f32_e32 v73, v73
	v_rcp_f32_e32 v72, v72
	s_nop 0
	v_pk_mul_f32 v[110:111], v[72:73], s[6:7] op_sel_hi:[1,0]
	ds_read_u16 v72, v0 offset:1856
	ds_read_u16 v73, v0 offset:2624
	ds_read_u16 v74, v0 offset:3392
	ds_read_u16 v75, v0 offset:4160
	s_waitcnt lgkmcnt(3)
	v_lshlrev_b32_e32 v72, 16, v72
	s_waitcnt lgkmcnt(1)
	v_lshlrev_b32_e32 v77, 16, v74
	ds_read_u16 v74, v0 offset:320
	ds_read_u16 v78, v0 offset:1088
	v_lshlrev_b32_e32 v73, 16, v73
	v_mov_b32_e32 v76, v73
	s_waitcnt lgkmcnt(2)
	v_lshlrev_b32_e32 v75, 16, v75
	s_waitcnt lgkmcnt(0)
	v_lshlrev_b32_e32 v79, 16, v78
	v_lshlrev_b32_e32 v78, 16, v74
	v_pk_mov_b32 v[116:117], v[78:79], v[72:73] op_sel:[1,0]
	v_mov_b32_e32 v74, v77
	v_pk_mul_f32 v[116:117], v[114:115], v[116:117] op_sel_hi:[0,1]
	v_pk_fma_f32 v[78:79], v[112:113], v[78:79], v[116:117] op_sel_hi:[0,1,1]
	v_pk_mul_f32 v[76:77], v[114:115], v[76:77] op_sel_hi:[0,1]
	v_pk_fma_f32 v[78:79], v[2:3], v[72:73], v[78:79] op_sel_hi:[0,1,1]
	v_pk_fma_f32 v[72:73], v[112:113], v[72:73], v[76:77] op_sel_hi:[0,1,1]
	v_pk_fma_f32 v[76:77], v[2:3], v[74:75], v[72:73] op_sel_hi:[0,1,1]
	global_load_dword v2, v159, s[58:59] offset:192
	global_load_dword v112, v159, s[58:59] offset:2240
	v_mfma_f32_16x16x32_bf16 v[72:75], v[64:67], v[56:59], 0
	v_mfma_f32_16x16x32_bf16 v[64:67], v[68:71], v[60:63], 0
	s_waitcnt vmcnt(1)
	s_nop 5
	v_add_f32_e32 v68, v72, v2
	s_waitcnt vmcnt(0)
	v_add_f32_e32 v64, v64, v112
	v_mul_f32_e32 v64, 0xbfb8aa3b, v64
	v_exp_f32_e32 v71, v64
	v_add_f32_e32 v64, v73, v2
	v_mul_f32_e32 v68, 0xbfb8aa3b, v68
	v_mul_f32_e32 v64, 0xbfb8aa3b, v64
	v_exp_f32_e32 v69, v68
	v_exp_f32_e32 v68, v64
	s_nop 0
	v_pk_add_f32 v[68:69], v[68:69], 1.0 op_sel_hi:[1,0]
	v_rcp_f32_e32 v69, v69
	v_rcp_f32_e32 v68, v68
	v_add_f32_e32 v64, v65, v112
	v_mul_f32_e32 v64, 0xbfb8aa3b, v64
	v_exp_f32_e32 v70, v64
	v_pk_mul_f32 v[126:127], v[68:69], s[6:7] op_sel_hi:[1,0]
	v_pk_add_f32 v[64:65], v[70:71], 1.0 op_sel_hi:[1,0]
	v_rcp_f32_e32 v65, v65
	v_rcp_f32_e32 v64, v64
	s_nop 0
	v_pk_mul_f32 v[128:129], v[64:65], s[6:7] op_sel_hi:[1,0]
	v_add_f32_e32 v64, v74, v2
	v_mul_f32_e32 v64, 0xbfb8aa3b, v64
	v_exp_f32_e32 v65, v64
	v_add_f32_e32 v64, v66, v112
	v_add_f32_e32 v2, v75, v2
	v_mul_f32_e32 v64, 0xbfb8aa3b, v64
	v_mul_f32_e32 v2, 0xbfb8aa3b, v2
	v_exp_f32_e32 v69, v64
	v_exp_f32_e32 v64, v2
	s_nop 0
	v_pk_add_f32 v[64:65], v[64:65], 1.0 op_sel_hi:[1,0]
	v_rcp_f32_e32 v65, v65
	v_rcp_f32_e32 v64, v64
	v_add_f32_e32 v2, v67, v112
	v_mul_f32_e32 v2, 0xbfb8aa3b, v2
	v_exp_f32_e32 v68, v2
	v_pk_mul_f32 v[130:131], v[64:65], s[6:7] op_sel_hi:[1,0]
	v_pk_add_f32 v[64:65], v[68:69], 1.0 op_sel_hi:[1,0]
	v_rcp_f32_e32 v65, v65
	v_rcp_f32_e32 v64, v64
	s_nop 0
	v_pk_mul_f32 v[134:135], v[64:65], s[6:7] op_sel_hi:[1,0]
	ds_read_u16 v2, v0 offset:1888
	ds_read_u16 v65, v0 offset:2656
	s_waitcnt lgkmcnt(1)
	v_lshlrev_b32_e32 v64, 16, v2
	ds_read_u16 v2, v0 offset:3424
	ds_read_u16 v66, v0 offset:4192
	s_waitcnt lgkmcnt(2)
	v_lshlrev_b32_e32 v65, 16, v65
	v_mov_b32_e32 v68, v65
	s_waitcnt lgkmcnt(1)
	v_lshlrev_b32_e32 v69, 16, v2
	ds_read_u16 v2, v0 offset:352
	ds_read_u16 v0, v0 offset:1120
	s_waitcnt lgkmcnt(2)
	v_lshlrev_b32_e32 v67, 16, v66
	v_mov_b32_e32 v66, v69
	s_waitcnt lgkmcnt(1)
	v_lshlrev_b32_e32 v70, 16, v2
	s_waitcnt lgkmcnt(0)
	v_lshlrev_b32_e32 v71, 16, v0
	v_mov_b32_e32 v2, v115
	v_pk_mov_b32 v[72:73], v[70:71], v[64:65] op_sel:[1,0]
	v_mov_b32_e32 v0, v113
	v_pk_mul_f32 v[72:73], v[2:3], v[72:73] op_sel_hi:[0,1]
	v_pk_fma_f32 v[70:71], v[0:1], v[70:71], v[72:73] op_sel_hi:[0,1,1]
	v_mov_b32_e32 v72, v3
	v_pk_mul_f32 v[2:3], v[2:3], v[68:69] op_sel_hi:[0,1]
	v_pk_fma_f32 v[2:3], v[0:1], v[64:65], v[2:3] op_sel_hi:[0,1,1]
	v_pk_fma_f32 v[112:113], v[72:73], v[64:65], v[70:71] op_sel_hi:[0,1,1]
	v_pk_fma_f32 v[68:69], v[72:73], v[66:67], v[2:3] op_sel_hi:[0,1,1]
	v_mov_b32_e32 v72, 0
	v_mov_b32_e32 v73, v72
	v_mov_b32_e32 v114, v72
	v_mov_b32_e32 v115, v72
	v_mov_b32_e32 v74, v72
	v_mov_b32_e32 v75, v72
	v_mov_b32_e32 v122, v72
	v_mov_b32_e32 v123, v72
	v_mov_b32_e32 v120, v72
	v_mov_b32_e32 v121, v72
	v_mov_b32_e32 v140, v72
	v_mov_b32_e32 v141, v72
	v_mov_b32_e32 v138, v72
	v_mov_b32_e32 v139, v72
	v_mov_b32_e32 v144, v72
	v_mov_b32_e32 v145, v72
	v_mov_b32_e32 v64, v72
	v_mov_b32_e32 v65, v72
	v_mov_b32_e32 v70, v72
	v_mov_b32_e32 v71, v72
	v_mov_b32_e32 v66, v72
	v_mov_b32_e32 v67, v72
	v_mov_b32_e32 v116, v72
	v_mov_b32_e32 v117, v72
	v_mov_b32_e32 v118, v72
	v_mov_b32_e32 v119, v72
	v_mov_b32_e32 v132, v72
	v_mov_b32_e32 v133, v72
	v_mov_b32_e32 v136, v72
	v_mov_b32_e32 v137, v72
	v_mov_b32_e32 v142, v72
	v_mov_b32_e32 v143, v72

.LBB0_657:
	s_and_b32 s25, s24, 1
	s_cmp_eq_u32 s25, 0
	s_cselect_b64 s[64:65], -1, 0
	s_waitcnt vmcnt(4)
	ds_write_b128 v61, v[2:5] offset:40960
	s_waitcnt vmcnt(3)
	ds_write_b128 v62, v[6:9] offset:40960
	s_waitcnt vmcnt(2)
	ds_write_b128 v63, v[10:13] offset:40960
	s_waitcnt vmcnt(0)
	ds_write_b128 v64, v[14:17] offset:40960
	v_cndmask_b32_e64 v18, v66, v65, s[64:65]
	s_waitcnt lgkmcnt(0)
	s_barrier
	v_mad_u64_u32 v[22:23], s[0:1], v18, s13, v[0:1]
	ds_read_u16 v18, v22 offset:41216
	v_sub_f32_e32 v51, 1.0, v98
	s_add_i32 s70, s24, s78
	s_cmpk_gt_i32 s70, 0x3ff
	s_waitcnt lgkmcnt(0)
	v_lshlrev_b32_e32 v18, 16, v18
	v_mul_f32_e32 v18, 0xbfb8aa3b, v18
	v_exp_f32_e32 v18, v18
	s_nop 0
	v_add_f32_e32 v18, 1.0, v18
	v_rcp_f32_e32 v18, v18
	s_nop 0
	v_fma_f32 v18, v51, v18, v98
	ds_read_u16 v21, v22 offset:40960
	v_log_f32_e32 v19, v18
	s_nop 1
	v_mul_f32_e32 v20, 0x3f317217, v19
	v_cndmask_b32_e64 v19, v68, v67, s[64:65]
	v_mad_u64_u32 v[24:25], s[0:1], v19, s13, v[0:1]
	ds_read_u16 v19, v24 offset:41216
	s_waitcnt lgkmcnt(0)
	v_lshlrev_b32_e32 v19, 16, v19
	v_mul_f32_e32 v19, 0xbfb8aa3b, v19
	v_exp_f32_e32 v19, v19
	s_nop 0
	v_add_f32_e32 v19, 1.0, v19
	v_rcp_f32_e32 v19, v19
	s_nop 0
	v_fma_f32 v22, v51, v19, v98
	v_log_f32_e32 v19, v22
	s_nop 1
	v_mul_f32_e32 v19, 0x3f317217, v19
	ds_read_u16 v23, v24 offset:40960
	v_cndmask_b32_e64 v24, v70, v69, s[64:65]
	v_mad_u64_u32 v[48:49], s[0:1], v24, s13, v[0:1]
	ds_read_u16 v24, v48 offset:41216
	s_waitcnt lgkmcnt(0)
	v_lshlrev_b32_e32 v24, 16, v24
	v_mul_f32_e32 v24, 0xbfb8aa3b, v24
	v_exp_f32_e32 v24, v24
	s_nop 0
	v_add_f32_e32 v24, 1.0, v24
	v_rcp_f32_e32 v24, v24
	s_nop 0
	v_fma_f32 v24, v51, v24, v98
	v_log_f32_e32 v25, v24
	s_nop 1
	v_mul_f32_e32 v29, 0x3f317217, v25
	ds_read_u16 v25, v48 offset:40960
	v_cndmask_b32_e64 v48, v72, v71, s[64:65]
	v_mad_u64_u32 v[102:103], s[0:1], v48, s13, v[0:1]
	ds_read_u16 v48, v102 offset:41216
	s_waitcnt lgkmcnt(0)
	v_lshlrev_b32_e32 v48, 16, v48
	v_mul_f32_e32 v48, 0xbfb8aa3b, v48
	v_exp_f32_e32 v48, v48
	s_nop 0
	v_add_f32_e32 v48, 1.0, v48
	v_rcp_f32_e32 v48, v48
	s_nop 0
	v_fma_f32 v48, v51, v48, v98
	v_cndmask_b32_e64 v101, v74, v73, s[64:65]
	v_log_f32_e32 v49, v48
	s_nop 1
	v_mul_f32_e32 v50, 0x3f317217, v49
	ds_read_u16 v49, v102 offset:40960
	v_mad_u64_u32 v[102:103], s[0:1], v101, s13, v[0:1]
	ds_read_u16 v101, v102 offset:41216
	ds_read_u16 v102, v102 offset:40960
	s_waitcnt lgkmcnt(1)
	v_lshlrev_b32_e32 v101, 16, v101
	v_mul_f32_e32 v101, 0xbfb8aa3b, v101
	v_exp_f32_e32 v101, v101
	s_nop 0
	v_add_f32_e32 v101, 1.0, v101
	v_rcp_f32_e32 v101, v101
	s_nop 0
	v_fma_f32 v101, v51, v101, v98
	v_log_f32_e32 v103, v101
	s_nop 1
	v_mul_f32_e32 v103, 0x3f317217, v103
	v_cndmask_b32_e64 v104, v76, v75, s[64:65]
	v_mad_u64_u32 v[108:109], s[0:1], v104, s13, v[0:1]
	ds_read_u16 v104, v108 offset:41216
	s_waitcnt lgkmcnt(0)
	v_lshlrev_b32_e32 v104, 16, v104
	v_mul_f32_e32 v104, 0xbfb8aa3b, v104
	v_exp_f32_e32 v104, v104
	s_nop 0
	v_add_f32_e32 v104, 1.0, v104
	v_rcp_f32_e32 v104, v104
	s_nop 0
	v_fma_f32 v104, v51, v104, v98
	v_cndmask_b32_e64 v107, v78, v77, s[64:65]
	v_log_f32_e32 v105, v104
	s_nop 1
	v_mul_f32_e32 v106, 0x3f317217, v105
	ds_read_u16 v105, v108 offset:40960
	v_mad_u64_u32 v[108:109], s[0:1], v107, s13, v[0:1]
	ds_read_u16 v107, v108 offset:41216
	ds_read_u16 v108, v108 offset:40960
	s_waitcnt lgkmcnt(1)
	v_lshlrev_b32_e32 v107, 16, v107
	v_mul_f32_e32 v107, 0xbfb8aa3b, v107
	v_exp_f32_e32 v107, v107
	s_nop 0
	v_add_f32_e32 v107, 1.0, v107
	v_rcp_f32_e32 v107, v107
	s_nop 0
	v_fma_f32 v107, v51, v107, v98
	v_log_f32_e32 v109, v107
	s_nop 1
	v_mul_f32_e32 v109, 0x3f317217, v109
	v_cndmask_b32_e64 v110, v80, v79, s[64:65]
	v_mad_u64_u32 v[114:115], s[0:1], v110, s13, v[0:1]
	ds_read_u16 v110, v114 offset:41216
	s_waitcnt lgkmcnt(0)
	v_lshlrev_b32_e32 v110, 16, v110
	v_mul_f32_e32 v110, 0xbfb8aa3b, v110
	v_exp_f32_e32 v110, v110
	s_nop 0
	v_add_f32_e32 v110, 1.0, v110
	v_rcp_f32_e32 v110, v110
	s_nop 0
	v_fma_f32 v110, v51, v110, v98
	v_cndmask_b32_e64 v113, v82, v81, s[64:65]
	v_log_f32_e32 v111, v110
	s_nop 1
	v_mul_f32_e32 v112, 0x3f317217, v111
	ds_read_u16 v111, v114 offset:40960
	v_mad_u64_u32 v[114:115], s[0:1], v113, s13, v[0:1]
	ds_read_u16 v113, v114 offset:41216
	ds_read_u16 v114, v114 offset:40960
	s_waitcnt lgkmcnt(1)
	v_lshlrev_b32_e32 v113, 16, v113
	v_mul_f32_e32 v113, 0xbfb8aa3b, v113
	v_exp_f32_e32 v113, v113
	s_nop 0
	v_add_f32_e32 v113, 1.0, v113
	v_rcp_f32_e32 v113, v113
	s_nop 0
	v_fma_f32 v113, v51, v113, v98
	v_log_f32_e32 v115, v113
	s_nop 1
	v_mul_f32_e32 v115, 0x3f317217, v115
	v_cndmask_b32_e64 v116, v84, v83, s[64:65]
	v_mad_u64_u32 v[120:121], s[0:1], v116, s13, v[0:1]
	ds_read_u16 v116, v120 offset:41216
	s_waitcnt lgkmcnt(0)
	v_lshlrev_b32_e32 v116, 16, v116
	v_mul_f32_e32 v116, 0xbfb8aa3b, v116
	v_exp_f32_e32 v116, v116
	s_nop 0
	v_add_f32_e32 v116, 1.0, v116
	v_rcp_f32_e32 v116, v116
	s_nop 0
	v_fma_f32 v116, v51, v116, v98
	v_cndmask_b32_e64 v119, v86, v85, s[64:65]
	v_log_f32_e32 v117, v116
	s_nop 1
	v_mul_f32_e32 v118, 0x3f317217, v117
	ds_read_u16 v117, v120 offset:40960
	v_mad_u64_u32 v[120:121], s[0:1], v119, s13, v[0:1]
	ds_read_u16 v119, v120 offset:41216
	ds_read_u16 v120, v120 offset:40960
	s_waitcnt lgkmcnt(1)
	v_lshlrev_b32_e32 v119, 16, v119
	v_mul_f32_e32 v119, 0xbfb8aa3b, v119
	v_exp_f32_e32 v119, v119
	s_nop 0
	v_add_f32_e32 v119, 1.0, v119
	v_rcp_f32_e32 v119, v119
	s_nop 0
	v_fma_f32 v119, v51, v119, v98
	v_log_f32_e32 v121, v119
	s_nop 1
	v_mul_f32_e32 v121, 0x3f317217, v121
	v_cndmask_b32_e64 v122, v88, v87, s[64:65]
	v_mad_u64_u32 v[128:129], s[0:1], v122, s13, v[0:1]
	ds_read_u16 v122, v128 offset:41216
	s_waitcnt lgkmcnt(0)
	v_lshlrev_b32_e32 v122, 16, v122
	v_mul_f32_e32 v122, 0xbfb8aa3b, v122
	v_exp_f32_e32 v122, v122
	s_nop 0
	v_add_f32_e32 v122, 1.0, v122
	v_rcp_f32_e32 v122, v122
	s_nop 0
	v_fma_f32 v122, v51, v122, v98
	v_cndmask_b32_e64 v127, v90, v89, s[64:65]
	v_log_f32_e32 v123, v122
	s_nop 1
	v_mul_f32_e32 v126, 0x3f317217, v123
	ds_read_u16 v123, v128 offset:40960
	v_mad_u64_u32 v[128:129], s[0:1], v127, s13, v[0:1]
	ds_read_u16 v127, v128 offset:41216
	ds_read_u16 v128, v128 offset:40960
	s_waitcnt lgkmcnt(1)
	v_lshlrev_b32_e32 v127, 16, v127
	v_mul_f32_e32 v127, 0xbfb8aa3b, v127
	v_exp_f32_e32 v127, v127
	s_nop 0
	v_add_f32_e32 v127, 1.0, v127
	v_rcp_f32_e32 v127, v127
	s_nop 0
	v_fma_f32 v127, v51, v127, v98
	v_log_f32_e32 v129, v127
	s_nop 1
	v_mul_f32_e32 v129, 0x3f317217, v129
	v_cndmask_b32_e64 v130, v92, v91, s[64:65]
	v_mad_u64_u32 v[134:135], s[0:1], v130, s13, v[0:1]
	ds_read_u16 v130, v134 offset:41216
	s_waitcnt lgkmcnt(0)
	v_lshlrev_b32_e32 v130, 16, v130
	v_mul_f32_e32 v130, 0xbfb8aa3b, v130
	v_exp_f32_e32 v130, v130
	s_nop 0
	v_add_f32_e32 v130, 1.0, v130
	v_rcp_f32_e32 v130, v130
	s_nop 0
	v_fma_f32 v130, v51, v130, v98
	v_cndmask_b32_e64 v133, v94, v93, s[64:65]
	v_log_f32_e32 v131, v130
	s_nop 1
	v_mul_f32_e32 v132, 0x3f317217, v131
	ds_read_u16 v131, v134 offset:40960
	v_mad_u64_u32 v[134:135], s[0:1], v133, s13, v[0:1]
	ds_read_u16 v133, v134 offset:41216
	ds_read_u16 v134, v134 offset:40960
	s_waitcnt lgkmcnt(1)
	v_lshlrev_b32_e32 v133, 16, v133
	v_mul_f32_e32 v133, 0xbfb8aa3b, v133
	v_exp_f32_e32 v133, v133
	s_nop 0
	v_add_f32_e32 v133, 1.0, v133
	v_rcp_f32_e32 v133, v133
	s_nop 0
	v_fma_f32 v133, v51, v133, v98
	v_log_f32_e32 v135, v133
	s_nop 1
	v_mul_f32_e32 v135, 0x3f317217, v135
	v_cndmask_b32_e64 v136, v96, v95, s[64:65]
	v_mad_u64_u32 v[136:137], s[0:1], v136, s13, v[0:1]
	ds_read_u16 v137, v136 offset:41216
	ds_read_u16 v136, v136 offset:40960
	s_waitcnt lgkmcnt(1)
	v_lshlrev_b32_e32 v137, 16, v137
	v_mul_f32_e32 v137, 0xbfb8aa3b, v137
	v_exp_f32_e32 v137, v137
	s_nop 0
	v_add_f32_e32 v137, 1.0, v137
	v_rcp_f32_e32 v137, v137
	s_nop 0
	v_fma_f32 v51, v51, v137, v98
	v_add_f32_e32 v140, v20, v19
	v_add_f32_e32 v141, v140, v29
	v_log_f32_e32 v137, v51
	v_add_f32_e32 v50, v141, v50
	v_add_f32_e32 v142, v50, v103
	v_add_f32_e32 v143, v142, v106
	v_add_f32_e32 v19, v143, v109
	v_add_f32_e32 v139, v19, v112
	v_mul_f32_e32 v137, 0x3f317217, v137
	v_add_f32_e32 v138, v139, v115
	v_add_f32_e32 v118, v138, v118
	v_add_f32_e32 v112, v118, v121
	v_add_f32_e32 v115, v112, v126
	v_add_f32_e32 v106, v115, v129
	v_add_f32_e32 v109, v106, v132
	v_add_f32_e32 v29, v109, v135
	v_add_f32_e32 v103, v29, v137
	ds_write_b32 v97, v103 offset:36864
	s_waitcnt lgkmcnt(0)
	s_barrier
	s_cselect_b64 s[0:1], -1, 0
	s_and_b64 vcc, exec, s[0:1]
	s_cbranch_vccnz .LBB0_659
	s_and_b32 s72, s28, 0x180
	s_and_b32 s74, s10, 0x200
	s_or_b32 s74, s72, s74
	s_add_i32 s73, s72, 0xffffff00
	s_add_i32 s75, s74, 0x380
	s_bitset1_b32 s72, 9
	v_mov_b32_e32 v16, s73
	v_mov_b32_e32 v17, s75
	s_and_b32 s71, s33, 0xffffffc0
	v_cndmask_b32_e64 v2, v16, v17, s[46:47]
	v_mov_b32_e32 v98, s72
	v_cndmask_b32_e64 v12, v16, v17, s[50:51]
	s_add_i32 s71, s71, s4
	v_cndmask_b32_e64 v2, v2, v98, s[38:39]
	v_cndmask_b32_e64 v12, v12, v98, s[42:43]
	v_add_u32_e32 v2, v2, v52
	v_add_u32_e32 v3, s71, v53
	v_mov_b64_e32 v[10:11], s[16:17]
	v_add_u32_e32 v12, v12, v56
	v_add_u32_e32 v13, s71, v57
	v_mad_i64_i32 v[4:5], s[72:73], v3, s12, v[10:11]
	v_ashrrev_i32_e32 v3, 31, v2
	v_mad_i64_i32 v[14:15], s[72:73], v13, s12, v[10:11]
	v_ashrrev_i32_e32 v13, 31, v12
	v_lshl_add_u64 v[2:3], v[2:3], 1, v[4:5]
	v_cndmask_b32_e64 v4, v16, v17, s[48:49]
	v_lshl_add_u64 v[12:13], v[12:13], 1, v[14:15]
	v_cndmask_b32_e64 v14, v16, v17, s[52:53]
	v_cndmask_b32_e64 v4, v4, v98, s[40:41]
	v_cndmask_b32_e64 v14, v14, v98, s[44:45]
	v_add_u32_e32 v4, v4, v54
	v_add_u32_e32 v5, s71, v55
	v_add_u32_e32 v14, v14, v58
	v_add_u32_e32 v15, s71, v59
	v_mad_i64_i32 v[6:7], s[72:73], v5, s12, v[10:11]
	v_ashrrev_i32_e32 v5, 31, v4
	v_mad_i64_i32 v[10:11], s[72:73], v15, s12, v[10:11]
	v_ashrrev_i32_e32 v15, 31, v14
	v_or_b32_e32 v98, s74, v60
	v_readlane_b32 s6, v253, 21
	v_lshl_add_u64 v[6:7], v[4:5], 1, v[6:7]
	v_lshl_add_u64 v[14:15], v[14:15], 1, v[10:11]
	v_lshlrev_b32_e32 v98, 2, v98
	v_readlane_b32 s7, v253, 22
	global_load_dwordx4 v[2:5], v[2:3], off
	s_nop 0
	global_load_dwordx4 v[6:9], v[6:7], off
	s_nop 0
	global_load_dwordx4 v[10:13], v[12:13], off
	s_nop 0
	global_load_dwordx4 v[14:17], v[14:15], off
	v_readlane_b32 s74, v255, 2
	global_load_dword v98, v98, s[6:7]
	v_readlane_b32 s75, v255, 3

.Lrb1_loop:
	ds_read2_b32 v[24:25], v10 offset1:4
	ds_read2_b32 v[26:27], v10 offset0:8 offset1:12
	ds_read2_b32 v[28:29], v10 offset0:16 offset1:20
	ds_read2_b32 v[30:31], v10 offset0:24 offset1:28
	ds_read2_b32 v[32:33], v10 offset0:32 offset1:36
	ds_read2_b32 v[34:35], v10 offset0:40 offset1:44
	ds_read2_b32 v[36:37], v10 offset0:48 offset1:52
	ds_read2_b32 v[38:39], v10 offset0:56 offset1:60
	s_waitcnt vmcnt(19)
	s_waitcnt lgkmcnt(7)
	v_mfma_f32_16x16x4_f32 v[16:19], v40, v24, v[56:59]
	v_mfma_f32_16x16x4_f32 v[20:23], v41, v25, 0
	global_load_dwordx4 v[96:99], v5, s[38:39]
	global_load_dword v80, v6, s[38:39]
	global_load_dword v81, v6, s[38:39] offset:1024
	s_waitcnt lgkmcnt(6)
	v_mfma_f32_16x16x4_f32 v[16:19], v42, v26, v[16:19]
	v_mfma_f32_16x16x4_f32 v[20:23], v43, v27, v[20:23]
	global_load_dword v82, v6, s[38:39] offset:2048
	global_load_dword v83, v6, s[38:39] offset:3072
	s_waitcnt lgkmcnt(5)
	v_mfma_f32_16x16x4_f32 v[16:19], v44, v28, v[16:19]
	v_mfma_f32_16x16x4_f32 v[20:23], v45, v29, v[20:23]
	global_load_dword v84, v7, s[38:39]
	global_load_dword v85, v7, s[38:39] offset:1024
	s_waitcnt lgkmcnt(4)
	v_mfma_f32_16x16x4_f32 v[16:19], v46, v30, v[16:19]
	v_mfma_f32_16x16x4_f32 v[20:23], v47, v31, v[20:23]
	global_load_dword v86, v7, s[38:39] offset:2048
	global_load_dword v87, v7, s[38:39] offset:3072
	s_waitcnt lgkmcnt(3)
	v_mfma_f32_16x16x4_f32 v[16:19], v48, v32, v[16:19]
	v_mfma_f32_16x16x4_f32 v[20:23], v49, v33, v[20:23]
	global_load_dword v88, v8, s[38:39]
	global_load_dword v89, v8, s[38:39] offset:1024
	s_waitcnt lgkmcnt(2)
	v_mfma_f32_16x16x4_f32 v[16:19], v50, v34, v[16:19]
	v_mfma_f32_16x16x4_f32 v[20:23], v51, v35, v[20:23]
	global_load_dword v90, v8, s[38:39] offset:2048
	global_load_dword v91, v8, s[38:39] offset:3072
	s_waitcnt lgkmcnt(1)
	v_mfma_f32_16x16x4_f32 v[16:19], v52, v36, v[16:19]
	v_mfma_f32_16x16x4_f32 v[20:23], v53, v37, v[20:23]
	global_load_dword v92, v9, s[38:39]
	global_load_dword v93, v9, s[38:39] offset:1024
	s_waitcnt lgkmcnt(0)
	v_mfma_f32_16x16x4_f32 v[16:19], v54, v38, v[16:19]
	v_mfma_f32_16x16x4_f32 v[20:23], v55, v39, v[20:23]
	global_load_dword v94, v9, s[38:39] offset:2048
	global_load_dword v95, v9, s[38:39] offset:3072
	s_add_u32 s38, s38, 0x8000
	s_addc_u32 s39, s39, 0
	v_xor_b32_e32 v10, 0x2000, v10
	s_nop 7
	s_nop 2
	v_add_f32_e32 v12, v16, v20
	v_add_f32_e32 v13, v17, v21
	v_add_f32_e32 v14, v18, v22
	v_add_f32_e32 v15, v19, v23
	s_waitcnt vmcnt(34)
	global_store_dwordx4 v5, v[12:15], s[40:41]
	s_add_u32 s40, s40, 0x8000
	s_addc_u32 s41, s41, 0
	ds_write_b128 v11, v[12:15]
	v_xor_b32_e32 v11, 0x2000, v11
	s_waitcnt lgkmcnt(0)
	s_barrier
	ds_read2_b32 v[24:25], v10 offset1:4
	ds_read2_b32 v[26:27], v10 offset0:8 offset1:12
	ds_read2_b32 v[28:29], v10 offset0:16 offset1:20
	ds_read2_b32 v[30:31], v10 offset0:24 offset1:28
	ds_read2_b32 v[32:33], v10 offset0:32 offset1:36
	ds_read2_b32 v[34:35], v10 offset0:40 offset1:44
	ds_read2_b32 v[36:37], v10 offset0:48 offset1:52
	ds_read2_b32 v[38:39], v10 offset0:56 offset1:60
	s_waitcnt vmcnt(19)
	s_waitcnt lgkmcnt(7)
	v_mfma_f32_16x16x4_f32 v[16:19], v60, v24, v[76:79]
	v_mfma_f32_16x16x4_f32 v[20:23], v61, v25, 0
	global_load_dwordx4 v[56:59], v5, s[38:39]
	global_load_dword v40, v6, s[38:39]
	global_load_dword v41, v6, s[38:39] offset:1024
	s_waitcnt lgkmcnt(6)
	v_mfma_f32_16x16x4_f32 v[16:19], v62, v26, v[16:19]
	v_mfma_f32_16x16x4_f32 v[20:23], v63, v27, v[20:23]
	global_load_dword v42, v6, s[38:39] offset:2048
	global_load_dword v43, v6, s[38:39] offset:3072
	s_waitcnt lgkmcnt(5)
	v_mfma_f32_16x16x4_f32 v[16:19], v64, v28, v[16:19]
	v_mfma_f32_16x16x4_f32 v[20:23], v65, v29, v[20:23]
	global_load_dword v44, v7, s[38:39]
	global_load_dword v45, v7, s[38:39] offset:1024
	s_waitcnt lgkmcnt(4)
	v_mfma_f32_16x16x4_f32 v[16:19], v66, v30, v[16:19]
	v_mfma_f32_16x16x4_f32 v[20:23], v67, v31, v[20:23]
	global_load_dword v46, v7, s[38:39] offset:2048
	global_load_dword v47, v7, s[38:39] offset:3072
	s_waitcnt lgkmcnt(3)
	v_mfma_f32_16x16x4_f32 v[16:19], v68, v32, v[16:19]
	v_mfma_f32_16x16x4_f32 v[20:23], v69, v33, v[20:23]
	global_load_dword v48, v8, s[38:39]
	global_load_dword v49, v8, s[38:39] offset:1024
	s_waitcnt lgkmcnt(2)
	v_mfma_f32_16x16x4_f32 v[16:19], v70, v34, v[16:19]
	v_mfma_f32_16x16x4_f32 v[20:23], v71, v35, v[20:23]
	global_load_dword v50, v8, s[38:39] offset:2048
	global_load_dword v51, v8, s[38:39] offset:3072
	s_waitcnt lgkmcnt(1)
	v_mfma_f32_16x16x4_f32 v[16:19], v72, v36, v[16:19]
	v_mfma_f32_16x16x4_f32 v[20:23], v73, v37, v[20:23]
	global_load_dword v52, v9, s[38:39]
	global_load_dword v53, v9, s[38:39] offset:1024
	s_waitcnt lgkmcnt(0)
	v_mfma_f32_16x16x4_f32 v[16:19], v74, v38, v[16:19]
	v_mfma_f32_16x16x4_f32 v[20:23], v75, v39, v[20:23]
	global_load_dword v54, v9, s[38:39] offset:2048
	global_load_dword v55, v9, s[38:39] offset:3072
	s_add_u32 s38, s38, 0x8000
	s_addc_u32 s39, s39, 0
	v_xor_b32_e32 v10, 0x2000, v10
	s_nop 7
	s_nop 2
	v_add_f32_e32 v12, v16, v20
	v_add_f32_e32 v13, v17, v21
	v_add_f32_e32 v14, v18, v22
	v_add_f32_e32 v15, v19, v23
	s_waitcnt vmcnt(34)
	global_store_dwordx4 v5, v[12:15], s[40:41]
	s_add_u32 s40, s40, 0x8000
	s_addc_u32 s41, s41, 0
	ds_write_b128 v11, v[12:15]
	v_xor_b32_e32 v11, 0x2000, v11
	s_waitcnt lgkmcnt(0)
	s_barrier
	ds_read2_b32 v[24:25], v10 offset1:4
	ds_read2_b32 v[26:27], v10 offset0:8 offset1:12
	ds_read2_b32 v[28:29], v10 offset0:16 offset1:20
	ds_read2_b32 v[30:31], v10 offset0:24 offset1:28
	ds_read2_b32 v[32:33], v10 offset0:32 offset1:36
	ds_read2_b32 v[34:35], v10 offset0:40 offset1:44
	ds_read2_b32 v[36:37], v10 offset0:48 offset1:52
	ds_read2_b32 v[38:39], v10 offset0:56 offset1:60
	s_waitcnt vmcnt(19)
	s_waitcnt lgkmcnt(7)
	v_mfma_f32_16x16x4_f32 v[16:19], v80, v24, v[96:99]
	v_mfma_f32_16x16x4_f32 v[20:23], v81, v25, 0
	global_load_dwordx4 v[76:79], v5, s[38:39]
	global_load_dword v60, v6, s[38:39]
	global_load_dword v61, v6, s[38:39] offset:1024
	s_waitcnt lgkmcnt(6)
	v_mfma_f32_16x16x4_f32 v[16:19], v82, v26, v[16:19]
	v_mfma_f32_16x16x4_f32 v[20:23], v83, v27, v[20:23]
	global_load_dword v62, v6, s[38:39] offset:2048
	global_load_dword v63, v6, s[38:39] offset:3072
	s_waitcnt lgkmcnt(5)
	v_mfma_f32_16x16x4_f32 v[16:19], v84, v28, v[16:19]
	v_mfma_f32_16x16x4_f32 v[20:23], v85, v29, v[20:23]
	global_load_dword v64, v7, s[38:39]
	global_load_dword v65, v7, s[38:39] offset:1024
	s_waitcnt lgkmcnt(4)
	v_mfma_f32_16x16x4_f32 v[16:19], v86, v30, v[16:19]
	v_mfma_f32_16x16x4_f32 v[20:23], v87, v31, v[20:23]
	global_load_dword v66, v7, s[38:39] offset:2048
	global_load_dword v67, v7, s[38:39] offset:3072
	s_waitcnt lgkmcnt(3)
	v_mfma_f32_16x16x4_f32 v[16:19], v88, v32, v[16:19]
	v_mfma_f32_16x16x4_f32 v[20:23], v89, v33, v[20:23]
	global_load_dword v68, v8, s[38:39]
	global_load_dword v69, v8, s[38:39] offset:1024
	s_waitcnt lgkmcnt(2)
	v_mfma_f32_16x16x4_f32 v[16:19], v90, v34, v[16:19]
	v_mfma_f32_16x16x4_f32 v[20:23], v91, v35, v[20:23]
	global_load_dword v70, v8, s[38:39] offset:2048
	global_load_dword v71, v8, s[38:39] offset:3072
	s_waitcnt lgkmcnt(1)
	v_mfma_f32_16x16x4_f32 v[16:19], v92, v36, v[16:19]
	v_mfma_f32_16x16x4_f32 v[20:23], v93, v37, v[20:23]
	global_load_dword v72, v9, s[38:39]
	global_load_dword v73, v9, s[38:39] offset:1024
	s_waitcnt lgkmcnt(0)
	v_mfma_f32_16x16x4_f32 v[16:19], v94, v38, v[16:19]
	v_mfma_f32_16x16x4_f32 v[20:23], v95, v39, v[20:23]
	global_load_dword v74, v9, s[38:39] offset:2048
	global_load_dword v75, v9, s[38:39] offset:3072
	s_add_u32 s38, s38, 0x8000
	s_addc_u32 s39, s39, 0
	v_xor_b32_e32 v10, 0x2000, v10
	s_nop 7
	s_nop 2
	v_add_f32_e32 v12, v16, v20
	v_add_f32_e32 v13, v17, v21
	v_add_f32_e32 v14, v18, v22
	v_add_f32_e32 v15, v19, v23
	s_waitcnt vmcnt(34)
	global_store_dwordx4 v5, v[12:15], s[40:41]
	s_add_u32 s40, s40, 0x8000
	s_addc_u32 s41, s41, 0
	ds_write_b128 v11, v[12:15]
	v_xor_b32_e32 v11, 0x2000, v11
	s_waitcnt lgkmcnt(0)
	s_barrier
	s_sub_u32 s10, s10, 1
	s_cmp_lg_u32 s10, 0
	s_cbranch_scc1 .Lrb1_loop
	ds_read2_b32 v[24:25], v10 offset1:4
	ds_read2_b32 v[26:27], v10 offset0:8 offset1:12
	ds_read2_b32 v[28:29], v10 offset0:16 offset1:20
	ds_read2_b32 v[30:31], v10 offset0:24 offset1:28
	ds_read2_b32 v[32:33], v10 offset0:32 offset1:36
	ds_read2_b32 v[34:35], v10 offset0:40 offset1:44
	ds_read2_b32 v[36:37], v10 offset0:48 offset1:52
	ds_read2_b32 v[38:39], v10 offset0:56 offset1:60
	s_waitcnt vmcnt(19)
	s_waitcnt lgkmcnt(7)
	v_mfma_f32_16x16x4_f32 v[16:19], v40, v24, v[56:59]
	v_mfma_f32_16x16x4_f32 v[20:23], v41, v25, 0
	global_load_dwordx4 v[96:99], v5, s[38:39]
	global_load_dword v80, v6, s[38:39]
	global_load_dword v81, v6, s[38:39] offset:1024
	s_waitcnt lgkmcnt(6)
	v_mfma_f32_16x16x4_f32 v[16:19], v42, v26, v[16:19]
	v_mfma_f32_16x16x4_f32 v[20:23], v43, v27, v[20:23]
	global_load_dword v82, v6, s[38:39] offset:2048
	global_load_dword v83, v6, s[38:39] offset:3072
	s_waitcnt lgkmcnt(5)
	v_mfma_f32_16x16x4_f32 v[16:19], v44, v28, v[16:19]
	v_mfma_f32_16x16x4_f32 v[20:23], v45, v29, v[20:23]
	global_load_dword v84, v7, s[38:39]
	global_load_dword v85, v7, s[38:39] offset:1024
	s_waitcnt lgkmcnt(4)
	v_mfma_f32_16x16x4_f32 v[16:19], v46, v30, v[16:19]
	v_mfma_f32_16x16x4_f32 v[20:23], v47, v31, v[20:23]
	global_load_dword v86, v7, s[38:39] offset:2048
	global_load_dword v87, v7, s[38:39] offset:3072
	s_waitcnt lgkmcnt(3)
	v_mfma_f32_16x16x4_f32 v[16:19], v48, v32, v[16:19]
	v_mfma_f32_16x16x4_f32 v[20:23], v49, v33, v[20:23]
	global_load_dword v88, v8, s[38:39]
	global_load_dword v89, v8, s[38:39] offset:1024
	s_waitcnt lgkmcnt(2)
	v_mfma_f32_16x16x4_f32 v[16:19], v50, v34, v[16:19]
	v_mfma_f32_16x16x4_f32 v[20:23], v51, v35, v[20:23]
	global_load_dword v90, v8, s[38:39] offset:2048
	global_load_dword v91, v8, s[38:39] offset:3072
	s_waitcnt lgkmcnt(1)
	v_mfma_f32_16x16x4_f32 v[16:19], v52, v36, v[16:19]
	v_mfma_f32_16x16x4_f32 v[20:23], v53, v37, v[20:23]
	global_load_dword v92, v9, s[38:39]
	global_load_dword v93, v9, s[38:39] offset:1024
	s_waitcnt lgkmcnt(0)
	v_mfma_f32_16x16x4_f32 v[16:19], v54, v38, v[16:19]
	v_mfma_f32_16x16x4_f32 v[20:23], v55, v39, v[20:23]
	global_load_dword v94, v9, s[38:39] offset:2048
	global_load_dword v95, v9, s[38:39] offset:3072
	s_add_u32 s38, s38, 0x8000
	s_addc_u32 s39, s39, 0
	v_xor_b32_e32 v10, 0x2000, v10
	s_nop 7
	s_nop 2
	v_add_f32_e32 v12, v16, v20
	v_add_f32_e32 v13, v17, v21
	v_add_f32_e32 v14, v18, v22
	v_add_f32_e32 v15, v19, v23
	s_waitcnt vmcnt(34)
	global_store_dwordx4 v5, v[12:15], s[40:41]
	s_add_u32 s40, s40, 0x8000
	s_addc_u32 s41, s41, 0
	ds_write_b128 v11, v[12:15]
	v_xor_b32_e32 v11, 0x2000, v11
	s_waitcnt lgkmcnt(0)
	s_barrier
	ds_read2_b32 v[24:25], v10 offset1:4
	ds_read2_b32 v[26:27], v10 offset0:8 offset1:12
	ds_read2_b32 v[28:29], v10 offset0:16 offset1:20
	ds_read2_b32 v[30:31], v10 offset0:24 offset1:28
	ds_read2_b32 v[32:33], v10 offset0:32 offset1:36
	ds_read2_b32 v[34:35], v10 offset0:40 offset1:44
	ds_read2_b32 v[36:37], v10 offset0:48 offset1:52
	ds_read2_b32 v[38:39], v10 offset0:56 offset1:60
	s_waitcnt vmcnt(19)
	s_waitcnt lgkmcnt(7)
	v_mfma_f32_16x16x4_f32 v[16:19], v60, v24, v[76:79]
	v_mfma_f32_16x16x4_f32 v[20:23], v61, v25, 0
	s_waitcnt lgkmcnt(6)
	v_mfma_f32_16x16x4_f32 v[16:19], v62, v26, v[16:19]
	v_mfma_f32_16x16x4_f32 v[20:23], v63, v27, v[20:23]
	s_waitcnt lgkmcnt(5)
	v_mfma_f32_16x16x4_f32 v[16:19], v64, v28, v[16:19]
	v_mfma_f32_16x16x4_f32 v[20:23], v65, v29, v[20:23]
	s_waitcnt lgkmcnt(4)
	v_mfma_f32_16x16x4_f32 v[16:19], v66, v30, v[16:19]
	v_mfma_f32_16x16x4_f32 v[20:23], v67, v31, v[20:23]
	s_waitcnt lgkmcnt(3)
	v_mfma_f32_16x16x4_f32 v[16:19], v68, v32, v[16:19]
	v_mfma_f32_16x16x4_f32 v[20:23], v69, v33, v[20:23]
	s_waitcnt lgkmcnt(2)
	v_mfma_f32_16x16x4_f32 v[16:19], v70, v34, v[16:19]
	v_mfma_f32_16x16x4_f32 v[20:23], v71, v35, v[20:23]
	s_waitcnt lgkmcnt(1)
	v_mfma_f32_16x16x4_f32 v[16:19], v72, v36, v[16:19]
	v_mfma_f32_16x16x4_f32 v[20:23], v73, v37, v[20:23]
	s_waitcnt lgkmcnt(0)
	v_mfma_f32_16x16x4_f32 v[16:19], v74, v38, v[16:19]
	v_mfma_f32_16x16x4_f32 v[20:23], v75, v39, v[20:23]
	v_xor_b32_e32 v10, 0x2000, v10
	s_nop 7
	s_nop 2
	v_add_f32_e32 v12, v16, v20
	v_add_f32_e32 v13, v17, v21
	v_add_f32_e32 v14, v18, v22
	v_add_f32_e32 v15, v19, v23
	s_waitcnt vmcnt(17)
	global_store_dwordx4 v5, v[12:15], s[40:41]
	s_add_u32 s40, s40, 0x8000
	s_addc_u32 s41, s41, 0
	ds_write_b128 v11, v[12:15]
	v_xor_b32_e32 v11, 0x2000, v11
	s_waitcnt lgkmcnt(0)
	s_barrier
	ds_read2_b32 v[24:25], v10 offset1:4
	ds_read2_b32 v[26:27], v10 offset0:8 offset1:12
	ds_read2_b32 v[28:29], v10 offset0:16 offset1:20
	ds_read2_b32 v[30:31], v10 offset0:24 offset1:28
	ds_read2_b32 v[32:33], v10 offset0:32 offset1:36
	ds_read2_b32 v[34:35], v10 offset0:40 offset1:44
	ds_read2_b32 v[36:37], v10 offset0:48 offset1:52
	ds_read2_b32 v[38:39], v10 offset0:56 offset1:60
	s_waitcnt vmcnt(0)
	s_waitcnt lgkmcnt(7)
	v_mfma_f32_16x16x4_f32 v[16:19], v80, v24, v[96:99]
	v_mfma_f32_16x16x4_f32 v[20:23], v81, v25, 0
	s_waitcnt lgkmcnt(6)
	v_mfma_f32_16x16x4_f32 v[16:19], v82, v26, v[16:19]
	v_mfma_f32_16x16x4_f32 v[20:23], v83, v27, v[20:23]
	s_waitcnt lgkmcnt(5)
	v_mfma_f32_16x16x4_f32 v[16:19], v84, v28, v[16:19]
	v_mfma_f32_16x16x4_f32 v[20:23], v85, v29, v[20:23]
	s_waitcnt lgkmcnt(4)
	v_mfma_f32_16x16x4_f32 v[16:19], v86, v30, v[16:19]
	v_mfma_f32_16x16x4_f32 v[20:23], v87, v31, v[20:23]
	s_waitcnt lgkmcnt(3)
	v_mfma_f32_16x16x4_f32 v[16:19], v88, v32, v[16:19]
	v_mfma_f32_16x16x4_f32 v[20:23], v89, v33, v[20:23]
	s_waitcnt lgkmcnt(2)
	v_mfma_f32_16x16x4_f32 v[16:19], v90, v34, v[16:19]
	v_mfma_f32_16x16x4_f32 v[20:23], v91, v35, v[20:23]
	s_waitcnt lgkmcnt(1)
	v_mfma_f32_16x16x4_f32 v[16:19], v92, v36, v[16:19]
	v_mfma_f32_16x16x4_f32 v[20:23], v93, v37, v[20:23]
	s_waitcnt lgkmcnt(0)
	v_mfma_f32_16x16x4_f32 v[16:19], v94, v38, v[16:19]
	v_mfma_f32_16x16x4_f32 v[20:23], v95, v39, v[20:23]
	v_xor_b32_e32 v10, 0x2000, v10
	s_nop 7
	s_nop 2
	v_add_f32_e32 v12, v16, v20
	v_add_f32_e32 v13, v17, v21
	v_add_f32_e32 v14, v18, v22
	v_add_f32_e32 v15, v19, v23
	s_waitcnt vmcnt(0)
	global_store_dwordx4 v5, v[12:15], s[40:41]
	s_add_u32 s40, s40, 0x8000
	s_addc_u32 s41, s41, 0
	ds_write_b128 v11, v[12:15]
	v_xor_b32_e32 v11, 0x2000, v11
	s_waitcnt lgkmcnt(0)
	s_barrier
	s_branch .Lrb1_done

.Lrb1_done:
.LBB0_737:
	s_cmp_lg_u32 s68, 0
	s_cbranch_scc1 .Lhb1_start
	v_readlane_b32 s6, v255, 18
	v_readlane_b32 s7, v255, 19
	s_mov_b32 s4, 0x100000
	s_andn2_b64 vcc, exec, s[6:7]
	v_cndmask_b32_e64 v0, 0, 1, s[6:7]
	v_cmp_ne_u32_e64 s[0:1], 1, v0
	v_readlane_b32 s5, v252, 34
	s_cbranch_vccnz .LBB0_739
	s_mov_b32 s4, 0x10000
	v_readlane_b32 s5, v254, 47

.LBB0_755:
	s_or_b64 exec, exec, s[40:41]
	s_branch .Lhb1_done
.Lhb1_start:
	s_cmp_lt_u32 s72, 128
	s_cbranch_scc1 .Lhb1_done
	s_waitcnt vmcnt(0) lgkmcnt(0)
	s_sub_u32 s0, s72, 128
	s_lshr_b32 s1, s0, 3
	s_and_b32 s4, s0, 7
	s_lshl_b32 s4, s4, 9
	v_add_u32_e32 v0, s4, v177
	v_lshlrev_b32_e32 v2, 4, v0
	v_lshrrev_b32_e32 v3, 5, v0
	v_lshlrev_b32_e32 v3, 2, v3
	v_readlane_b32 s38, v253, 1
	v_readlane_b32 s39, v253, 2
	v_readlane_b32 s44, v252, 6
	v_readlane_b32 s45, v252, 7
	s_lshl_b32 s5, s1, 22
	s_nop 3
	s_add_u32 s38, s38, s5
	s_addc_u32 s39, s39, 0
	s_mov_b64 s[40:41], s[38:39]
	s_lshl_b32 s5, s1, 15
	s_add_u32 s42, s2, s5
	s_addc_u32 s43, s3, 0
	s_lshr_b32 s5, s1, 3
	s_lshl_b32 s5, s5, 1
	s_and_b32 s6, s1, 1
	s_or_b32 s5, s5, s6
	s_lshl_b32 s5, s5, 2
	s_bfe_u32 s6, s1, 0x20001
	s_or_b32 s5, s5, s6
	s_lshl_b32 s5, s5, 16
	s_add_u32 s44, s44, s5
	s_addc_u32 s45, s45, 0
	global_load_dwordx4 v[4:7], v2, s[44:45]
	global_load_dwordx4 v[8:11], v2, s[38:39]
	global_load_dword v40, v3, s[42:43]
	s_add_u32 s38, s38, 0x10000
	s_addc_u32 s39, s39, 0
	s_add_u32 s42, s42, 0x200
	s_addc_u32 s43, s43, 0
	global_load_dwordx4 v[12:15], v2, s[38:39]
	global_load_dword v41, v3, s[42:43]
	s_add_u32 s38, s38, 0x10000
	s_addc_u32 s39, s39, 0
	s_add_u32 s42, s42, 0x200
	s_addc_u32 s43, s43, 0
	global_load_dwordx4 v[16:19], v2, s[38:39]
	global_load_dword v42, v3, s[42:43]
	s_add_u32 s38, s38, 0x10000
	s_addc_u32 s39, s39, 0
	s_add_u32 s42, s42, 0x200
	s_addc_u32 s43, s43, 0
	global_load_dwordx4 v[20:23], v2, s[38:39]
	global_load_dword v43, v3, s[42:43]
	s_add_u32 s38, s38, 0x10000
	s_addc_u32 s39, s39, 0
	s_add_u32 s42, s42, 0x200
	s_addc_u32 s43, s43, 0
	global_load_dwordx4 v[24:27], v2, s[38:39]
	global_load_dword v44, v3, s[42:43]
	s_add_u32 s38, s38, 0x10000
	s_addc_u32 s39, s39, 0
	s_add_u32 s42, s42, 0x200
	s_addc_u32 s43, s43, 0
	global_load_dwordx4 v[28:31], v2, s[38:39]
	global_load_dword v45, v3, s[42:43]
	s_add_u32 s38, s38, 0x10000
	s_addc_u32 s39, s39, 0
	s_add_u32 s42, s42, 0x200
	s_addc_u32 s43, s43, 0
	global_load_dwordx4 v[32:35], v2, s[38:39]
	global_load_dword v46, v3, s[42:43]
	s_add_u32 s38, s38, 0x10000
	s_addc_u32 s39, s39, 0
	s_add_u32 s42, s42, 0x200
	s_addc_u32 s43, s43, 0
	global_load_dwordx4 v[36:39], v2, s[38:39]
	global_load_dword v47, v3, s[42:43]
	s_add_u32 s38, s38, 0x10000
	s_addc_u32 s39, s39, 0
	s_add_u32 s42, s42, 0x200
	s_addc_u32 s43, s43, 0
	s_waitcnt vmcnt(14)
	global_store_dwordx4 v2, v[4:7], s[40:41]
	s_add_u32 s40, s40, 0x10000
	s_addc_u32 s41, s41, 0
	v_fma_f32 v4, v4, v40, v8
	v_fma_f32 v5, v5, v40, v9
	v_fma_f32 v6, v6, v40, v10
	v_fma_f32 v7, v7, v40, v11
	global_load_dwordx4 v[8:11], v2, s[38:39]
	global_load_dword v40, v3, s[42:43]
	s_add_u32 s38, s38, 0x10000
	s_addc_u32 s39, s39, 0
	s_add_u32 s42, s42, 0x200
	s_addc_u32 s43, s43, 0
	s_waitcnt vmcnt(15)
	global_store_dwordx4 v2, v[4:7], s[40:41]
	s_add_u32 s40, s40, 0x10000
	s_addc_u32 s41, s41, 0
	v_fma_f32 v4, v4, v41, v12
	v_fma_f32 v5, v5, v41, v13
	v_fma_f32 v6, v6, v41, v14
	v_fma_f32 v7, v7, v41, v15
	global_load_dwordx4 v[12:15], v2, s[38:39]
	global_load_dword v41, v3, s[42:43]
	s_add_u32 s38, s38, 0x10000
	s_addc_u32 s39, s39, 0
	s_add_u32 s42, s42, 0x200
	s_addc_u32 s43, s43, 0
	s_waitcnt vmcnt(16)
	global_store_dwordx4 v2, v[4:7], s[40:41]
	s_add_u32 s40, s40, 0x10000
	s_addc_u32 s41, s41, 0
	v_fma_f32 v4, v4, v42, v16
	v_fma_f32 v5, v5, v42, v17
	v_fma_f32 v6, v6, v42, v18
	v_fma_f32 v7, v7, v42, v19
	global_load_dwordx4 v[16:19], v2, s[38:39]
	global_load_dword v42, v3, s[42:43]
	s_add_u32 s38, s38, 0x10000
	s_addc_u32 s39, s39, 0
	s_add_u32 s42, s42, 0x200
	s_addc_u32 s43, s43, 0
	s_waitcnt vmcnt(17)
	global_store_dwordx4 v2, v[4:7], s[40:41]
	s_add_u32 s40, s40, 0x10000
	s_addc_u32 s41, s41, 0
	v_fma_f32 v4, v4, v43, v20
	v_fma_f32 v5, v5, v43, v21
	v_fma_f32 v6, v6, v43, v22
	v_fma_f32 v7, v7, v43, v23
	global_load_dwordx4 v[20:23], v2, s[38:39]
	global_load_dword v43, v3, s[42:43]
	s_add_u32 s38, s38, 0x10000
	s_addc_u32 s39, s39, 0
	s_add_u32 s42, s42, 0x200
	s_addc_u32 s43, s43, 0
	s_waitcnt vmcnt(18)
	global_store_dwordx4 v2, v[4:7], s[40:41]
	s_add_u32 s40, s40, 0x10000
	s_addc_u32 s41, s41, 0
	v_fma_f32 v4, v4, v44, v24
	v_fma_f32 v5, v5, v44, v25
	v_fma_f32 v6, v6, v44, v26
	v_fma_f32 v7, v7, v44, v27
	global_load_dwordx4 v[24:27], v2, s[38:39]
	global_load_dword v44, v3, s[42:43]
	s_add_u32 s38, s38, 0x10000
	s_addc_u32 s39, s39, 0
	s_add_u32 s42, s42, 0x200
	s_addc_u32 s43, s43, 0
	s_waitcnt vmcnt(19)
	global_store_dwordx4 v2, v[4:7], s[40:41]
	s_add_u32 s40, s40, 0x10000
	s_addc_u32 s41, s41, 0
	v_fma_f32 v4, v4, v45, v28
	v_fma_f32 v5, v5, v45, v29
	v_fma_f32 v6, v6, v45, v30
	v_fma_f32 v7, v7, v45, v31
	global_load_dwordx4 v[28:31], v2, s[38:39]
	global_load_dword v45, v3, s[42:43]
	s_add_u32 s38, s38, 0x10000
	s_addc_u32 s39, s39, 0
	s_add_u32 s42, s42, 0x200
	s_addc_u32 s43, s43, 0
	s_waitcnt vmcnt(20)
	global_store_dwordx4 v2, v[4:7], s[40:41]
	s_add_u32 s40, s40, 0x10000
	s_addc_u32 s41, s41, 0
	v_fma_f32 v4, v4, v46, v32
	v_fma_f32 v5, v5, v46, v33
	v_fma_f32 v6, v6, v46, v34
	v_fma_f32 v7, v7, v46, v35
	global_load_dwordx4 v[32:35], v2, s[38:39]
	global_load_dword v46, v3, s[42:43]
	s_add_u32 s38, s38, 0x10000
	s_addc_u32 s39, s39, 0
	s_add_u32 s42, s42, 0x200
	s_addc_u32 s43, s43, 0
	s_waitcnt vmcnt(21)
	global_store_dwordx4 v2, v[4:7], s[40:41]
	s_add_u32 s40, s40, 0x10000
	s_addc_u32 s41, s41, 0
	v_fma_f32 v4, v4, v47, v36
	v_fma_f32 v5, v5, v47, v37
	v_fma_f32 v6, v6, v47, v38
	v_fma_f32 v7, v7, v47, v39
	global_load_dwordx4 v[36:39], v2, s[38:39]
	global_load_dword v47, v3, s[42:43]
	s_add_u32 s38, s38, 0x10000
	s_addc_u32 s39, s39, 0
	s_add_u32 s42, s42, 0x200
	s_addc_u32 s43, s43, 0
	s_waitcnt vmcnt(21)
	global_store_dwordx4 v2, v[4:7], s[40:41]
	s_add_u32 s40, s40, 0x10000
	s_addc_u32 s41, s41, 0
	v_fma_f32 v4, v4, v40, v8
	v_fma_f32 v5, v5, v40, v9
	v_fma_f32 v6, v6, v40, v10
	v_fma_f32 v7, v7, v40, v11
	global_load_dwordx4 v[8:11], v2, s[38:39]
	global_load_dword v40, v3, s[42:43]
	s_add_u32 s38, s38, 0x10000
	s_addc_u32 s39, s39, 0
	s_add_u32 s42, s42, 0x200
	s_addc_u32 s43, s43, 0
	s_waitcnt vmcnt(21)
	global_store_dwordx4 v2, v[4:7], s[40:41]
	s_add_u32 s40, s40, 0x10000
	s_addc_u32 s41, s41, 0
	v_fma_f32 v4, v4, v41, v12
	v_fma_f32 v5, v5, v41, v13
	v_fma_f32 v6, v6, v41, v14
	v_fma_f32 v7, v7, v41, v15
	global_load_dwordx4 v[12:15], v2, s[38:39]
	global_load_dword v41, v3, s[42:43]
	s_add_u32 s38, s38, 0x10000
	s_addc_u32 s39, s39, 0
	s_add_u32 s42, s42, 0x200
	s_addc_u32 s43, s43, 0
	s_waitcnt vmcnt(21)
	global_store_dwordx4 v2, v[4:7], s[40:41]
	s_add_u32 s40, s40, 0x10000
	s_addc_u32 s41, s41, 0
	v_fma_f32 v4, v4, v42, v16
	v_fma_f32 v5, v5, v42, v17
	v_fma_f32 v6, v6, v42, v18
	v_fma_f32 v7, v7, v42, v19
	global_load_dwordx4 v[16:19], v2, s[38:39]
	global_load_dword v42, v3, s[42:43]
	s_add_u32 s38, s38, 0x10000
	s_addc_u32 s39, s39, 0
	s_add_u32 s42, s42, 0x200
	s_addc_u32 s43, s43, 0
	s_waitcnt vmcnt(21)
	global_store_dwordx4 v2, v[4:7], s[40:41]
	s_add_u32 s40, s40, 0x10000
	s_addc_u32 s41, s41, 0
	v_fma_f32 v4, v4, v43, v20
	v_fma_f32 v5, v5, v43, v21
	v_fma_f32 v6, v6, v43, v22
	v_fma_f32 v7, v7, v43, v23
	global_load_dwordx4 v[20:23], v2, s[38:39]
	global_load_dword v43, v3, s[42:43]
	s_add_u32 s38, s38, 0x10000
	s_addc_u32 s39, s39, 0
	s_add_u32 s42, s42, 0x200
	s_addc_u32 s43, s43, 0
	s_waitcnt vmcnt(21)
	global_store_dwordx4 v2, v[4:7], s[40:41]
	s_add_u32 s40, s40, 0x10000
	s_addc_u32 s41, s41, 0
	v_fma_f32 v4, v4, v44, v24
	v_fma_f32 v5, v5, v44, v25
	v_fma_f32 v6, v6, v44, v26
	v_fma_f32 v7, v7, v44, v27
	global_load_dwordx4 v[24:27], v2, s[38:39]
	global_load_dword v44, v3, s[42:43]
	s_add_u32 s38, s38, 0x10000
	s_addc_u32 s39, s39, 0
	s_add_u32 s42, s42, 0x200
	s_addc_u32 s43, s43, 0
	s_waitcnt vmcnt(21)
	global_store_dwordx4 v2, v[4:7], s[40:41]
	s_add_u32 s40, s40, 0x10000
	s_addc_u32 s41, s41, 0
	v_fma_f32 v4, v4, v45, v28
	v_fma_f32 v5, v5, v45, v29
	v_fma_f32 v6, v6, v45, v30
	v_fma_f32 v7, v7, v45, v31
	global_load_dwordx4 v[28:31], v2, s[38:39]
	global_load_dword v45, v3, s[42:43]
	s_add_u32 s38, s38, 0x10000
	s_addc_u32 s39, s39, 0
	s_add_u32 s42, s42, 0x200
	s_addc_u32 s43, s43, 0
	s_waitcnt vmcnt(21)
	global_store_dwordx4 v2, v[4:7], s[40:41]
	s_add_u32 s40, s40, 0x10000
	s_addc_u32 s41, s41, 0
	v_fma_f32 v4, v4, v46, v32
	v_fma_f32 v5, v5, v46, v33
	v_fma_f32 v6, v6, v46, v34
	v_fma_f32 v7, v7, v46, v35
	global_load_dwordx4 v[32:35], v2, s[38:39]
	global_load_dword v46, v3, s[42:43]
	s_add_u32 s38, s38, 0x10000
	s_addc_u32 s39, s39, 0
	s_add_u32 s42, s42, 0x200
	s_addc_u32 s43, s43, 0
	s_waitcnt vmcnt(21)
	global_store_dwordx4 v2, v[4:7], s[40:41]
	s_add_u32 s40, s40, 0x10000
	s_addc_u32 s41, s41, 0
	v_fma_f32 v4, v4, v47, v36
	v_fma_f32 v5, v5, v47, v37
	v_fma_f32 v6, v6, v47, v38
	v_fma_f32 v7, v7, v47, v39
	global_load_dwordx4 v[36:39], v2, s[38:39]
	global_load_dword v47, v3, s[42:43]
	s_add_u32 s38, s38, 0x10000
	s_addc_u32 s39, s39, 0
	s_add_u32 s42, s42, 0x200
	s_addc_u32 s43, s43, 0
	s_waitcnt vmcnt(21)
	global_store_dwordx4 v2, v[4:7], s[40:41]
	s_add_u32 s40, s40, 0x10000
	s_addc_u32 s41, s41, 0
	v_fma_f32 v4, v4, v40, v8
	v_fma_f32 v5, v5, v40, v9
	v_fma_f32 v6, v6, v40, v10
	v_fma_f32 v7, v7, v40, v11
	global_load_dwordx4 v[8:11], v2, s[38:39]
	global_load_dword v40, v3, s[42:43]
	s_add_u32 s38, s38, 0x10000
	s_addc_u32 s39, s39, 0
	s_add_u32 s42, s42, 0x200
	s_addc_u32 s43, s43, 0
	s_waitcnt vmcnt(21)
	global_store_dwordx4 v2, v[4:7], s[40:41]
	s_add_u32 s40, s40, 0x10000
	s_addc_u32 s41, s41, 0
	v_fma_f32 v4, v4, v41, v12
	v_fma_f32 v5, v5, v41, v13
	v_fma_f32 v6, v6, v41, v14
	v_fma_f32 v7, v7, v41, v15
	global_load_dwordx4 v[12:15], v2, s[38:39]
	global_load_dword v41, v3, s[42:43]
	s_add_u32 s38, s38, 0x10000
	s_addc_u32 s39, s39, 0
	s_add_u32 s42, s42, 0x200
	s_addc_u32 s43, s43, 0
	s_waitcnt vmcnt(21)
	global_store_dwordx4 v2, v[4:7], s[40:41]
	s_add_u32 s40, s40, 0x10000
	s_addc_u32 s41, s41, 0
	v_fma_f32 v4, v4, v42, v16
	v_fma_f32 v5, v5, v42, v17
	v_fma_f32 v6, v6, v42, v18
	v_fma_f32 v7, v7, v42, v19
	global_load_dwordx4 v[16:19], v2, s[38:39]
	global_load_dword v42, v3, s[42:43]
	s_add_u32 s38, s38, 0x10000
	s_addc_u32 s39, s39, 0
	s_add_u32 s42, s42, 0x200
	s_addc_u32 s43, s43, 0
	s_waitcnt vmcnt(21)
	global_store_dwordx4 v2, v[4:7], s[40:41]
	s_add_u32 s40, s40, 0x10000
	s_addc_u32 s41, s41, 0
	v_fma_f32 v4, v4, v43, v20
	v_fma_f32 v5, v5, v43, v21
	v_fma_f32 v6, v6, v43, v22
	v_fma_f32 v7, v7, v43, v23
	global_load_dwordx4 v[20:23], v2, s[38:39]
	global_load_dword v43, v3, s[42:43]
	s_add_u32 s38, s38, 0x10000
	s_addc_u32 s39, s39, 0
	s_add_u32 s42, s42, 0x200
	s_addc_u32 s43, s43, 0
	s_waitcnt vmcnt(21)
	global_store_dwordx4 v2, v[4:7], s[40:41]
	s_add_u32 s40, s40, 0x10000
	s_addc_u32 s41, s41, 0
	v_fma_f32 v4, v4, v44, v24
	v_fma_f32 v5, v5, v44, v25
	v_fma_f32 v6, v6, v44, v26
	v_fma_f32 v7, v7, v44, v27
	global_load_dwordx4 v[24:27], v2, s[38:39]
	global_load_dword v44, v3, s[42:43]
	s_add_u32 s38, s38, 0x10000
	s_addc_u32 s39, s39, 0
	s_add_u32 s42, s42, 0x200
	s_addc_u32 s43, s43, 0
	s_waitcnt vmcnt(21)
	global_store_dwordx4 v2, v[4:7], s[40:41]
	s_add_u32 s40, s40, 0x10000
	s_addc_u32 s41, s41, 0
	v_fma_f32 v4, v4, v45, v28
	v_fma_f32 v5, v5, v45, v29
	v_fma_f32 v6, v6, v45, v30
	v_fma_f32 v7, v7, v45, v31
	global_load_dwordx4 v[28:31], v2, s[38:39]
	global_load_dword v45, v3, s[42:43]
	s_add_u32 s38, s38, 0x10000
	s_addc_u32 s39, s39, 0
	s_add_u32 s42, s42, 0x200
	s_addc_u32 s43, s43, 0
	s_waitcnt vmcnt(21)
	global_store_dwordx4 v2, v[4:7], s[40:41]
	s_add_u32 s40, s40, 0x10000
	s_addc_u32 s41, s41, 0
	v_fma_f32 v4, v4, v46, v32
	v_fma_f32 v5, v5, v46, v33
	v_fma_f32 v6, v6, v46, v34
	v_fma_f32 v7, v7, v46, v35
	global_load_dwordx4 v[32:35], v2, s[38:39]
	global_load_dword v46, v3, s[42:43]
	s_add_u32 s38, s38, 0x10000
	s_addc_u32 s39, s39, 0
	s_add_u32 s42, s42, 0x200
	s_addc_u32 s43, s43, 0
	s_waitcnt vmcnt(21)
	global_store_dwordx4 v2, v[4:7], s[40:41]
	s_add_u32 s40, s40, 0x10000
	s_addc_u32 s41, s41, 0
	v_fma_f32 v4, v4, v47, v36
	v_fma_f32 v5, v5, v47, v37
	v_fma_f32 v6, v6, v47, v38
	v_fma_f32 v7, v7, v47, v39
	global_load_dwordx4 v[36:39], v2, s[38:39]
	global_load_dword v47, v3, s[42:43]
	s_add_u32 s38, s38, 0x10000
	s_addc_u32 s39, s39, 0
	s_add_u32 s42, s42, 0x200
	s_addc_u32 s43, s43, 0
	s_waitcnt vmcnt(21)
	global_store_dwordx4 v2, v[4:7], s[40:41]
	s_add_u32 s40, s40, 0x10000
	s_addc_u32 s41, s41, 0
	v_fma_f32 v4, v4, v40, v8
	v_fma_f32 v5, v5, v40, v9
	v_fma_f32 v6, v6, v40, v10
	v_fma_f32 v7, v7, v40, v11
	global_load_dwordx4 v[8:11], v2, s[38:39]
	global_load_dword v40, v3, s[42:43]
	s_add_u32 s38, s38, 0x10000
	s_addc_u32 s39, s39, 0
	s_add_u32 s42, s42, 0x200
	s_addc_u32 s43, s43, 0
	s_waitcnt vmcnt(21)
	global_store_dwordx4 v2, v[4:7], s[40:41]
	s_add_u32 s40, s40, 0x10000
	s_addc_u32 s41, s41, 0
	v_fma_f32 v4, v4, v41, v12
	v_fma_f32 v5, v5, v41, v13
	v_fma_f32 v6, v6, v41, v14
	v_fma_f32 v7, v7, v41, v15
	global_load_dwordx4 v[12:15], v2, s[38:39]
	global_load_dword v41, v3, s[42:43]
	s_add_u32 s38, s38, 0x10000
	s_addc_u32 s39, s39, 0
	s_add_u32 s42, s42, 0x200
	s_addc_u32 s43, s43, 0
	s_waitcnt vmcnt(21)
	global_store_dwordx4 v2, v[4:7], s[40:41]
	s_add_u32 s40, s40, 0x10000
	s_addc_u32 s41, s41, 0
	v_fma_f32 v4, v4, v42, v16
	v_fma_f32 v5, v5, v42, v17
	v_fma_f32 v6, v6, v42, v18
	v_fma_f32 v7, v7, v42, v19
	global_load_dwordx4 v[16:19], v2, s[38:39]
	global_load_dword v42, v3, s[42:43]
	s_add_u32 s38, s38, 0x10000
	s_addc_u32 s39, s39, 0
	s_add_u32 s42, s42, 0x200
	s_addc_u32 s43, s43, 0
	s_waitcnt vmcnt(21)
	global_store_dwordx4 v2, v[4:7], s[40:41]
	s_add_u32 s40, s40, 0x10000
	s_addc_u32 s41, s41, 0
	v_fma_f32 v4, v4, v43, v20
	v_fma_f32 v5, v5, v43, v21
	v_fma_f32 v6, v6, v43, v22
	v_fma_f32 v7, v7, v43, v23
	global_load_dwordx4 v[20:23], v2, s[38:39]
	global_load_dword v43, v3, s[42:43]
	s_add_u32 s38, s38, 0x10000
	s_addc_u32 s39, s39, 0
	s_add_u32 s42, s42, 0x200
	s_addc_u32 s43, s43, 0
	s_waitcnt vmcnt(21)
	global_store_dwordx4 v2, v[4:7], s[40:41]
	s_add_u32 s40, s40, 0x10000
	s_addc_u32 s41, s41, 0
	v_fma_f32 v4, v4, v44, v24
	v_fma_f32 v5, v5, v44, v25
	v_fma_f32 v6, v6, v44, v26
	v_fma_f32 v7, v7, v44, v27
	global_load_dwordx4 v[24:27], v2, s[38:39]
	global_load_dword v44, v3, s[42:43]
	s_add_u32 s38, s38, 0x10000
	s_addc_u32 s39, s39, 0
	s_add_u32 s42, s42, 0x200
	s_addc_u32 s43, s43, 0
	s_waitcnt vmcnt(21)
	global_store_dwordx4 v2, v[4:7], s[40:41]
	s_add_u32 s40, s40, 0x10000
	s_addc_u32 s41, s41, 0
	v_fma_f32 v4, v4, v45, v28
	v_fma_f32 v5, v5, v45, v29
	v_fma_f32 v6, v6, v45, v30
	v_fma_f32 v7, v7, v45, v31
	global_load_dwordx4 v[28:31], v2, s[38:39]
	global_load_dword v45, v3, s[42:43]
	s_add_u32 s38, s38, 0x10000
	s_addc_u32 s39, s39, 0
	s_add_u32 s42, s42, 0x200
	s_addc_u32 s43, s43, 0
	s_waitcnt vmcnt(21)
	global_store_dwordx4 v2, v[4:7], s[40:41]
	s_add_u32 s40, s40, 0x10000
	s_addc_u32 s41, s41, 0
	v_fma_f32 v4, v4, v46, v32
	v_fma_f32 v5, v5, v46, v33
	v_fma_f32 v6, v6, v46, v34
	v_fma_f32 v7, v7, v46, v35
	global_load_dwordx4 v[32:35], v2, s[38:39]
	global_load_dword v46, v3, s[42:43]
	s_add_u32 s38, s38, 0x10000
	s_addc_u32 s39, s39, 0
	s_add_u32 s42, s42, 0x200
	s_addc_u32 s43, s43, 0
	s_waitcnt vmcnt(21)
	global_store_dwordx4 v2, v[4:7], s[40:41]
	s_add_u32 s40, s40, 0x10000
	s_addc_u32 s41, s41, 0
	v_fma_f32 v4, v4, v47, v36
	v_fma_f32 v5, v5, v47, v37
	v_fma_f32 v6, v6, v47, v38
	v_fma_f32 v7, v7, v47, v39
	global_load_dwordx4 v[36:39], v2, s[38:39]
	global_load_dword v47, v3, s[42:43]
	s_add_u32 s38, s38, 0x10000
	s_addc_u32 s39, s39, 0
	s_add_u32 s42, s42, 0x200
	s_addc_u32 s43, s43, 0
	s_waitcnt vmcnt(21)
	global_store_dwordx4 v2, v[4:7], s[40:41]
	s_add_u32 s40, s40, 0x10000
	s_addc_u32 s41, s41, 0
	v_fma_f32 v4, v4, v40, v8
	v_fma_f32 v5, v5, v40, v9
	v_fma_f32 v6, v6, v40, v10
	v_fma_f32 v7, v7, v40, v11
	global_load_dwordx4 v[8:11], v2, s[38:39]
	global_load_dword v40, v3, s[42:43]
	s_add_u32 s38, s38, 0x10000
	s_addc_u32 s39, s39, 0
	s_add_u32 s42, s42, 0x200
	s_addc_u32 s43, s43, 0
	s_waitcnt vmcnt(21)
	global_store_dwordx4 v2, v[4:7], s[40:41]
	s_add_u32 s40, s40, 0x10000
	s_addc_u32 s41, s41, 0
	v_fma_f32 v4, v4, v41, v12
	v_fma_f32 v5, v5, v41, v13
	v_fma_f32 v6, v6, v41, v14
	v_fma_f32 v7, v7, v41, v15
	global_load_dwordx4 v[12:15], v2, s[38:39]
	global_load_dword v41, v3, s[42:43]
	s_add_u32 s38, s38, 0x10000
	s_addc_u32 s39, s39, 0
	s_add_u32 s42, s42, 0x200
	s_addc_u32 s43, s43, 0
	s_waitcnt vmcnt(21)
	global_store_dwordx4 v2, v[4:7], s[40:41]
	s_add_u32 s40, s40, 0x10000
	s_addc_u32 s41, s41, 0
	v_fma_f32 v4, v4, v42, v16
	v_fma_f32 v5, v5, v42, v17
	v_fma_f32 v6, v6, v42, v18
	v_fma_f32 v7, v7, v42, v19
	global_load_dwordx4 v[16:19], v2, s[38:39]
	global_load_dword v42, v3, s[42:43]
	s_add_u32 s38, s38, 0x10000
	s_addc_u32 s39, s39, 0
	s_add_u32 s42, s42, 0x200
	s_addc_u32 s43, s43, 0
	s_waitcnt vmcnt(21)
	global_store_dwordx4 v2, v[4:7], s[40:41]
	s_add_u32 s40, s40, 0x10000
	s_addc_u32 s41, s41, 0
	v_fma_f32 v4, v4, v43, v20
	v_fma_f32 v5, v5, v43, v21
	v_fma_f32 v6, v6, v43, v22
	v_fma_f32 v7, v7, v43, v23
	global_load_dwordx4 v[20:23], v2, s[38:39]
	global_load_dword v43, v3, s[42:43]
	s_add_u32 s38, s38, 0x10000
	s_addc_u32 s39, s39, 0
	s_add_u32 s42, s42, 0x200
	s_addc_u32 s43, s43, 0
	s_waitcnt vmcnt(21)
	global_store_dwordx4 v2, v[4:7], s[40:41]
	s_add_u32 s40, s40, 0x10000
	s_addc_u32 s41, s41, 0
	v_fma_f32 v4, v4, v44, v24
	v_fma_f32 v5, v5, v44, v25
	v_fma_f32 v6, v6, v44, v26
	v_fma_f32 v7, v7, v44, v27
	global_load_dwordx4 v[24:27], v2, s[38:39]
	global_load_dword v44, v3, s[42:43]
	s_add_u32 s38, s38, 0x10000
	s_addc_u32 s39, s39, 0
	s_add_u32 s42, s42, 0x200
	s_addc_u32 s43, s43, 0
	s_waitcnt vmcnt(21)
	global_store_dwordx4 v2, v[4:7], s[40:41]
	s_add_u32 s40, s40, 0x10000
	s_addc_u32 s41, s41, 0
	v_fma_f32 v4, v4, v45, v28
	v_fma_f32 v5, v5, v45, v29
	v_fma_f32 v6, v6, v45, v30
	v_fma_f32 v7, v7, v45, v31
	global_load_dwordx4 v[28:31], v2, s[38:39]
	global_load_dword v45, v3, s[42:43]
	s_add_u32 s38, s38, 0x10000
	s_addc_u32 s39, s39, 0
	s_add_u32 s42, s42, 0x200
	s_addc_u32 s43, s43, 0
	s_waitcnt vmcnt(21)
	global_store_dwordx4 v2, v[4:7], s[40:41]
	s_add_u32 s40, s40, 0x10000
	s_addc_u32 s41, s41, 0
	v_fma_f32 v4, v4, v46, v32
	v_fma_f32 v5, v5, v46, v33
	v_fma_f32 v6, v6, v46, v34
	v_fma_f32 v7, v7, v46, v35
	global_load_dwordx4 v[32:35], v2, s[38:39]
	global_load_dword v46, v3, s[42:43]
	s_add_u32 s38, s38, 0x10000
	s_addc_u32 s39, s39, 0
	s_add_u32 s42, s42, 0x200
	s_addc_u32 s43, s43, 0
	s_waitcnt vmcnt(21)
	global_store_dwordx4 v2, v[4:7], s[40:41]
	s_add_u32 s40, s40, 0x10000
	s_addc_u32 s41, s41, 0
	v_fma_f32 v4, v4, v47, v36
	v_fma_f32 v5, v5, v47, v37
	v_fma_f32 v6, v6, v47, v38
	v_fma_f32 v7, v7, v47, v39
	global_load_dwordx4 v[36:39], v2, s[38:39]
	global_load_dword v47, v3, s[42:43]
	s_add_u32 s38, s38, 0x10000
	s_addc_u32 s39, s39, 0
	s_add_u32 s42, s42, 0x200
	s_addc_u32 s43, s43, 0
	s_waitcnt vmcnt(21)
	global_store_dwordx4 v2, v[4:7], s[40:41]
	s_add_u32 s40, s40, 0x10000
	s_addc_u32 s41, s41, 0
	v_fma_f32 v4, v4, v40, v8
	v_fma_f32 v5, v5, v40, v9
	v_fma_f32 v6, v6, v40, v10
	v_fma_f32 v7, v7, v40, v11
	global_load_dwordx4 v[8:11], v2, s[38:39]
	global_load_dword v40, v3, s[42:43]
	s_add_u32 s38, s38, 0x10000
	s_addc_u32 s39, s39, 0
	s_add_u32 s42, s42, 0x200
	s_addc_u32 s43, s43, 0
	s_waitcnt vmcnt(21)
	global_store_dwordx4 v2, v[4:7], s[40:41]
	s_add_u32 s40, s40, 0x10000
	s_addc_u32 s41, s41, 0
	v_fma_f32 v4, v4, v41, v12
	v_fma_f32 v5, v5, v41, v13
	v_fma_f32 v6, v6, v41, v14
	v_fma_f32 v7, v7, v41, v15
	global_load_dwordx4 v[12:15], v2, s[38:39]
	global_load_dword v41, v3, s[42:43]
	s_add_u32 s38, s38, 0x10000
	s_addc_u32 s39, s39, 0
	s_add_u32 s42, s42, 0x200
	s_addc_u32 s43, s43, 0
	s_waitcnt vmcnt(21)
	global_store_dwordx4 v2, v[4:7], s[40:41]
	s_add_u32 s40, s40, 0x10000
	s_addc_u32 s41, s41, 0
	v_fma_f32 v4, v4, v42, v16
	v_fma_f32 v5, v5, v42, v17
	v_fma_f32 v6, v6, v42, v18
	v_fma_f32 v7, v7, v42, v19
	global_load_dwordx4 v[16:19], v2, s[38:39]
	global_load_dword v42, v3, s[42:43]
	s_add_u32 s38, s38, 0x10000
	s_addc_u32 s39, s39, 0
	s_add_u32 s42, s42, 0x200
	s_addc_u32 s43, s43, 0
	s_waitcnt vmcnt(21)
	global_store_dwordx4 v2, v[4:7], s[40:41]
	s_add_u32 s40, s40, 0x10000
	s_addc_u32 s41, s41, 0
	v_fma_f32 v4, v4, v43, v20
	v_fma_f32 v5, v5, v43, v21
	v_fma_f32 v6, v6, v43, v22
	v_fma_f32 v7, v7, v43, v23
	global_load_dwordx4 v[20:23], v2, s[38:39]
	global_load_dword v43, v3, s[42:43]
	s_add_u32 s38, s38, 0x10000
	s_addc_u32 s39, s39, 0
	s_add_u32 s42, s42, 0x200
	s_addc_u32 s43, s43, 0
	s_waitcnt vmcnt(21)
	global_store_dwordx4 v2, v[4:7], s[40:41]
	s_add_u32 s40, s40, 0x10000
	s_addc_u32 s41, s41, 0
	v_fma_f32 v4, v4, v44, v24
	v_fma_f32 v5, v5, v44, v25
	v_fma_f32 v6, v6, v44, v26
	v_fma_f32 v7, v7, v44, v27
	global_load_dwordx4 v[24:27], v2, s[38:39]
	global_load_dword v44, v3, s[42:43]
	s_add_u32 s38, s38, 0x10000
	s_addc_u32 s39, s39, 0
	s_add_u32 s42, s42, 0x200
	s_addc_u32 s43, s43, 0
	s_waitcnt vmcnt(21)
	global_store_dwordx4 v2, v[4:7], s[40:41]
	s_add_u32 s40, s40, 0x10000
	s_addc_u32 s41, s41, 0
	v_fma_f32 v4, v4, v45, v28
	v_fma_f32 v5, v5, v45, v29
	v_fma_f32 v6, v6, v45, v30
	v_fma_f32 v7, v7, v45, v31
	global_load_dwordx4 v[28:31], v2, s[38:39]
	global_load_dword v45, v3, s[42:43]
	s_add_u32 s38, s38, 0x10000
	s_addc_u32 s39, s39, 0
	s_add_u32 s42, s42, 0x200
	s_addc_u32 s43, s43, 0
	s_waitcnt vmcnt(21)
	global_store_dwordx4 v2, v[4:7], s[40:41]
	s_add_u32 s40, s40, 0x10000
	s_addc_u32 s41, s41, 0
	v_fma_f32 v4, v4, v46, v32
	v_fma_f32 v5, v5, v46, v33
	v_fma_f32 v6, v6, v46, v34
	v_fma_f32 v7, v7, v46, v35
	global_load_dwordx4 v[32:35], v2, s[38:39]
	global_load_dword v46, v3, s[42:43]
	s_add_u32 s38, s38, 0x10000
	s_addc_u32 s39, s39, 0
	s_add_u32 s42, s42, 0x200
	s_addc_u32 s43, s43, 0
	s_waitcnt vmcnt(21)
	global_store_dwordx4 v2, v[4:7], s[40:41]
	s_add_u32 s40, s40, 0x10000
	s_addc_u32 s41, s41, 0
	v_fma_f32 v4, v4, v47, v36
	v_fma_f32 v5, v5, v47, v37
	v_fma_f32 v6, v6, v47, v38
	v_fma_f32 v7, v7, v47, v39
	global_load_dwordx4 v[36:39], v2, s[38:39]
	global_load_dword v47, v3, s[42:43]
	s_add_u32 s38, s38, 0x10000
	s_addc_u32 s39, s39, 0
	s_add_u32 s42, s42, 0x200
	s_addc_u32 s43, s43, 0
	s_waitcnt vmcnt(21)
	global_store_dwordx4 v2, v[4:7], s[40:41]
	s_add_u32 s40, s40, 0x10000
	s_addc_u32 s41, s41, 0
	v_fma_f32 v4, v4, v40, v8
	v_fma_f32 v5, v5, v40, v9
	v_fma_f32 v6, v6, v40, v10
	v_fma_f32 v7, v7, v40, v11
	global_load_dwordx4 v[8:11], v2, s[38:39]
	global_load_dword v40, v3, s[42:43]
	s_add_u32 s38, s38, 0x10000
	s_addc_u32 s39, s39, 0
	s_add_u32 s42, s42, 0x200
	s_addc_u32 s43, s43, 0
	s_waitcnt vmcnt(21)
	global_store_dwordx4 v2, v[4:7], s[40:41]
	s_add_u32 s40, s40, 0x10000
	s_addc_u32 s41, s41, 0
	v_fma_f32 v4, v4, v41, v12
	v_fma_f32 v5, v5, v41, v13
	v_fma_f32 v6, v6, v41, v14
	v_fma_f32 v7, v7, v41, v15
	global_load_dwordx4 v[12:15], v2, s[38:39]
	global_load_dword v41, v3, s[42:43]
	s_add_u32 s38, s38, 0x10000
	s_addc_u32 s39, s39, 0
	s_add_u32 s42, s42, 0x200
	s_addc_u32 s43, s43, 0
	s_waitcnt vmcnt(21)
	global_store_dwordx4 v2, v[4:7], s[40:41]
	s_add_u32 s40, s40, 0x10000
	s_addc_u32 s41, s41, 0
	v_fma_f32 v4, v4, v42, v16
	v_fma_f32 v5, v5, v42, v17
	v_fma_f32 v6, v6, v42, v18
	v_fma_f32 v7, v7, v42, v19
	global_load_dwordx4 v[16:19], v2, s[38:39]
	global_load_dword v42, v3, s[42:43]
	s_add_u32 s38, s38, 0x10000
	s_addc_u32 s39, s39, 0
	s_add_u32 s42, s42, 0x200
	s_addc_u32 s43, s43, 0
	s_waitcnt vmcnt(21)
	global_store_dwordx4 v2, v[4:7], s[40:41]
	s_add_u32 s40, s40, 0x10000
	s_addc_u32 s41, s41, 0
	v_fma_f32 v4, v4, v43, v20
	v_fma_f32 v5, v5, v43, v21
	v_fma_f32 v6, v6, v43, v22
	v_fma_f32 v7, v7, v43, v23
	global_load_dwordx4 v[20:23], v2, s[38:39]
	global_load_dword v43, v3, s[42:43]
	s_add_u32 s38, s38, 0x10000
	s_addc_u32 s39, s39, 0
	s_add_u32 s42, s42, 0x200
	s_addc_u32 s43, s43, 0
	s_waitcnt vmcnt(21)
	global_store_dwordx4 v2, v[4:7], s[40:41]
	s_add_u32 s40, s40, 0x10000
	s_addc_u32 s41, s41, 0
	v_fma_f32 v4, v4, v44, v24
	v_fma_f32 v5, v5, v44, v25
	v_fma_f32 v6, v6, v44, v26
	v_fma_f32 v7, v7, v44, v27
	global_load_dwordx4 v[24:27], v2, s[38:39]
	global_load_dword v44, v3, s[42:43]
	s_add_u32 s38, s38, 0x10000
	s_addc_u32 s39, s39, 0
	s_add_u32 s42, s42, 0x200
	s_addc_u32 s43, s43, 0
	s_waitcnt vmcnt(21)
	global_store_dwordx4 v2, v[4:7], s[40:41]
	s_add_u32 s40, s40, 0x10000
	s_addc_u32 s41, s41, 0
	v_fma_f32 v4, v4, v45, v28
	v_fma_f32 v5, v5, v45, v29
	v_fma_f32 v6, v6, v45, v30
	v_fma_f32 v7, v7, v45, v31
	global_load_dwordx4 v[28:31], v2, s[38:39]
	global_load_dword v45, v3, s[42:43]
	s_add_u32 s38, s38, 0x10000
	s_addc_u32 s39, s39, 0
	s_add_u32 s42, s42, 0x200
	s_addc_u32 s43, s43, 0
	s_waitcnt vmcnt(21)
	global_store_dwordx4 v2, v[4:7], s[40:41]
	s_add_u32 s40, s40, 0x10000
	s_addc_u32 s41, s41, 0
	v_fma_f32 v4, v4, v46, v32
	v_fma_f32 v5, v5, v46, v33
	v_fma_f32 v6, v6, v46, v34
	v_fma_f32 v7, v7, v46, v35
	global_load_dwordx4 v[32:35], v2, s[38:39]
	global_load_dword v46, v3, s[42:43]
	s_add_u32 s38, s38, 0x10000
	s_addc_u32 s39, s39, 0
	s_add_u32 s42, s42, 0x200
	s_addc_u32 s43, s43, 0
	s_waitcnt vmcnt(21)
	global_store_dwordx4 v2, v[4:7], s[40:41]
	s_add_u32 s40, s40, 0x10000
	s_addc_u32 s41, s41, 0
	v_fma_f32 v4, v4, v47, v36
	v_fma_f32 v5, v5, v47, v37
	v_fma_f32 v6, v6, v47, v38
	v_fma_f32 v7, v7, v47, v39
	global_load_dwordx4 v[36:39], v2, s[38:39]
	global_load_dword v47, v3, s[42:43]
	s_add_u32 s38, s38, 0x10000
	s_addc_u32 s39, s39, 0
	s_add_u32 s42, s42, 0x200
	s_addc_u32 s43, s43, 0
	s_waitcnt vmcnt(21)
	global_store_dwordx4 v2, v[4:7], s[40:41]
	s_add_u32 s40, s40, 0x10000
	s_addc_u32 s41, s41, 0
	v_fma_f32 v4, v4, v40, v8
	v_fma_f32 v5, v5, v40, v9
	v_fma_f32 v6, v6, v40, v10
	v_fma_f32 v7, v7, v40, v11
	s_waitcnt vmcnt(19)
	global_store_dwordx4 v2, v[4:7], s[40:41]
	s_add_u32 s40, s40, 0x10000
	s_addc_u32 s41, s41, 0
	v_fma_f32 v4, v4, v41, v12
	v_fma_f32 v5, v5, v41, v13
	v_fma_f32 v6, v6, v41, v14
	v_fma_f32 v7, v7, v41, v15
	s_waitcnt vmcnt(17)
	global_store_dwordx4 v2, v[4:7], s[40:41]
	s_add_u32 s40, s40, 0x10000
	s_addc_u32 s41, s41, 0
	v_fma_f32 v4, v4, v42, v16
	v_fma_f32 v5, v5, v42, v17
	v_fma_f32 v6, v6, v42, v18
	v_fma_f32 v7, v7, v42, v19
	s_waitcnt vmcnt(15)
	global_store_dwordx4 v2, v[4:7], s[40:41]
	s_add_u32 s40, s40, 0x10000
	s_addc_u32 s41, s41, 0
	v_fma_f32 v4, v4, v43, v20
	v_fma_f32 v5, v5, v43, v21
	v_fma_f32 v6, v6, v43, v22
	v_fma_f32 v7, v7, v43, v23
	s_waitcnt vmcnt(13)
	global_store_dwordx4 v2, v[4:7], s[40:41]
	s_add_u32 s40, s40, 0x10000
	s_addc_u32 s41, s41, 0
	v_fma_f32 v4, v4, v44, v24
	v_fma_f32 v5, v5, v44, v25
	v_fma_f32 v6, v6, v44, v26
	v_fma_f32 v7, v7, v44, v27
	s_waitcnt vmcnt(11)
	global_store_dwordx4 v2, v[4:7], s[40:41]
	s_add_u32 s40, s40, 0x10000
	s_addc_u32 s41, s41, 0
	v_fma_f32 v4, v4, v45, v28
	v_fma_f32 v5, v5, v45, v29
	v_fma_f32 v6, v6, v45, v30
	v_fma_f32 v7, v7, v45, v31
	s_waitcnt vmcnt(9)
	global_store_dwordx4 v2, v[4:7], s[40:41]
	s_add_u32 s40, s40, 0x10000
	s_addc_u32 s41, s41, 0
	v_fma_f32 v4, v4, v46, v32
	v_fma_f32 v5, v5, v46, v33
	v_fma_f32 v6, v6, v46, v34
	v_fma_f32 v7, v7, v46, v35
	s_waitcnt vmcnt(7)
	global_store_dwordx4 v2, v[4:7], s[40:41]
	s_add_u32 s40, s40, 0x10000
	s_addc_u32 s41, s41, 0

.LBB0_850:
	s_or_b64 exec, exec, s[0:1]
	s_movk_i32 s0, 0x100
	v_ashrrev_i32_e32 v202, 6, v196
	v_cmp_gt_u32_e64 s[36:37], s0, v196
	s_movk_i32 s0, 0xff
	v_and_b32_e32 v198, 3, v202
	s_waitcnt lgkmcnt(0)
	s_barrier
	v_cmp_lt_u32_e64 s[38:39], s0, v196
	s_lshl_b32 s0, s74, 6
	v_lshlrev_b32_e32 v195, 4, v198
	v_or_b32_e32 v191, s0, v192
	v_and_b32_e32 v200, 48, v196
	v_lshlrev_b32_e32 v118, 1, v192
	v_or_b32_e32 v197, v195, v192
	v_lshlrev_b32_e32 v190, 2, v191
	v_lshl_add_u32 v116, v192, 2, 0
	v_add_lshl_u32 v201, v192, s0, 2
	s_and_saveexec_b64 s[0:1], s[38:39]
	s_xor_b64 s[44:45], exec, s[0:1]
	s_cbranch_execz .LBB0_852
	v_readlane_b32 s80, v252, 18
	v_readlane_b32 s94, v252, 32
	v_readlane_b32 s95, v252, 33
	v_mul_u32_u24_e32 v0, 0x190, v197
	v_readlane_b32 s0, v254, 52
	v_readlane_b32 s81, v252, 19
	v_readlane_b32 s82, v252, 20
	v_add3_u32 v0, s0, v0, v200
	global_load_dword v76, v190, s[94:95]
	ds_read_b128 v[64:67], v0 offset:128
	v_readlane_b32 s83, v252, 21
	v_readlane_b32 s84, v252, 22
	v_readlane_b32 s85, v252, 23
	v_readlane_b32 s86, v252, 24
	v_readlane_b32 s87, v252, 25
	v_readlane_b32 s88, v252, 26
	v_readlane_b32 s89, v252, 27
	v_readlane_b32 s90, v252, 28
	v_readlane_b32 s91, v252, 29
	v_readlane_b32 s92, v252, 30
	v_readlane_b32 s93, v252, 31
	v_lshl_or_b32 v0, v194, 2, v195
	s_mov_b64 s[54:55], s[94:95]
	v_readlane_b32 s80, v252, 35
	v_mul_u32_u24_e32 v2, 0x300, v0
	v_readlane_b32 s81, v252, 36
	v_readlane_b32 s82, v252, 37
	v_readlane_b32 s83, v252, 38
	v_readlane_b32 s84, v252, 39
	v_readlane_b32 s85, v252, 40
	v_readlane_b32 s86, v252, 41
	v_readlane_b32 s87, v252, 42
	v_readlane_b32 s88, v252, 43
	v_readlane_b32 s89, v252, 44
	v_readlane_b32 s90, v252, 45
	v_readlane_b32 s91, v252, 46
	v_readlane_b32 s92, v252, 47
	v_readlane_b32 s93, v252, 48
	s_mov_b64 s[80:81], s[84:85]
	v_add_u32_e32 v77, 0xc400, v116
	v_add_u32_e32 v90, 0xcc00, v116
	v_add_u32_e32 v96, 0xd000, v116
	v_add3_u32 v85, 0, v2, v118
	s_waitcnt lgkmcnt(0)
	v_mfma_f32_16x16x32_bf16 v[72:75], v[64:67], v[24:27], 0
	s_mov_b64 s[82:83], s[86:87]
	global_load_dword v3, v190, s[80:81]
	global_load_dword v0, v190, s[82:83]
	ds_read2_b32 v[68:69], v77 offset0:192 offset1:208
	ds_read2_b32 v[80:81], v90 offset0:64 offset1:80
	ds_read2_b32 v[70:71], v96 offset0:192 offset1:208
	ds_read_u16 v2, v85 offset:128
	ds_read_u16 v82, v85 offset:160
	ds_read_u16 v79, v85 offset:896
	ds_read_u16 v107, v85 offset:1664
	ds_read_u16 v88, v85 offset:2432
	v_mfma_f32_16x16x32_bf16 v[112:115], v[64:67], v[48:51], 0
	s_waitcnt lgkmcnt(4)
	v_lshlrev_b32_e32 v78, 16, v2
	v_mov_b32_e32 v137, v81
	v_mov_b32_e32 v149, v71
	v_mov_b32_e32 v150, v81
	v_mov_b32_e32 v151, v80
	v_mov_b32_e32 v152, v71
	v_mov_b32_e32 v153, v70
	s_mov_b32 s4, 0x2b8cbccc
	v_readlane_b32 s94, v252, 49
	v_readlane_b32 s95, v252, 50
	s_mov_b64 s[84:85], s[88:89]
	s_mov_b64 s[86:87], s[90:91]
	s_mov_b64 s[88:89], s[92:93]
	s_waitcnt vmcnt(2)
	v_add_f32_e32 v2, v76, v72
	v_mul_f32_e32 v2, 0xbfb8aa3b, v2
	v_exp_f32_e32 v84, v2
	v_add_f32_e32 v2, v76, v73
	v_mul_f32_e32 v2, 0xbfb8aa3b, v2
	v_exp_f32_e32 v86, v2
	ds_read_u16 v2, v85 offset:3200
	s_waitcnt lgkmcnt(0)
	v_lshlrev_b32_e32 v83, 16, v2
	v_add_f32_e32 v2, v76, v74
	v_mul_f32_e32 v2, 0xbfb8aa3b, v2
	v_exp_f32_e32 v87, v2
	ds_read_u16 v2, v85 offset:3968
	v_pk_add_f32 v[86:87], v[86:87], 1.0 op_sel_hi:[1,0]
	s_waitcnt lgkmcnt(0)
	v_lshlrev_b32_e32 v89, 16, v2
	v_add_f32_e32 v2, v76, v75
	v_mul_f32_e32 v2, 0xbfb8aa3b, v2
	v_exp_f32_e32 v93, v2
	global_load_dword v2, v201, s[54:55] offset:64
	global_load_dword v101, v201, s[80:81] offset:64
	global_load_dword v102, v201, s[82:83] offset:64
	v_mfma_f32_16x16x32_bf16 v[72:75], v[64:67], v[32:35], 0
	ds_read_u16 v134, v85 offset:928
	ds_read_u16 v135, v85 offset:1696
	v_mfma_f32_16x16x32_bf16 v[64:67], v[64:67], v[56:59], 0
	s_waitcnt vmcnt(2)
	s_nop 3
	v_add_f32_e32 v72, v2, v72
	v_add_f32_e32 v73, v2, v73
	v_mul_f32_e32 v72, 0xbfb8aa3b, v72
	v_mul_f32_e32 v73, 0xbfb8aa3b, v73
	v_exp_f32_e32 v92, v72
	ds_read_u16 v72, v85 offset:2464
	v_exp_f32_e32 v108, v73
	ds_read_u16 v73, v85 offset:3232
	v_pk_add_f32 v[92:93], v[92:93], 1.0 op_sel_hi:[1,0]
	s_waitcnt lgkmcnt(0)
	v_lshlrev_b32_e32 v105, 16, v73
	v_add_f32_e32 v73, v2, v74
	v_add_f32_e32 v2, v2, v75
	v_mul_f32_e32 v73, 0xbfb8aa3b, v73
	v_mul_f32_e32 v2, 0xbfb8aa3b, v2
	v_exp_f32_e32 v109, v73
	ds_read_u16 v73, v85 offset:4000
	v_exp_f32_e32 v75, v2
	global_load_dword v76, v201, s[54:55] offset:128
	global_load_dword v91, v201, s[80:81] offset:128
	global_load_dword v2, v201, s[82:83] offset:128
	ds_read2_b32 v[94:95], v77 offset0:224 offset1:240
	ds_read2_b32 v[98:99], v90 offset0:96 offset1:112
	ds_read2_b32 v[96:97], v96 offset0:224 offset1:240
	ds_read_u16 v104, v85 offset:192
	ds_read_u16 v100, v85 offset:960
	ds_read_u16 v130, v85 offset:1728
	s_waitcnt lgkmcnt(4)
	v_mov_b32_e32 v128, v99
	v_mov_b32_e32 v129, v98
	v_mov_b32_e32 v116, v95
	v_mov_b32_e32 v117, v99
	s_waitcnt lgkmcnt(3)
	v_mov_b32_e32 v132, v97
	v_mov_b32_e32 v133, v96
	s_waitcnt lgkmcnt(1)
	v_lshlrev_b32_e32 v144, 16, v100
	s_waitcnt lgkmcnt(0)
	v_lshlrev_b32_e32 v145, 16, v130
	v_mov_b32_e32 v130, v94
	v_lshlrev_b32_e32 v73, 16, v73
	v_mov_b32_e32 v148, v96
	v_pk_add_f32 v[108:109], v[108:109], 1.0 op_sel_hi:[1,0]
	s_waitcnt vmcnt(2)
	v_add_f32_e32 v77, v76, v113
	v_mul_f32_e32 v77, 0xbfb8aa3b, v77
	v_add_f32_e32 v74, v76, v112
	ds_read_u16 v112, v85 offset:2496
	v_exp_f32_e32 v120, v77
	ds_read_u16 v77, v85 offset:3264
	v_mul_f32_e32 v74, 0xbfb8aa3b, v74
	v_exp_f32_e32 v74, v74
	s_waitcnt lgkmcnt(0)
	v_lshlrev_b32_e32 v119, 16, v77
	v_add_f32_e32 v77, v76, v114
	ds_read_u16 v114, v85 offset:4032
	global_load_dword v110, v201, s[54:55] offset:192
	global_load_dword v90, v201, s[80:81] offset:192
	global_load_dword v106, v201, s[82:83] offset:192
	v_add_f32_e32 v76, v76, v115
	v_mul_f32_e32 v77, 0xbfb8aa3b, v77
	v_mul_f32_e32 v76, 0xbfb8aa3b, v76
	v_exp_f32_e32 v121, v77
	v_exp_f32_e32 v77, v76
	ds_read_u16 v113, v85 offset:224
	ds_read_u16 v111, v85 offset:992
	ds_read_u16 v115, v85 offset:1760
	ds_read_u16 v118, v85 offset:2528
	ds_read_u16 v126, v85 offset:3296
	v_pk_add_f32 v[74:75], v[74:75], 1.0 op_sel_hi:[1,0]
	s_waitcnt lgkmcnt(3)
	v_lshlrev_b32_e32 v122, 16, v111
	s_waitcnt vmcnt(2)
	v_add_f32_e32 v64, v110, v64
	v_mul_f32_e32 v64, 0xbfb8aa3b, v64
	v_exp_f32_e32 v76, v64
	v_add_f32_e32 v64, v110, v65
	v_add_f32_e32 v65, v110, v66
	ds_read_u16 v66, v85 offset:4064
	v_mul_f32_e32 v64, 0xbfb8aa3b, v64
	v_mul_f32_e32 v65, 0xbfb8aa3b, v65
	v_exp_f32_e32 v64, v64
	v_exp_f32_e32 v65, v65
	s_waitcnt lgkmcnt(0)
	v_lshlrev_b32_e32 v103, 16, v66
	v_add_f32_e32 v66, v110, v67
	v_mul_f32_e32 v66, 0xbfb8aa3b, v66
	v_and_b32_e32 v67, 64, v179
	v_exp_f32_e32 v85, v66
	v_xor_b32_e32 v66, 1, v179
	v_add_u32_e32 v67, 64, v67
	v_cmp_lt_i32_e32 vcc, v66, v67
	v_pk_add_f32 v[64:65], v[64:65], 1.0 op_sel_hi:[1,0]
	v_lshlrev_b32_e32 v123, 16, v118
	v_cndmask_b32_e32 v66, v179, v66, vcc
	v_lshlrev_b32_e32 v143, 2, v66
	v_xor_b32_e32 v66, 2, v179
	v_cmp_lt_i32_e32 vcc, v66, v67
	v_pk_add_f32 v[76:77], v[76:77], 1.0 op_sel_hi:[1,0]
	v_lshlrev_b32_e32 v127, 16, v126
	v_cndmask_b32_e32 v66, v179, v66, vcc
	v_lshlrev_b32_e32 v142, 2, v66
	v_xor_b32_e32 v66, 4, v179
	v_cmp_lt_i32_e32 vcc, v66, v67
	v_mov_b32_e32 v126, v123
	v_pk_add_f32 v[84:85], v[84:85], 1.0 op_sel_hi:[1,0]
	v_cndmask_b32_e32 v66, v179, v66, vcc
	v_lshlrev_b32_e32 v141, 2, v66
	v_xor_b32_e32 v66, 8, v179
	v_cmp_lt_i32_e32 vcc, v66, v67
	s_nop 1
	v_cndmask_b32_e32 v66, v179, v66, vcc
	v_lshlrev_b32_e32 v140, 2, v66
	v_rcp_f32_e32 v111, v65
	v_lshlrev_b32_e32 v67, 16, v112
	v_lshlrev_b32_e32 v66, 16, v113
	v_rcp_f32_e32 v110, v64
	v_mov_b32_e32 v64, v95
	v_mov_b32_e32 v65, v94
	v_rcp_f32_e32 v113, v77
	v_mov_b32_e32 v118, v122
	v_rcp_f32_e32 v112, v76
	v_lshlrev_b32_e32 v77, 16, v114
	v_lshlrev_b32_e32 v76, 16, v115
	v_pk_mul_f32 v[114:115], v[128:129], v[118:119]
	v_mov_b32_e32 v136, v98
	v_pk_fma_f32 v[64:65], v[64:65], v[66:67], v[114:115]
	v_mov_b32_e32 v66, v97
	v_pk_fma_f32 v[138:139], v[132:133], v[76:77], v[64:65]
	v_pk_mul_f32 v[76:77], v[116:117], v[76:77] op_sel:[1,0] op_sel_hi:[0,0]
	v_mov_b32_e32 v64, v112
	v_mov_b32_e32 v65, v110
	v_pk_fma_f32 v[76:77], v[116:117], v[122:123], v[76:77]
	v_pk_add_f32 v[64:65], v[64:65], -1.0 op_sel_hi:[1,0]
	v_pk_fma_f32 v[128:129], v[66:67], v[126:127], v[76:77] op_sel_hi:[0,1,1]
	s_waitcnt vmcnt(0)
	v_pk_fma_f32 v[64:65], v[106:107], v[64:65], 1.0 op_sel_hi:[0,1,0]
	v_mov_b32_e32 v76, v138
	v_mov_b32_e32 v77, v128
	v_pk_mul_f32 v[76:77], v[64:65], v[76:77]
	v_pk_add_f32 v[64:65], v[120:121], 1.0 op_sel_hi:[1,0]
	v_pk_mul_f32 v[116:117], v[90:91], v[128:129] op_sel_hi:[0,1]
	v_mov_b32_e32 v131, v69
	v_pk_mul_f32 v[114:115], v[90:91], v[138:139]
	v_rcp_f32_e32 v121, v65
	v_rcp_f32_e32 v120, v64
	v_mov_b32_e32 v64, v121
	v_mov_b32_e32 v65, v113
	v_pk_add_f32 v[64:65], v[64:65], -1.0 op_sel_hi:[1,0]
	v_mov_b32_e32 v66, v145
	v_pk_fma_f32 v[146:147], v[2:3], v[64:65], 1.0 op_sel_hi:[0,1,0]
	v_lshlrev_b32_e32 v65, 16, v72
	v_lshlrev_b32_e32 v64, 16, v104
	v_mov_b32_e32 v118, v67
	v_pk_mul_f32 v[66:67], v[98:99], v[66:67] op_sel_hi:[0,1]
	v_pk_fma_f32 v[66:67], v[94:95], v[144:145], v[66:67] op_sel_hi:[0,1,1]
	v_rcp_f32_e32 v133, v75
	v_pk_fma_f32 v[66:67], v[96:97], v[118:119], v[66:67] op_sel_hi:[0,1,1]
	v_mov_b32_e32 v100, v91
	v_mov_b32_e32 v138, v67
	v_mov_b32_e32 v104, v144
	v_rcp_f32_e32 v132, v74
	v_pk_mul_f32 v[74:75], v[136:137], v[104:105]
	v_mov_b32_e32 v72, v145
	v_pk_fma_f32 v[74:75], v[130:131], v[64:65], v[74:75]
	v_mov_b32_e32 v104, v65
	v_pk_fma_f32 v[148:149], v[148:149], v[72:73], v[74:75]
	v_mov_b32_e32 v72, v132
	v_mov_b32_e32 v73, v120
	v_pk_add_f32 v[72:73], v[72:73], -1.0 op_sel_hi:[1,0]
	v_mov_b32_e32 v74, v148
	v_pk_fma_f32 v[72:73], v[2:3], v[72:73], 1.0 op_sel_hi:[0,1,0]
	v_mov_b32_e32 v2, v91
	v_pk_mul_f32 v[118:119], v[2:3], v[66:67] op_sel_hi:[0,1]
	v_mov_b32_e32 v75, v66
	v_pk_mul_f32 v[72:73], v[72:73], v[74:75]
	v_pk_mul_f32 v[74:75], v[146:147], v[138:139]
	v_rcp_f32_e32 v109, v109
	v_lshlrev_b32_e32 v138, 16, v82
	v_lshlrev_b32_e32 v139, 16, v88
	v_lshlrev_b32_e32 v67, 16, v135
	v_lshlrev_b32_e32 v66, 16, v134
	v_mov_b32_e32 v134, v109
	v_mov_b32_e32 v135, v133
	v_pk_add_f32 v[134:135], v[134:135], -1.0 op_sel_hi:[1,0]
	v_pk_fma_f32 v[144:145], v[102:103], v[134:135], 1.0 op_sel_hi:[0,1,0]
	v_rcp_f32_e32 v135, v93
	v_mov_b32_e32 v146, v69
	v_mov_b32_e32 v147, v68
	v_rcp_f32_e32 v108, v108
	v_rcp_f32_e32 v134, v92
	v_mov_b32_e32 v82, v66
	v_pk_mul_f32 v[92:93], v[150:151], v[82:83]
	v_mov_b32_e32 v88, v67
	v_pk_fma_f32 v[92:93], v[146:147], v[138:139], v[92:93]
	v_mov_b32_e32 v64, v67
	v_mov_b32_e32 v2, v101
	v_pk_fma_f32 v[92:93], v[152:153], v[88:89], v[92:93]
	v_mov_b32_e32 v82, v81
	v_pk_mul_f32 v[88:89], v[2:3], v[92:93]
	v_mov_b32_e32 v2, v69
	v_pk_mul_f32 v[64:65], v[82:83], v[64:65] op_sel_hi:[0,1]
	v_pk_fma_f32 v[64:65], v[2:3], v[66:67], v[64:65] op_sel_hi:[0,1,1]
	v_mov_b32_e32 v2, v71
	v_pk_fma_f32 v[66:67], v[2:3], v[104:105], v[64:65] op_sel_hi:[0,1,1]
	v_mov_b32_e32 v2, v101
	v_pk_mul_f32 v[130:131], v[100:101], v[148:149]
	v_pk_mul_f32 v[100:101], v[2:3], v[66:67] op_sel_hi:[0,1]
	v_mov_b32_e32 v148, v67
	v_mov_b32_e32 v65, v66
	v_pk_mul_f32 v[66:67], v[144:145], v[148:149]
	v_lshlrev_b32_e32 v144, 16, v79
	v_rcp_f32_e32 v87, v87
	v_mov_b32_e32 v146, v134
	v_mov_b32_e32 v147, v108
	v_pk_add_f32 v[146:147], v[146:147], -1.0 op_sel_hi:[1,0]
	v_rcp_f32_e32 v86, v86
	v_mov_b32_e32 v104, v87
	v_mov_b32_e32 v105, v135
	v_pk_fma_f32 v[146:147], v[102:103], v[146:147], 1.0 op_sel_hi:[0,1,0]
	v_mov_b32_e32 v64, v92
	v_pk_add_f32 v[104:105], v[104:105], -1.0 op_sel_hi:[1,0]
	v_pk_mul_f32 v[64:65], v[146:147], v[64:65]
	v_pk_fma_f32 v[146:147], v[0:1], v[104:105], 1.0 op_sel_hi:[0,1,0]
	v_rcp_f32_e32 v105, v85
	v_mov_b32_e32 v85, v86
	v_lshlrev_b32_e32 v145, 16, v107
	v_mov_b32_e32 v122, v144
	v_rcp_f32_e32 v104, v84
	s_nop 0
	v_mov_b32_e32 v84, v104
	v_mov_b32_e32 v69, v99
	v_mov_b32_e32 v79, v127
	v_pk_add_f32 v[84:85], v[84:85], -1.0 op_sel_hi:[1,0]
	v_pk_mul_f32 v[78:79], v[68:69], v[78:79]
	v_mov_b32_e32 v81, v95
	v_pk_fma_f32 v[148:149], v[0:1], v[84:85], 1.0 op_sel_hi:[0,1,0]
	v_mov_b32_e32 v84, v111
	v_mov_b32_e32 v85, v105
	v_mov_b32_e32 v71, v97
	v_pk_fma_f32 v[78:79], v[80:81], v[122:123], v[78:79]
	v_mov_b32_e32 v102, v145
	v_pk_add_f32 v[84:85], v[84:85], -1.0 op_sel_hi:[1,0]
	v_pk_fma_f32 v[94:95], v[70:71], v[102:103], v[78:79]
	v_pk_fma_f32 v[84:85], v[106:107], v[84:85], 1.0 op_sel_hi:[0,1,0]
	v_mov_b32_e32 v78, v129
	v_mov_b32_e32 v79, v95
	v_mov_b32_e32 v138, v145
	v_pk_mul_f32 v[78:79], v[84:85], v[78:79]
	v_mov_b32_e32 v84, v3
	v_mov_b32_e32 v85, v90
	v_pk_mul_f32 v[84:85], v[84:85], v[94:95]
	v_pk_mul_f32 v[80:81], v[80:81], v[138:139] op_sel_hi:[0,1]
	v_pk_fma_f32 v[68:69], v[68:69], v[144:145], v[80:81] op_sel_hi:[0,1,1]
	v_mov_b32_e32 v80, v84
	v_mov_b32_e32 v81, v131
	v_pk_mul_f32 v[80:81], v[80:81], v[80:81]
	v_mov_b32_e32 v136, v130
	v_mov_b32_e32 v137, v115
	v_pk_fma_f32 v[80:81], v[88:89], v[88:89], v[80:81]
	v_mov_b32_e32 v90, v114
	v_mov_b32_e32 v91, v85
	v_pk_fma_f32 v[80:81], v[136:137], v[136:137], v[80:81]
	v_mov_b32_e32 v82, v139
	v_pk_fma_f32 v[80:81], v[90:91], v[90:91], v[80:81]
	ds_bpermute_b32 v90, v143, v80
	ds_bpermute_b32 v91, v143, v81
	v_pk_fma_f32 v[70:71], v[70:71], v[82:83], v[68:69] op_sel_hi:[0,1,1]
	v_mov_b32_e32 v0, v3
	v_pk_mul_f32 v[2:3], v[0:1], v[70:71] op_sel_hi:[0,1]
	v_pk_mul_f32 v[82:83], v[100:101], v[100:101]
	s_waitcnt lgkmcnt(0)
	v_pk_add_f32 v[80:81], v[80:81], v[90:91]
	ds_bpermute_b32 v90, v142, v80
	ds_bpermute_b32 v91, v142, v81
	v_pk_fma_f32 v[82:83], v[2:3], v[2:3], v[82:83]
	v_mov_b32_e32 v92, v71
	v_pk_fma_f32 v[82:83], v[118:119], v[118:119], v[82:83]
	v_mov_b32_e32 v95, v70
	s_waitcnt lgkmcnt(0)
	v_pk_add_f32 v[80:81], v[80:81], v[90:91]
	ds_bpermute_b32 v90, v141, v80
	ds_bpermute_b32 v91, v141, v81
	v_pk_fma_f32 v[82:83], v[116:117], v[116:117], v[82:83]
	v_pk_mul_f32 v[70:71], v[146:147], v[92:93]
	v_pk_mul_f32 v[68:69], v[148:149], v[94:95]
	s_waitcnt lgkmcnt(0)
	v_pk_add_f32 v[80:81], v[80:81], v[90:91]
	ds_bpermute_b32 v90, v140, v80
	ds_bpermute_b32 v91, v140, v81
	s_waitcnt lgkmcnt(0)
	v_pk_add_f32 v[80:81], v[80:81], v[90:91]
	ds_bpermute_b32 v90, v143, v82
	ds_bpermute_b32 v91, v143, v83
	v_pk_add_f32 v[80:81], v[80:81], s[4:5] op_sel_hi:[1,0]
	s_waitcnt lgkmcnt(0)
	v_pk_add_f32 v[82:83], v[82:83], v[90:91]
	ds_bpermute_b32 v90, v142, v82
	ds_bpermute_b32 v91, v142, v83
	v_mul_f32_e32 v0, 0x4b800000, v80
	v_cmp_gt_f32_e64 s[0:1], s29, v80
	v_cmp_gt_f32_e32 vcc, s29, v81
	s_waitcnt lgkmcnt(0)
	v_pk_add_f32 v[82:83], v[82:83], v[90:91]
	ds_bpermute_b32 v90, v141, v82
	ds_bpermute_b32 v91, v141, v83
	v_cndmask_b32_e64 v0, v80, v0, s[0:1]
	v_rsq_f32_e32 v80, v0
	s_waitcnt lgkmcnt(0)
	v_pk_add_f32 v[82:83], v[82:83], v[90:91]
	ds_bpermute_b32 v90, v140, v82
	ds_bpermute_b32 v91, v140, v83
	s_waitcnt lgkmcnt(0)
	v_pk_add_f32 v[82:83], v[82:83], v[90:91]
	s_nop 0
	v_pk_add_f32 v[82:83], v[82:83], s[4:5] op_sel_hi:[1,0]
	s_mov_b32 s4, 0x45800000
	v_mul_f32_e32 v0, 0x4b800000, v82
	v_cmp_gt_f32_e64 s[42:43], s29, v82
	v_cmp_gt_f32_e64 s[40:41], s29, v83
	s_nop 0
	v_cndmask_b32_e64 v0, v82, v0, s[42:43]
	v_rsq_f32_e32 v82, v0
	v_mul_f32_e32 v0, 0x4b800000, v83
	v_cndmask_b32_e64 v0, v83, v0, s[40:41]
	v_rsq_f32_e32 v83, v0
	v_mul_f32_e32 v0, 0x4b800000, v81
	v_cndmask_b32_e32 v0, v81, v0, vcc
	v_rsq_f32_e32 v81, v0
	v_pk_mul_f32 v[90:91], v[82:83], s[4:5] op_sel_hi:[1,0]
	s_nop 0
	v_cndmask_b32_e64 v83, v83, v91, s[40:41]
	v_cndmask_b32_e64 v82, v82, v90, s[42:43]
	v_pk_mul_f32 v[90:91], v[80:81], s[4:5] op_sel_hi:[1,0]
	v_pk_mul_f32 v[140:141], v[2:3], v[82:83]
	v_cndmask_b32_e32 v81, v81, v91, vcc
	v_cndmask_b32_e64 v80, v80, v90, s[0:1]
	v_pk_mul_f32 v[128:129], v[88:89], v[80:81]
	v_pk_mul_f32 v[130:131], v[130:131], v[80:81]
	v_pk_mul_f32 v[126:127], v[84:85], v[80:81]
	v_pk_mul_f32 v[92:93], v[86:87], v[140:141]
	v_pk_mul_f32 v[90:91], v[134:135], v[128:129]
	v_pk_mul_f32 v[138:139], v[100:101], v[82:83]
	v_pk_mul_f32 v[86:87], v[132:133], v[130:131]
	v_pk_mul_f32 v[136:137], v[118:119], v[82:83]
	v_pk_mul_f32 v[132:133], v[114:115], v[80:81]
	v_pk_mul_f32 v[134:135], v[116:117], v[82:83]
	v_pk_mul_f32 v[88:89], v[108:109], v[138:139]
	v_pk_mul_f32 v[84:85], v[120:121], v[136:137]
	v_pk_mul_f32 v[80:81], v[112:113], v[132:133]
	v_pk_mul_f32 v[2:3], v[110:111], v[134:135]
	v_pk_mul_f32 v[82:83], v[104:105], v[126:127]
.LBB0_852:
	s_or_saveexec_b64 s[0:1], s[44:45]
	v_mov_b32_e32 v98, 0
	v_mov_b32_e32 v99, 0
	v_mov_b32_e32 v94, 0
	v_mov_b32_e32 v95, 0
	v_mov_b32_e32 v102, 0
	v_mov_b32_e32 v103, 0
	v_mov_b32_e32 v100, 0
	v_mov_b32_e32 v101, 0
	v_mov_b32_e32 v142, 0
	v_mov_b32_e32 v143, 0
	v_mov_b32_e32 v120, 0
	v_mov_b32_e32 v121, 0
	v_mov_b32_e32 v108, 0
	v_mov_b32_e32 v109, 0
	v_mov_b32_e32 v104, 0
	v_mov_b32_e32 v105, 0
	v_mov_b32_e32 v152, 0
	v_mov_b32_e32 v153, 0
	v_mov_b32_e32 v96, 0
	v_mov_b32_e32 v97, 0
	v_mov_b32_e32 v148, 0
	v_mov_b32_e32 v149, 0
	v_mov_b32_e32 v146, 0
	v_mov_b32_e32 v147, 0
	v_mov_b32_e32 v144, 0
	v_mov_b32_e32 v145, 0
	v_mov_b32_e32 v122, 0
	v_mov_b32_e32 v123, 0
	v_mov_b32_e32 v110, 0
	v_mov_b32_e32 v111, 0
	v_mov_b32_e32 v106, 0
	v_mov_b32_e32 v107, 0
	s_xor_b64 exec, exec, s[0:1]
	s_cbranch_execz .LBB0_854
	v_lshlrev_b32_e32 v66, 4, v202
	v_or_b32_e32 v0, v66, v192
	v_mul_lo_u32 v0, v0, s6
	v_lshlrev_b32_e32 v2, 4, v194
	v_readlane_b32 s4, v254, 52
	v_mov_b32_e32 v3, v1
	s_mul_i32 s10, s74, 0x3000
	v_add3_u32 v67, s4, v0, v2
	v_mul_u32_u24_e32 v0, 0x60, v192
	v_readlane_b32 s4, v253, 3
	v_lshlrev_b32_e32 v0, 1, v0
	v_readlane_b32 s5, v253, 4
	ds_read_b128 v[76:79], v67
	ds_read_b128 v[80:83], v67 offset:64
	v_lshl_add_u64 v[64:65], s[4:5], 0, v[0:1]
	v_lshl_add_u64 v[154:155], v[64:65], 0, v[2:3]
	v_lshl_add_u64 v[2:3], v[154:155], 0, s[10:11]
	ds_read_b128 v[92:95], v67 offset:192
	ds_read_b128 v[88:91], v67 offset:256
	ds_read_b128 v[84:87], v67 offset:320
	global_load_dwordx4 v[68:71], v[2:3], off
	global_load_dwordx4 v[96:99], v[2:3], off offset:64
	v_readlane_b32 s40, v252, 18
	v_readlane_b32 s44, v252, 22
	v_readlane_b32 s45, v252, 23
	v_readlane_b32 s46, v252, 24
	v_readlane_b32 s47, v252, 25
	v_readlane_b32 s48, v252, 26
	v_readlane_b32 s49, v252, 27
	v_readlane_b32 s50, v252, 28
	v_readlane_b32 s51, v252, 29
	s_mov_b64 s[44:45], s[48:49]
	s_mov_b64 s[46:47], s[50:51]
	s_waitcnt lgkmcnt(4)
	v_mfma_f32_16x16x32_bf16 v[72:75], v[76:79], v[24:27], 0
	v_lshl_or_b32 v0, v194, 2, v66
	v_mul_lo_u32 v0, v0, s13
	v_add_u32_e32 v132, 0xc800, v116
	s_waitcnt lgkmcnt(3)
	v_mfma_f32_16x16x32_bf16 v[64:67], v[80:83], v[20:23], 0
	v_add_u32_e32 v133, 0xcc00, v116
	v_add_u32_e32 v136, 0xd400, v116
	v_add_u32_e32 v137, 0xc400, v116
	v_add_u32_e32 v146, 0xd000, v116
	v_add3_u32 v119, 0, v0, v118
	s_mov_b32 s6, 0xbf1b4598
	v_readlane_b32 s41, v252, 19
	v_readlane_b32 s42, v252, 20
	v_readlane_b32 s43, v252, 21
	v_readlane_b32 s52, v252, 30
	v_readlane_b32 s53, v252, 31
	v_readlane_b32 s54, v252, 32
	v_readlane_b32 s55, v252, 33
	s_waitcnt vmcnt(1) lgkmcnt(2)
	v_mfma_f32_16x16x32_bf16 v[68:71], v[92:95], v[68:71], 0
	s_waitcnt vmcnt(0) lgkmcnt(1)
	v_mfma_f32_16x16x32_bf16 v[68:71], v[88:91], v[96:99], v[68:71]
	global_load_dwordx4 v[96:99], v[2:3], off offset:128
	global_load_dword v108, v190, s[46:47]
	global_load_dword v110, v190, s[46:47] offset:2048
	ds_read2_b32 v[100:101], v132 offset1:16
	ds_read2_b32 v[102:103], v133 offset0:128 offset1:144
	ds_read2_b32 v[130:131], v136 offset1:16
	ds_read2_b32 v[112:113], v137 offset0:128 offset1:144
	ds_read2_b32 v[114:115], v133 offset1:16
	ds_read2_b32 v[116:117], v146 offset0:128 offset1:144
	s_waitcnt vmcnt(2) lgkmcnt(6)
	v_mfma_f32_16x16x32_bf16 v[68:71], v[84:87], v[96:99], v[68:71]
	s_waitcnt vmcnt(1)
	v_add_f32_e32 v2, v72, v108
	v_mul_f32_e32 v2, 0xbfb8aa3b, v2
	v_exp_f32_e32 v97, v2
	s_waitcnt vmcnt(0)
	v_add_f32_e32 v2, v64, v110
	v_mul_f32_e32 v2, 0xbfb8aa3b, v2
	v_exp_f32_e32 v99, v2
	ds_read_u16 v0, v119
	ds_read_u16 v2, v119 offset:32
	s_waitcnt lgkmcnt(3)
	v_mov_b32_e32 v210, v115
	v_mov_b32_e32 v211, v114
	v_mov_b32_e32 v208, v113
	s_waitcnt lgkmcnt(1)
	v_lshlrev_b32_e32 v118, 16, v0
	v_add_f32_e32 v0, v73, v108
	v_mul_f32_e32 v0, 0xbfb8aa3b, v0
	v_exp_f32_e32 v96, v0
	v_mov_b32_e32 v209, v112
	v_pk_add_f32 v[72:73], v[96:97], 1.0 op_sel_hi:[1,0]
	v_rcp_f32_e32 v73, v73
	v_rcp_f32_e32 v72, v72
	v_add_f32_e32 v0, v65, v110
	v_mul_f32_e32 v0, 0xbfb8aa3b, v0
	v_exp_f32_e32 v98, v0
	v_pk_mul_f32 v[104:105], v[72:73], s[6:7] op_sel_hi:[1,0]
	v_pk_add_f32 v[64:65], v[98:99], 1.0 op_sel_hi:[1,0]
	v_rcp_f32_e32 v65, v65
	v_rcp_f32_e32 v64, v64
	ds_read_u16 v0, v119 offset:256
	ds_read_u16 v3, v119 offset:1024
	v_pk_mul_f32 v[106:107], v[64:65], s[6:7] op_sel_hi:[1,0]
	s_waitcnt lgkmcnt(1)
	v_lshlrev_b32_e32 v64, 16, v0
	ds_read_u16 v0, v119 offset:2560
	ds_read_u16 v65, v119 offset:1792
	s_waitcnt lgkmcnt(1)
	v_lshlrev_b32_e32 v73, 16, v0
	s_waitcnt lgkmcnt(0)
	v_lshlrev_b32_e32 v72, 16, v65
	v_lshlrev_b32_e32 v65, 16, v3
	v_mov_b32_e32 v96, v65
	v_mov_b32_e32 v97, v72
	v_pk_mul_f32 v[96:97], v[102:103], v[96:97] op_sel_hi:[0,1]
	v_add_f32_e32 v0, v74, v108
	v_pk_fma_f32 v[64:65], v[100:101], v[64:65], v[96:97] op_sel_hi:[0,1,1]
	v_mul_f32_e32 v0, 0xbfb8aa3b, v0
	v_pk_fma_f32 v[126:127], v[130:131], v[72:73], v[64:65] op_sel_hi:[0,1,1]
	v_exp_f32_e32 v65, v0
	v_add_f32_e32 v0, v66, v110
	v_mul_f32_e32 v0, 0xbfb8aa3b, v0
	v_exp_f32_e32 v97, v0
	ds_read_u16 v0, v119 offset:3072
	s_waitcnt lgkmcnt(0)
	v_lshlrev_b32_e32 v3, 16, v0
	v_add_f32_e32 v0, v75, v108
	v_mul_f32_e32 v0, 0xbfb8aa3b, v0
	v_exp_f32_e32 v64, v0
	s_nop 0
	v_pk_add_f32 v[64:65], v[64:65], 1.0 op_sel_hi:[1,0]
	v_rcp_f32_e32 v65, v65
	v_rcp_f32_e32 v64, v64
	v_add_f32_e32 v0, v67, v110
	v_mul_f32_e32 v0, 0xbfb8aa3b, v0
	v_exp_f32_e32 v96, v0
	v_pk_mul_f32 v[108:109], v[64:65], s[6:7] op_sel_hi:[1,0]
	v_pk_add_f32 v[64:65], v[96:97], 1.0 op_sel_hi:[1,0]
	v_mfma_f32_16x16x32_bf16 v[96:99], v[76:79], v[32:35], 0
	v_rcp_f32_e32 v65, v65
	v_rcp_f32_e32 v64, v64
	s_nop 0
	v_pk_mul_f32 v[110:111], v[64:65], s[6:7] op_sel_hi:[1,0]
	ds_read_u16 v0, v119 offset:4096
	ds_read_u16 v64, v119 offset:3328
	s_waitcnt lgkmcnt(1)
	v_lshlrev_b32_e32 v65, 16, v0
	ds_read_u16 v0, v119 offset:3840
	s_waitcnt lgkmcnt(1)
	v_lshlrev_b32_e32 v64, 16, v64
	v_pk_mov_b32 v[66:67], v[72:73], v[64:65] op_sel:[1,0]
	s_waitcnt lgkmcnt(0)
	v_lshlrev_b32_e32 v153, 16, v0
	v_or_b32_e32 v0, 16, v191
	v_sub_u32_e32 v0, v0, v192
	v_mul_u32_u24_e32 v0, 0x60, v0
	v_pk_mul_f32 v[66:67], v[102:103], v[66:67] op_sel_hi:[0,1]
	v_lshlrev_b32_e32 v0, 1, v0
	v_pk_fma_f32 v[66:67], v[100:101], v[72:73], v[66:67] op_sel_hi:[0,1,1]
	v_lshl_add_u64 v[134:135], v[154:155], 0, v[0:1]
	v_pk_fma_f32 v[128:129], v[130:131], v[64:65], v[66:67] op_sel_hi:[0,1,1]
	global_load_dwordx4 v[64:67], v[134:135], off
	global_load_dwordx4 v[120:123], v[134:135], off offset:64
	v_mfma_f32_16x16x32_bf16 v[72:75], v[80:83], v[28:31], 0
	s_waitcnt vmcnt(1)
	v_mfma_f32_16x16x32_bf16 v[64:67], v[92:95], v[64:67], 0
	s_waitcnt vmcnt(0)
	v_mfma_f32_16x16x32_bf16 v[64:67], v[88:91], v[120:123], v[64:67]
	global_load_dwordx4 v[120:123], v[134:135], off offset:128
	global_load_dword v130, v201, s[46:47] offset:64
	global_load_dword v138, v201, s[46:47] offset:2112
	s_waitcnt vmcnt(1)
	v_add_f32_e32 v0, v96, v130
	v_mul_f32_e32 v0, 0xbfb8aa3b, v0
	v_mfma_f32_16x16x32_bf16 v[64:67], v[84:87], v[120:123], v[64:67]
	v_exp_f32_e32 v121, v0
	s_waitcnt vmcnt(0)
	v_add_f32_e32 v0, v72, v138
	v_mul_f32_e32 v0, 0xbfb8aa3b, v0
	v_exp_f32_e32 v123, v0
	v_add_f32_e32 v0, v97, v130
	v_mul_f32_e32 v0, 0xbfb8aa3b, v0
	v_exp_f32_e32 v120, v0
	s_nop 0
	v_pk_add_f32 v[96:97], v[120:121], 1.0 op_sel_hi:[1,0]
	v_rcp_f32_e32 v97, v97
	v_rcp_f32_e32 v96, v96
	v_add_f32_e32 v0, v73, v138
	v_mul_f32_e32 v0, 0xbfb8aa3b, v0
	v_exp_f32_e32 v122, v0
	v_pk_mul_f32 v[120:121], v[96:97], s[6:7] op_sel_hi:[1,0]
	v_pk_add_f32 v[72:73], v[122:123], 1.0 op_sel_hi:[1,0]
	v_rcp_f32_e32 v73, v73
	v_rcp_f32_e32 v72, v72
	s_nop 0
	v_pk_mul_f32 v[122:123], v[72:73], s[6:7] op_sel_hi:[1,0]
	ds_read_u16 v0, v119 offset:288
	ds_read_u16 v73, v119 offset:1056
	v_mov_b32_e32 v100, v103
	s_waitcnt lgkmcnt(1)
	v_lshlrev_b32_e32 v72, 16, v0
	ds_read_u16 v0, v119 offset:2592
	ds_read_u16 v96, v119 offset:1824
	s_waitcnt lgkmcnt(2)
	v_lshlrev_b32_e32 v73, 16, v73
	v_mov_b32_e32 v134, v73
	s_waitcnt lgkmcnt(1)
	v_lshlrev_b32_e32 v97, 16, v0
	s_waitcnt lgkmcnt(0)
	v_lshlrev_b32_e32 v96, 16, v96
	v_mov_b32_e32 v135, v96
	v_mov_b32_e32 v0, v101
	v_pk_mul_f32 v[102:103], v[100:101], v[134:135] op_sel_hi:[0,1]
	v_pk_fma_f32 v[72:73], v[0:1], v[72:73], v[102:103] op_sel_hi:[0,1,1]
	v_mov_b32_e32 v102, v131
	v_pk_fma_f32 v[134:135], v[102:103], v[96:97], v[72:73] op_sel_hi:[0,1,1]
	v_add_f32_e32 v72, v98, v130
	v_mul_f32_e32 v72, 0xbfb8aa3b, v72
	v_exp_f32_e32 v73, v72
	v_add_f32_e32 v72, v74, v138
	v_mul_f32_e32 v72, 0xbfb8aa3b, v72
	v_exp_f32_e32 v131, v72
	ds_read_u16 v72, v119 offset:3104
	s_waitcnt lgkmcnt(0)
	v_lshlrev_b32_e32 v167, 16, v72
	v_add_f32_e32 v72, v99, v130
	v_mul_f32_e32 v72, 0xbfb8aa3b, v72
	v_exp_f32_e32 v72, v72
	s_nop 0
	v_pk_add_f32 v[72:73], v[72:73], 1.0 op_sel_hi:[1,0]
	v_rcp_f32_e32 v73, v73
	v_div_scale_f32 v74, s[4:5], v72, v72, 1.0
	v_rcp_f32_e32 v98, v74
	s_nop 0
	v_fma_f32 v99, -v74, v98, 1.0
	v_fmac_f32_e32 v98, v99, v98
	v_div_scale_f32 v99, vcc, 1.0, v72, 1.0
	v_mul_f32_e32 v101, v99, v98
	v_fma_f32 v103, -v74, v101, v99
	v_fmac_f32_e32 v101, v103, v98
	v_fma_f32 v74, -v74, v101, v99
	v_div_fmas_f32 v74, v74, v98, v101
	v_div_fixup_f32 v72, v74, v72, 1.0
	v_pk_mul_f32 v[142:143], v[72:73], s[6:7] op_sel_hi:[1,0]
	v_add_f32_e32 v72, v75, v138
	v_mul_f32_e32 v72, 0xbfb8aa3b, v72
	v_exp_f32_e32 v130, v72
	s_nop 0
	v_pk_add_f32 v[72:73], v[130:131], 1.0 op_sel_hi:[1,0]
	v_rcp_f32_e32 v73, v73
	v_div_scale_f32 v74, s[4:5], v72, v72, 1.0
	v_rcp_f32_e32 v75, v74
	s_nop 0
	v_fma_f32 v98, -v74, v75, 1.0
	v_fmac_f32_e32 v75, v98, v75
	v_div_scale_f32 v98, vcc, 1.0, v72, 1.0
	v_mul_f32_e32 v99, v98, v75
	v_fma_f32 v101, -v74, v99, v98
	v_fmac_f32_e32 v99, v101, v75
	v_fma_f32 v74, -v74, v99, v98
	v_div_fmas_f32 v74, v74, v75, v99
	v_div_fixup_f32 v72, v74, v72, 1.0
	v_pk_mul_f32 v[144:145], v[72:73], s[6:7] op_sel_hi:[1,0]
	ds_read_u16 v73, v119 offset:4128
	ds_read_u16 v72, v119 offset:3360
	s_waitcnt lgkmcnt(1)
	v_lshlrev_b32_e32 v73, 16, v73
	s_waitcnt lgkmcnt(0)
	v_lshlrev_b32_e32 v72, 16, v72
	v_pk_mov_b32 v[74:75], v[96:97], v[72:73] op_sel:[1,0]
	s_nop 0
	v_pk_mul_f32 v[74:75], v[100:101], v[74:75] op_sel_hi:[0,1]
	v_pk_fma_f32 v[74:75], v[0:1], v[96:97], v[74:75] op_sel_hi:[0,1,1]
	ds_read_u16 v0, v119 offset:3872
	v_pk_fma_f32 v[130:131], v[102:103], v[72:73], v[74:75] op_sel_hi:[0,1,1]
	v_mfma_f32_16x16x32_bf16 v[96:99], v[80:83], v[36:39], 0
	s_waitcnt lgkmcnt(0)
	v_lshlrev_b32_e32 v169, 16, v0
	v_or_b32_e32 v0, 32, v191
	v_sub_u32_e32 v0, v0, v192
	v_mul_u32_u24_e32 v0, 0x60, v0
	v_lshlrev_b32_e32 v0, 1, v0
	v_lshl_add_u64 v[148:149], v[154:155], 0, v[0:1]
	global_load_dwordx4 v[72:75], v[148:149], off
	global_load_dwordx4 v[138:141], v[148:149], off offset:64
	s_waitcnt vmcnt(1)
	v_mfma_f32_16x16x32_bf16 v[72:75], v[92:95], v[72:75], 0
	s_waitcnt vmcnt(0)
	v_mfma_f32_16x16x32_bf16 v[72:75], v[88:91], v[138:141], v[72:75]
	global_load_dwordx4 v[138:141], v[148:149], off offset:128
	global_load_dword v0, v201, s[46:47] offset:128
	global_load_dword v152, v201, s[46:47] offset:2176
	s_waitcnt vmcnt(0)
	v_add_f32_e32 v96, v96, v152
	v_mfma_f32_16x16x32_bf16 v[100:103], v[76:79], v[48:51], 0
	v_mul_f32_e32 v96, 0xbfb8aa3b, v96
	v_exp_f32_e32 v147, v96
	v_mfma_f32_16x16x32_bf16 v[72:75], v[84:87], v[138:141], v[72:75]
	ds_read2_b32 v[158:159], v132 offset0:32 offset1:48
	ds_read2_b32 v[164:165], v133 offset0:160 offset1:176
	ds_read2_b32 v[156:157], v136 offset0:32 offset1:48
	ds_read2_b32 v[140:141], v137 offset0:160 offset1:176
	ds_read2_b32 v[138:139], v133 offset0:32 offset1:48
	ds_read2_b32 v[136:137], v146 offset0:160 offset1:176
	v_add_f32_e32 v100, v100, v0
	v_add_f32_e32 v96, v101, v0
	v_mul_f32_e32 v100, 0xbfb8aa3b, v100
	v_mul_f32_e32 v96, 0xbfb8aa3b, v96
	v_exp_f32_e32 v133, v100
	v_exp_f32_e32 v132, v96
	v_mfma_f32_16x16x32_bf16 v[80:83], v[80:83], v[60:63], 0
	s_waitcnt lgkmcnt(4)
	v_mov_b32_e32 v176, v165
	s_waitcnt lgkmcnt(3)
	v_mov_b32_e32 v178, v157
	v_pk_add_f32 v[100:101], v[132:133], 1.0 op_sel_hi:[1,0]
	v_rcp_f32_e32 v101, v101
	v_rcp_f32_e32 v100, v100
	v_add_f32_e32 v96, v97, v152
	v_mul_f32_e32 v96, 0xbfb8aa3b, v96
	v_exp_f32_e32 v146, v96
	v_pk_mul_f32 v[100:101], v[100:101], s[6:7] op_sel_hi:[1,0]
	v_pk_add_f32 v[96:97], v[146:147], 1.0 op_sel_hi:[1,0]
	v_rcp_f32_e32 v97, v97
	v_rcp_f32_e32 v96, v96
	s_nop 0
	v_pk_mul_f32 v[146:147], v[96:97], s[6:7] op_sel_hi:[1,0]
	ds_read_u16 v96, v119 offset:320
	ds_read_u16 v97, v119 offset:1088
	ds_read_u16 v133, v119 offset:2624
	ds_read_u16 v132, v119 offset:1856
	s_waitcnt lgkmcnt(3)
	v_lshlrev_b32_e32 v96, 16, v96
	s_waitcnt lgkmcnt(2)
	v_lshlrev_b32_e32 v97, 16, v97
	s_waitcnt lgkmcnt(0)
	v_lshlrev_b32_e32 v132, 16, v132
	v_mov_b32_e32 v148, v97
	v_mov_b32_e32 v149, v132
	v_pk_mul_f32 v[148:149], v[164:165], v[148:149] op_sel_hi:[0,1]
	v_lshlrev_b32_e32 v133, 16, v133
	v_pk_fma_f32 v[96:97], v[158:159], v[96:97], v[148:149] op_sel_hi:[0,1,1]
	v_pk_fma_f32 v[150:151], v[156:157], v[132:133], v[96:97] op_sel_hi:[0,1,1]
	v_add_f32_e32 v96, v102, v0
	v_mul_f32_e32 v96, 0xbfb8aa3b, v96
	v_exp_f32_e32 v97, v96
	v_add_f32_e32 v96, v98, v152
	v_mul_f32_e32 v96, 0xbfb8aa3b, v96
	v_exp_f32_e32 v149, v96
	ds_read_u16 v96, v119 offset:3136
	v_add_f32_e32 v0, v103, v0
	v_mul_f32_e32 v0, 0xbfb8aa3b, v0
	s_waitcnt lgkmcnt(0)
	v_lshlrev_b32_e32 v171, 16, v96
	v_exp_f32_e32 v96, v0
	s_nop 0
	v_pk_add_f32 v[96:97], v[96:97], 1.0 op_sel_hi:[1,0]
	v_rcp_f32_e32 v97, v97
	v_rcp_f32_e32 v96, v96
	v_add_f32_e32 v0, v99, v152
	v_mul_f32_e32 v0, 0xbfb8aa3b, v0
	v_exp_f32_e32 v148, v0
	v_pk_mul_f32 v[102:103], v[96:97], s[6:7] op_sel_hi:[1,0]
	v_pk_add_f32 v[96:97], v[148:149], 1.0 op_sel_hi:[1,0]
	v_rcp_f32_e32 v97, v97
	v_rcp_f32_e32 v96, v96
	s_nop 0
	v_pk_mul_f32 v[148:149], v[96:97], s[6:7] op_sel_hi:[1,0]
	ds_read_u16 v0, v119 offset:4160
	ds_read_u16 v96, v119 offset:3392
	s_waitcnt lgkmcnt(1)
	v_lshlrev_b32_e32 v97, 16, v0
	ds_read_u16 v0, v119 offset:3904
	s_waitcnt lgkmcnt(1)
	v_lshlrev_b32_e32 v96, 16, v96
	v_pk_mov_b32 v[98:99], v[132:133], v[96:97] op_sel:[1,0]
	s_waitcnt lgkmcnt(0)
	v_lshlrev_b32_e32 v173, 16, v0
	v_or_b32_e32 v0, 48, v191
	v_sub_u32_e32 v0, v0, v192
	v_mul_u32_u24_e32 v0, 0x60, v0
	v_pk_mul_f32 v[98:99], v[164:165], v[98:99] op_sel_hi:[0,1]
	v_lshlrev_b32_e32 v0, 1, v0
	v_pk_fma_f32 v[98:99], v[158:159], v[132:133], v[98:99] op_sel_hi:[0,1,1]
	v_lshl_add_u64 v[154:155], v[154:155], 0, v[0:1]
	v_pk_fma_f32 v[132:133], v[156:157], v[96:97], v[98:99] op_sel_hi:[0,1,1]
	v_mfma_f32_16x16x32_bf16 v[96:99], v[76:79], v[56:59], 0
	global_load_dwordx4 v[76:79], v[154:155], off
	s_waitcnt vmcnt(0)
	v_mfma_f32_16x16x32_bf16 v[76:79], v[92:95], v[76:79], 0
	global_load_dwordx4 v[92:95], v[154:155], off offset:64
	s_waitcnt vmcnt(0)
	v_mfma_f32_16x16x32_bf16 v[76:79], v[88:91], v[92:95], v[76:79]
	global_load_dwordx4 v[88:91], v[154:155], off offset:128
	global_load_dword v180, v201, s[46:47] offset:192
	global_load_dword v203, v201, s[46:47] offset:2240
	s_waitcnt vmcnt(1)
	v_add_f32_e32 v0, v96, v180
	v_mul_f32_e32 v0, 0xbfb8aa3b, v0
	v_mfma_f32_16x16x32_bf16 v[76:79], v[84:87], v[88:91], v[76:79]
	v_exp_f32_e32 v85, v0
	s_waitcnt vmcnt(0)
	v_add_f32_e32 v0, v80, v203
	v_mul_f32_e32 v0, 0xbfb8aa3b, v0
	v_exp_f32_e32 v87, v0
	v_add_f32_e32 v0, v97, v180
	v_mul_f32_e32 v0, 0xbfb8aa3b, v0
	v_exp_f32_e32 v84, v0
	v_lshlrev_b32_e32 v90, 16, v2
	v_pk_add_f32 v[84:85], v[84:85], 1.0 op_sel_hi:[1,0]
	v_rcp_f32_e32 v85, v85
	v_rcp_f32_e32 v84, v84
	v_add_f32_e32 v0, v81, v203
	v_mul_f32_e32 v0, 0xbfb8aa3b, v0
	v_exp_f32_e32 v86, v0
	v_pk_mul_f32 v[94:95], v[84:85], s[6:7] op_sel_hi:[1,0]
	v_pk_add_f32 v[80:81], v[86:87], 1.0 op_sel_hi:[1,0]
	v_rcp_f32_e32 v81, v81
	v_rcp_f32_e32 v80, v80
	s_nop 0
	v_pk_mul_f32 v[96:97], v[80:81], s[6:7] op_sel_hi:[1,0]
	ds_read_u16 v0, v119 offset:352
	ds_read_u16 v81, v119 offset:1120
	s_waitcnt lgkmcnt(1)
	v_lshlrev_b32_e32 v80, 16, v0
	ds_read_u16 v0, v119 offset:2656
	ds_read_u16 v84, v119 offset:1888
	s_waitcnt lgkmcnt(2)
	v_lshlrev_b32_e32 v81, 16, v81
	s_waitcnt lgkmcnt(1)
	v_lshlrev_b32_e32 v175, 16, v0
	s_waitcnt lgkmcnt(0)
	v_lshlrev_b32_e32 v174, 16, v84
	v_mov_b32_e32 v84, v81
	v_mov_b32_e32 v85, v174
	v_mov_b32_e32 v0, v159
	v_pk_mul_f32 v[84:85], v[176:177], v[84:85] op_sel_hi:[0,1]
	v_pk_fma_f32 v[80:81], v[0:1], v[80:81], v[84:85] op_sel_hi:[0,1,1]
	v_pk_fma_f32 v[154:155], v[178:179], v[174:175], v[80:81] op_sel_hi:[0,1,1]
	v_add_f32_e32 v80, v98, v180
	v_mul_f32_e32 v80, 0xbfb8aa3b, v80
	v_exp_f32_e32 v205, v80
	v_add_f32_e32 v80, v82, v203
	v_mul_f32_e32 v80, 0xbfb8aa3b, v80
	v_exp_f32_e32 v181, v80
	ds_read_u16 v80, v119 offset:864
	ds_read_u16 v81, v119 offset:1632
	v_mov_b32_e32 v98, v115
	s_waitcnt lgkmcnt(1)
	v_lshlrev_b32_e32 v206, 16, v80
	ds_read_u16 v80, v119 offset:3168
	ds_read_u16 v82, v119 offset:2400
	s_waitcnt lgkmcnt(2)
	v_lshlrev_b32_e32 v207, 16, v81
	v_mov_b32_e32 v156, v207
	v_mov_b32_e32 v172, v207
	s_waitcnt lgkmcnt(1)
	v_lshlrev_b32_e32 v159, 16, v80
	s_waitcnt lgkmcnt(0)
	v_lshlrev_b32_e32 v157, 16, v82
	ds_read_u16 v80, v119 offset:96
	ds_read_u16 v81, v119 offset:2368
	ds_read_u16 v82, v119 offset:832
	ds_read_u16 v84, v119 offset:1600
	v_mov_b32_e32 v158, v157
	s_waitcnt lgkmcnt(3)
	v_lshlrev_b32_e32 v80, 16, v80
	s_waitcnt lgkmcnt(2)
	v_lshlrev_b32_e32 v81, 16, v81
	s_waitcnt lgkmcnt(0)
	v_lshlrev_b32_e32 v85, 16, v84
	v_lshlrev_b32_e32 v84, 16, v82
	ds_read_u16 v82, v119 offset:64
	ds_read_u16 v86, v119 offset:2336
	v_mov_b32_e32 v168, v85
	v_mov_b32_e32 v170, v81
	s_waitcnt lgkmcnt(0)
	v_lshlrev_b32_e32 v87, 16, v86
	v_lshlrev_b32_e32 v86, 16, v82
	ds_read_u16 v82, v119 offset:800
	ds_read_u16 v88, v119 offset:1568
	v_mov_b32_e32 v166, v87
	s_waitcnt lgkmcnt(0)
	v_lshlrev_b32_e32 v89, 16, v88
	v_lshlrev_b32_e32 v88, 16, v82
	ds_read_u16 v82, v119 offset:2304
	v_mov_b32_e32 v152, v89
	s_waitcnt lgkmcnt(0)
	v_lshlrev_b32_e32 v91, 16, v82
	ds_read_u16 v2, v119 offset:768
	ds_read_u16 v82, v119 offset:1536
	v_mov_b32_e32 v93, v91
	s_waitcnt lgkmcnt(1)
	v_lshlrev_b32_e32 v164, 16, v2
	s_waitcnt lgkmcnt(0)
	v_lshlrev_b32_e32 v165, 16, v82
	v_mov_b32_e32 v92, v165
	v_pk_mul_f32 v[92:93], v[114:115], v[92:93] op_sel_hi:[0,1]
	v_mov_b32_e32 v2, v91
	v_pk_fma_f32 v[92:93], v[112:113], v[164:165], v[92:93] op_sel_hi:[0,1,1]
	v_pk_fma_f32 v[92:93], v[116:117], v[2:3], v[92:93] op_sel_hi:[0,1,1]
	v_mov_b32_e32 v2, v88
	v_pk_mul_f32 v[2:3], v[210:211], v[2:3]
	v_mov_b32_e32 v82, v117
	v_pk_fma_f32 v[2:3], v[208:209], v[90:91], v[2:3]
	v_mov_b32_e32 v90, v117
	v_mov_b32_e32 v91, v116
	v_pk_fma_f32 v[90:91], v[90:91], v[152:153], v[2:3]
	v_mov_b32_e32 v153, v87
	v_mov_b32_e32 v2, v113
	v_pk_mul_f32 v[152:153], v[98:99], v[152:153] op_sel_hi:[0,1]
	v_pk_fma_f32 v[2:3], v[2:3], v[88:89], v[152:153] op_sel_hi:[0,1,1]
	v_pk_fma_f32 v[88:89], v[82:83], v[166:167], v[2:3] op_sel_hi:[0,1,1]
	v_mov_b32_e32 v152, v138
	v_mov_b32_e32 v153, v115
	v_mov_b32_e32 v166, v84
	v_mov_b32_e32 v2, v140
	v_mov_b32_e32 v3, v113
	v_pk_mul_f32 v[152:153], v[152:153], v[166:167]
	v_mov_b32_e32 v82, v139
	v_pk_fma_f32 v[2:3], v[2:3], v[86:87], v[152:153]
	v_mov_b32_e32 v86, v136
	v_mov_b32_e32 v87, v117
	v_pk_fma_f32 v[86:87], v[86:87], v[168:169], v[2:3]
	v_mov_b32_e32 v2, v85
	v_mov_b32_e32 v3, v81
	v_pk_mul_f32 v[2:3], v[138:139], v[2:3] op_sel_hi:[0,1]
	v_pk_fma_f32 v[2:3], v[140:141], v[84:85], v[2:3] op_sel_hi:[0,1,1]
	v_pk_fma_f32 v[84:85], v[136:137], v[170:171], v[2:3] op_sel_hi:[0,1,1]
	v_mov_b32_e32 v152, v139
	v_mov_b32_e32 v153, v138
	v_mov_b32_e32 v170, v206
	v_mov_b32_e32 v2, v141
	v_mov_b32_e32 v3, v140
	v_pk_mul_f32 v[152:153], v[152:153], v[170:171]
	v_mov_b32_e32 v140, v127
	v_pk_fma_f32 v[2:3], v[2:3], v[80:81], v[152:153]
	v_mov_b32_e32 v80, v137
	v_mov_b32_e32 v81, v136
	v_pk_fma_f32 v[80:81], v[80:81], v[172:173], v[2:3]
	v_mov_b32_e32 v2, v141
	v_pk_mul_f32 v[152:153], v[82:83], v[156:157] op_sel_hi:[0,1]
	v_pk_fma_f32 v[2:3], v[2:3], v[206:207], v[152:153] op_sel_hi:[0,1,1]
	v_mov_b32_e32 v82, v137
	v_pk_fma_f32 v[2:3], v[82:83], v[158:159], v[2:3] op_sel_hi:[0,1,1]
	v_add_f32_e32 v82, v99, v180
	v_mul_f32_e32 v82, 0xbfb8aa3b, v82
	v_exp_f32_e32 v204, v82
	v_mov_b32_e32 v156, v164
	v_pk_add_f32 v[98:99], v[204:205], 1.0 op_sel_hi:[1,0]
	v_rcp_f32_e32 v99, v99
	v_rcp_f32_e32 v98, v98
	v_add_f32_e32 v82, v83, v203
	v_mul_f32_e32 v82, 0xbfb8aa3b, v82
	v_exp_f32_e32 v180, v82
	v_pk_mul_f32 v[98:99], v[98:99], s[6:7] op_sel_hi:[1,0]
	v_pk_add_f32 v[82:83], v[180:181], 1.0 op_sel_hi:[1,0]
	v_rcp_f32_e32 v83, v83
	v_rcp_f32_e32 v82, v82
	s_nop 0
	v_pk_mul_f32 v[152:153], v[82:83], s[6:7] op_sel_hi:[1,0]
	ds_read_u16 v82, v119 offset:4192
	ds_read_u16 v83, v119 offset:3424
	v_mov_b32_e32 v113, v139
	v_mov_b32_e32 v115, v141
	v_mov_b32_e32 v117, v137
	s_waitcnt lgkmcnt(1)
	v_lshlrev_b32_e32 v167, 16, v82
	s_waitcnt lgkmcnt(0)
	v_lshlrev_b32_e32 v166, 16, v83
	v_pk_mov_b32 v[82:83], v[174:175], v[166:167] op_sel:[1,0]
	v_mov_b32_e32 v141, v128
	v_pk_mul_f32 v[82:83], v[176:177], v[82:83] op_sel_hi:[0,1]
	v_pk_fma_f32 v[82:83], v[0:1], v[174:175], v[82:83] op_sel_hi:[0,1,1]
	ds_read_u16 v0, v119 offset:3936
	v_mov_b32_e32 v119, v159
	v_pk_mul_f32 v[112:113], v[112:113], v[118:119]
	v_pk_fma_f32 v[166:167], v[178:179], v[166:167], v[82:83] op_sel_hi:[0,1,1]
	v_pk_fma_f32 v[112:113], v[114:115], v[156:157], v[112:113]
	s_waitcnt lgkmcnt(0)
	v_lshlrev_b32_e32 v83, 16, v0
	v_mov_b32_e32 v82, v165
	v_pk_fma_f32 v[82:83], v[116:117], v[82:83], v[112:113]
	v_mov_b32_e32 v128, v134
	v_mov_b32_e32 v138, v135
	v_mov_b32_e32 v139, v130
	v_mov_b32_e32 v130, v150
	v_mov_b32_e32 v136, v151
	v_mov_b32_e32 v137, v132
	v_mov_b32_e32 v132, v154
	v_mov_b32_e32 v134, v155
	v_mov_b32_e32 v135, v166
	v_mov_b32_e32 v127, v167

.LBB0_1106:
	ds_read2st64_b32 v[28:29], v120 offset1:1
	v_and_b32_e32 v0, 64, v179
	v_add_u32_e32 v0, 64, v0
	v_xor_b32_e32 v26, 1, v179
	v_cmp_lt_i32_e32 vcc, v26, v0
	s_waitcnt lgkmcnt(0)
	v_pk_mul_f32 v[48:49], v[28:29], v[28:29]
	s_lshl_b32 s10, s4, 1
	v_cndmask_b32_e32 v26, v179, v26, vcc
	v_lshlrev_b32_e32 v47, 2, v26
	v_add_f32_e32 v48, v48, v49
	ds_bpermute_b32 v49, v47, v48
	v_xor_b32_e32 v26, 2, v179
	v_cmp_lt_i32_e32 vcc, v26, v0
	v_lshlrev_b64 v[42:43], 11, v[42:43]
	s_waitcnt lgkmcnt(0)
	v_add_f32_e32 v48, v48, v49
	v_cndmask_b32_e32 v26, v179, v26, vcc
	v_lshlrev_b32_e32 v46, 2, v26
	ds_bpermute_b32 v49, v46, v48
	v_xor_b32_e32 v26, 4, v179
	v_cmp_lt_i32_e32 vcc, v26, v0
	s_waitcnt lgkmcnt(0)
	v_add_f32_e32 v48, v48, v49
	v_cndmask_b32_e32 v26, v179, v26, vcc
	v_lshlrev_b32_e32 v45, 2, v26
	ds_bpermute_b32 v49, v45, v48
	v_xor_b32_e32 v26, 8, v179
	v_cmp_lt_i32_e32 vcc, v26, v0
	s_waitcnt lgkmcnt(0)
	v_add_f32_e32 v48, v48, v49
	v_cndmask_b32_e32 v26, v179, v26, vcc
	v_lshlrev_b32_e32 v44, 2, v26
	ds_bpermute_b32 v49, v44, v48
	v_xor_b32_e32 v26, 16, v179
	v_cmp_lt_i32_e32 vcc, v26, v0
	s_waitcnt lgkmcnt(0)
	v_add_f32_e32 v48, v48, v49
	v_cndmask_b32_e32 v26, v179, v26, vcc
	v_lshlrev_b32_e32 v41, 2, v26
	ds_bpermute_b32 v49, v41, v48
	v_xor_b32_e32 v26, 32, v179
	v_cmp_lt_i32_e32 vcc, v26, v0
	s_waitcnt lgkmcnt(0)
	v_add_f32_e32 v48, v48, v49
	v_cndmask_b32_e32 v0, v179, v26, vcc
	v_lshlrev_b32_e32 v0, 2, v0
	ds_bpermute_b32 v49, v0, v48
	v_lshl_add_u64 v[26:27], v[36:37], 0, s[10:11]
	v_lshl_add_u64 v[42:43], v[26:27], 0, v[42:43]
	s_waitcnt lgkmcnt(0)
	v_add_f32_e32 v48, v48, v49
	v_fmamk_f32 v48, v48, 0x3c000000, v184
	v_cmp_gt_f32_e32 vcc, s29, v48
	v_mul_f32_e32 v49, 0x4b800000, v48
	s_nop 0
	v_cndmask_b32_e32 v48, v48, v49, vcc
	v_rsq_f32_e32 v48, v48
	s_nop 0
	v_mul_f32_e32 v49, 0x45800000, v48
	v_cndmask_b32_e32 v48, v48, v49, vcc
	s_waitcnt vmcnt(15)
	v_lshlrev_b32_e32 v49, 16, v150
	v_mul_f32_e32 v50, 0xbfb8aa3b, v49
	v_exp_f32_e32 v50, v50
	v_mul_f32_e32 v28, v28, v48
	v_mul_f32_e32 v28, v137, v28
	v_add_f32_e32 v50, 1.0, v50
	v_rcp_f32_e32 v50, v50
	s_nop 0
	v_mul_f32_e32 v49, v50, v49
	v_mul_f32_e32 v28, v49, v28
	v_cvt_pk_bf16_f32 v28, v28, v28
	global_store_short v[42:43], v28, off
	v_mul_f32_e32 v28, v29, v48
	s_waitcnt vmcnt(15)
	v_lshlrev_b32_e32 v29, 16, v151
	v_mul_f32_e32 v48, 0xbfb8aa3b, v29
	v_exp_f32_e32 v48, v48
	v_mul_f32_e32 v28, v159, v28
	v_add_f32_e32 v48, 1.0, v48
	v_rcp_f32_e32 v48, v48
	s_nop 0
	v_mul_f32_e32 v29, v48, v29
	v_mul_f32_e32 v28, v29, v28
	v_cvt_pk_bf16_f32 v28, v28, v28
	global_store_short v[42:43], v28, off offset:128
	ds_read2st64_b32 v[42:43], v122 offset1:1
	v_add_u32_e32 v28, s93, v121
	s_waitcnt lgkmcnt(0)
	v_pk_mul_f32 v[48:49], v[42:43], v[42:43]
	v_add_f32_e32 v29, v48, v49
	ds_bpermute_b32 v48, v47, v29
	s_waitcnt lgkmcnt(0)
	v_add_f32_e32 v29, v29, v48
	ds_bpermute_b32 v48, v46, v29
	s_waitcnt lgkmcnt(0)
	v_add_f32_e32 v29, v29, v48
	ds_bpermute_b32 v48, v45, v29
	s_waitcnt lgkmcnt(0)
	v_add_f32_e32 v29, v29, v48
	ds_bpermute_b32 v48, v44, v29
	s_waitcnt lgkmcnt(0)
	v_add_f32_e32 v29, v29, v48
	ds_bpermute_b32 v48, v41, v29
	s_waitcnt lgkmcnt(0)
	v_add_f32_e32 v29, v29, v48
	ds_bpermute_b32 v48, v0, v29
	s_waitcnt lgkmcnt(0)
	v_add_f32_e32 v29, v29, v48
	v_fmamk_f32 v29, v29, 0x3c000000, v184
	v_cmp_gt_f32_e32 vcc, s29, v29
	v_mul_f32_e32 v48, 0x4b800000, v29
	s_nop 0
	v_cndmask_b32_e32 v29, v29, v48, vcc
	v_rsq_f32_e32 v29, v29
	s_nop 0
	v_mul_f32_e32 v48, 0x45800000, v29
	v_cndmask_b32_e32 v48, v29, v48, vcc
	v_mul_f32_e32 v29, v42, v48
	s_waitcnt vmcnt(15)
	v_lshlrev_b32_e32 v42, 16, v152
	v_mul_f32_e32 v49, 0xbfb8aa3b, v42
	v_exp_f32_e32 v49, v49
	v_mul_f32_e32 v29, v137, v29
	v_add_f32_e32 v49, 1.0, v49
	v_rcp_f32_e32 v49, v49
	s_nop 0
	v_mul_f32_e32 v42, v49, v42
	v_mul_f32_e32 v29, v42, v29
	v_cvt_pk_bf16_f32 v42, v29, v29
	v_ashrrev_i32_e32 v29, 31, v28
	v_lshlrev_b64 v[28:29], 11, v[28:29]
	v_lshl_add_u64 v[28:29], v[26:27], 0, v[28:29]
	global_store_short v[28:29], v42, off
	v_mul_f32_e32 v42, v43, v48
	s_waitcnt vmcnt(15)
	v_lshlrev_b32_e32 v43, 16, v153
	v_mul_f32_e32 v48, 0xbfb8aa3b, v43
	v_exp_f32_e32 v48, v48
	v_mul_f32_e32 v42, v159, v42
	v_add_f32_e32 v48, 1.0, v48
	v_rcp_f32_e32 v48, v48
	s_nop 0
	v_mul_f32_e32 v43, v48, v43
	v_mul_f32_e32 v42, v43, v42
	v_cvt_pk_bf16_f32 v42, v42, v42
	global_store_short v[28:29], v42, off offset:128
	ds_read2st64_b32 v[42:43], v126 offset1:1
	v_add_u32_e32 v28, s93, v123
	s_waitcnt lgkmcnt(0)
	v_pk_mul_f32 v[48:49], v[42:43], v[42:43]
	v_add_f32_e32 v29, v48, v49
	ds_bpermute_b32 v48, v47, v29
	s_waitcnt lgkmcnt(0)
	v_add_f32_e32 v29, v29, v48
	ds_bpermute_b32 v48, v46, v29
	s_waitcnt lgkmcnt(0)
	v_add_f32_e32 v29, v29, v48
	ds_bpermute_b32 v48, v45, v29
	s_waitcnt lgkmcnt(0)
	v_add_f32_e32 v29, v29, v48
	ds_bpermute_b32 v48, v44, v29
	s_waitcnt lgkmcnt(0)
	v_add_f32_e32 v29, v29, v48
	ds_bpermute_b32 v48, v41, v29
	s_waitcnt lgkmcnt(0)
	v_add_f32_e32 v29, v29, v48
	ds_bpermute_b32 v48, v0, v29
	s_waitcnt lgkmcnt(0)
	v_add_f32_e32 v29, v29, v48
	v_fmamk_f32 v29, v29, 0x3c000000, v184
	v_cmp_gt_f32_e32 vcc, s29, v29
	v_mul_f32_e32 v48, 0x4b800000, v29
	s_nop 0
	v_cndmask_b32_e32 v29, v29, v48, vcc
	v_rsq_f32_e32 v29, v29
	s_nop 0
	v_mul_f32_e32 v48, 0x45800000, v29
	v_cndmask_b32_e32 v48, v29, v48, vcc
	v_mul_f32_e32 v29, v42, v48
	s_waitcnt vmcnt(15)
	v_lshlrev_b32_e32 v42, 16, v154
	v_mul_f32_e32 v49, 0xbfb8aa3b, v42
	v_exp_f32_e32 v49, v49
	v_mul_f32_e32 v29, v137, v29
	v_add_f32_e32 v49, 1.0, v49
	v_rcp_f32_e32 v49, v49
	s_nop 0
	v_mul_f32_e32 v42, v49, v42
	v_mul_f32_e32 v29, v42, v29
	v_cvt_pk_bf16_f32 v42, v29, v29
	v_ashrrev_i32_e32 v29, 31, v28
	v_lshlrev_b64 v[28:29], 11, v[28:29]
	v_lshl_add_u64 v[28:29], v[26:27], 0, v[28:29]
	global_store_short v[28:29], v42, off
	v_mul_f32_e32 v42, v43, v48
	s_waitcnt vmcnt(15)
	v_lshlrev_b32_e32 v43, 16, v155
	v_mul_f32_e32 v48, 0xbfb8aa3b, v43
	v_exp_f32_e32 v48, v48
	v_mul_f32_e32 v42, v159, v42
	v_add_f32_e32 v48, 1.0, v48
	v_rcp_f32_e32 v48, v48
	s_nop 0
	v_mul_f32_e32 v43, v48, v43
	v_mul_f32_e32 v42, v43, v42
	v_cvt_pk_bf16_f32 v42, v42, v42
	global_store_short v[28:29], v42, off offset:128
	ds_read2st64_b32 v[42:43], v128 offset1:1
	v_add_u32_e32 v28, s93, v127
	s_waitcnt lgkmcnt(0)
	v_pk_mul_f32 v[48:49], v[42:43], v[42:43]
	v_add_f32_e32 v29, v48, v49
	ds_bpermute_b32 v48, v47, v29
	s_waitcnt lgkmcnt(0)
	v_add_f32_e32 v29, v29, v48
	ds_bpermute_b32 v48, v46, v29
	s_waitcnt lgkmcnt(0)
	v_add_f32_e32 v29, v29, v48
	ds_bpermute_b32 v48, v45, v29
	s_waitcnt lgkmcnt(0)
	v_add_f32_e32 v29, v29, v48
	ds_bpermute_b32 v48, v44, v29
	s_waitcnt lgkmcnt(0)
	v_add_f32_e32 v29, v29, v48
	ds_bpermute_b32 v48, v41, v29
	s_waitcnt lgkmcnt(0)
	v_add_f32_e32 v29, v29, v48
	ds_bpermute_b32 v48, v0, v29
	s_waitcnt lgkmcnt(0)
	v_add_f32_e32 v29, v29, v48
	v_fmamk_f32 v29, v29, 0x3c000000, v184
	v_cmp_gt_f32_e32 vcc, s29, v29
	v_mul_f32_e32 v48, 0x4b800000, v29
	s_nop 0
	v_cndmask_b32_e32 v29, v29, v48, vcc
	v_rsq_f32_e32 v29, v29
	s_nop 0
	v_mul_f32_e32 v48, 0x45800000, v29
	v_cndmask_b32_e32 v48, v29, v48, vcc
	v_mul_f32_e32 v29, v42, v48
	s_waitcnt vmcnt(15)
	v_lshlrev_b32_e32 v42, 16, v156
	v_mul_f32_e32 v49, 0xbfb8aa3b, v42
	v_exp_f32_e32 v49, v49
	v_mul_f32_e32 v29, v137, v29
	v_add_f32_e32 v49, 1.0, v49
	v_rcp_f32_e32 v49, v49
	s_nop 0
	v_mul_f32_e32 v42, v49, v42
	v_mul_f32_e32 v29, v42, v29
	v_cvt_pk_bf16_f32 v42, v29, v29
	v_ashrrev_i32_e32 v29, 31, v28
	v_lshlrev_b64 v[28:29], 11, v[28:29]
	v_lshl_add_u64 v[28:29], v[26:27], 0, v[28:29]
	global_store_short v[28:29], v42, off
	v_mul_f32_e32 v42, v43, v48
	s_waitcnt vmcnt(15)
	v_lshlrev_b32_e32 v43, 16, v157
	v_mul_f32_e32 v48, 0xbfb8aa3b, v43
	v_exp_f32_e32 v48, v48
	v_mul_f32_e32 v42, v159, v42
	v_add_f32_e32 v48, 1.0, v48
	v_rcp_f32_e32 v48, v48
	s_nop 0
	v_mul_f32_e32 v43, v48, v43
	v_mul_f32_e32 v42, v43, v42
	v_cvt_pk_bf16_f32 v42, v42, v42
	global_store_short v[28:29], v42, off offset:128
	ds_read2st64_b32 v[42:43], v130 offset1:1
	v_add_u32_e32 v28, s93, v129
	s_waitcnt lgkmcnt(0)
	v_pk_mul_f32 v[48:49], v[42:43], v[42:43]
	v_add_f32_e32 v29, v48, v49
	ds_bpermute_b32 v48, v47, v29
	s_waitcnt lgkmcnt(0)
	v_add_f32_e32 v29, v29, v48
	ds_bpermute_b32 v48, v46, v29
	s_waitcnt lgkmcnt(0)
	v_add_f32_e32 v29, v29, v48
	ds_bpermute_b32 v48, v45, v29
	s_waitcnt lgkmcnt(0)
	v_add_f32_e32 v29, v29, v48
	ds_bpermute_b32 v48, v44, v29
	s_waitcnt lgkmcnt(0)
	v_add_f32_e32 v29, v29, v48
	ds_bpermute_b32 v48, v41, v29
	s_waitcnt lgkmcnt(0)
	v_add_f32_e32 v29, v29, v48
	ds_bpermute_b32 v48, v0, v29
	s_waitcnt lgkmcnt(0)
	v_add_f32_e32 v29, v29, v48
	v_fmamk_f32 v29, v29, 0x3c000000, v184
	v_cmp_gt_f32_e32 vcc, s29, v29
	v_mul_f32_e32 v48, 0x4b800000, v29
	s_nop 0
	v_cndmask_b32_e32 v29, v29, v48, vcc
	v_rsq_f32_e32 v29, v29
	s_nop 0
	v_mul_f32_e32 v48, 0x45800000, v29
	v_cndmask_b32_e32 v48, v29, v48, vcc
	v_mul_f32_e32 v29, v42, v48
	s_waitcnt vmcnt(15)
	v_lshlrev_b32_e32 v42, 16, v158
	v_mul_f32_e32 v49, 0xbfb8aa3b, v42
	v_exp_f32_e32 v49, v49
	v_mul_f32_e32 v29, v137, v29
	v_add_f32_e32 v49, 1.0, v49
	v_rcp_f32_e32 v49, v49
	s_nop 0
	v_mul_f32_e32 v42, v49, v42
	v_mul_f32_e32 v29, v42, v29
	v_cvt_pk_bf16_f32 v42, v29, v29
	v_ashrrev_i32_e32 v29, 31, v28
	v_lshlrev_b64 v[28:29], 11, v[28:29]
	v_lshl_add_u64 v[28:29], v[26:27], 0, v[28:29]
	global_store_short v[28:29], v42, off
	v_mul_f32_e32 v42, v43, v48
	s_waitcnt vmcnt(15)
	v_lshlrev_b32_e32 v43, 16, v164
	v_mul_f32_e32 v48, 0xbfb8aa3b, v43
	v_exp_f32_e32 v48, v48
	v_mul_f32_e32 v42, v159, v42
	v_add_f32_e32 v48, 1.0, v48
	v_rcp_f32_e32 v48, v48
	s_nop 0
	v_mul_f32_e32 v43, v48, v43
	v_mul_f32_e32 v42, v43, v42
	v_cvt_pk_bf16_f32 v42, v42, v42
	global_store_short v[28:29], v42, off offset:128
	ds_read2st64_b32 v[42:43], v132 offset1:1
	v_add_u32_e32 v28, s93, v131
	s_waitcnt lgkmcnt(0)
	v_pk_mul_f32 v[48:49], v[42:43], v[42:43]
	v_add_f32_e32 v29, v48, v49
	ds_bpermute_b32 v48, v47, v29
	s_waitcnt lgkmcnt(0)
	v_add_f32_e32 v29, v29, v48
	ds_bpermute_b32 v48, v46, v29
	s_waitcnt lgkmcnt(0)
	v_add_f32_e32 v29, v29, v48
	ds_bpermute_b32 v48, v45, v29
	s_waitcnt lgkmcnt(0)
	v_add_f32_e32 v29, v29, v48
	ds_bpermute_b32 v48, v44, v29
	s_waitcnt lgkmcnt(0)
	v_add_f32_e32 v29, v29, v48
	ds_bpermute_b32 v48, v41, v29
	s_waitcnt lgkmcnt(0)
	v_add_f32_e32 v29, v29, v48
	ds_bpermute_b32 v48, v0, v29
	s_waitcnt lgkmcnt(0)
	v_add_f32_e32 v29, v29, v48
	v_fmamk_f32 v29, v29, 0x3c000000, v184
	v_cmp_gt_f32_e32 vcc, s29, v29
	v_mul_f32_e32 v48, 0x4b800000, v29
	s_nop 0
	v_cndmask_b32_e32 v29, v29, v48, vcc
	v_rsq_f32_e32 v29, v29
	s_nop 0
	v_mul_f32_e32 v48, 0x45800000, v29
	v_cndmask_b32_e32 v48, v29, v48, vcc
	v_mul_f32_e32 v29, v42, v48
	s_waitcnt vmcnt(15)
	v_lshlrev_b32_e32 v42, 16, v165
	v_mul_f32_e32 v49, 0xbfb8aa3b, v42
	v_exp_f32_e32 v49, v49
	v_mul_f32_e32 v29, v137, v29
	v_add_f32_e32 v49, 1.0, v49
	v_rcp_f32_e32 v49, v49
	s_nop 0
	v_mul_f32_e32 v42, v49, v42
	v_mul_f32_e32 v29, v42, v29
	v_cvt_pk_bf16_f32 v42, v29, v29
	v_ashrrev_i32_e32 v29, 31, v28
	v_lshlrev_b64 v[28:29], 11, v[28:29]
	v_lshl_add_u64 v[28:29], v[26:27], 0, v[28:29]
	global_store_short v[28:29], v42, off
	v_mul_f32_e32 v42, v43, v48
	s_waitcnt vmcnt(15)
	v_lshlrev_b32_e32 v43, 16, v166
	v_mul_f32_e32 v48, 0xbfb8aa3b, v43
	v_exp_f32_e32 v48, v48
	v_mul_f32_e32 v42, v159, v42
	v_add_f32_e32 v48, 1.0, v48
	v_rcp_f32_e32 v48, v48
	s_nop 0
	v_mul_f32_e32 v43, v48, v43
	v_mul_f32_e32 v42, v43, v42
	v_cvt_pk_bf16_f32 v42, v42, v42
	global_store_short v[28:29], v42, off offset:128
	ds_read2st64_b32 v[42:43], v134 offset1:1
	v_add_u32_e32 v28, s93, v133
	s_waitcnt lgkmcnt(0)
	v_pk_mul_f32 v[48:49], v[42:43], v[42:43]
	v_add_f32_e32 v29, v48, v49
	ds_bpermute_b32 v48, v47, v29
	s_waitcnt lgkmcnt(0)
	v_add_f32_e32 v29, v29, v48
	ds_bpermute_b32 v48, v46, v29
	s_waitcnt lgkmcnt(0)
	v_add_f32_e32 v29, v29, v48
	ds_bpermute_b32 v48, v45, v29
	s_waitcnt lgkmcnt(0)
	v_add_f32_e32 v29, v29, v48
	ds_bpermute_b32 v48, v44, v29
	s_waitcnt lgkmcnt(0)
	v_add_f32_e32 v29, v29, v48
	ds_bpermute_b32 v48, v41, v29
	s_waitcnt lgkmcnt(0)
	v_add_f32_e32 v29, v29, v48
	ds_bpermute_b32 v48, v0, v29
	s_waitcnt lgkmcnt(0)
	v_add_f32_e32 v29, v29, v48
	v_fmamk_f32 v29, v29, 0x3c000000, v184
	v_cmp_gt_f32_e32 vcc, s29, v29
	v_mul_f32_e32 v48, 0x4b800000, v29
	s_nop 0
	v_cndmask_b32_e32 v29, v29, v48, vcc
	v_rsq_f32_e32 v29, v29
	s_nop 0
	v_mul_f32_e32 v48, 0x45800000, v29
	v_cndmask_b32_e32 v48, v29, v48, vcc
	v_mul_f32_e32 v29, v42, v48
	s_waitcnt vmcnt(15)
	v_lshlrev_b32_e32 v42, 16, v167
	v_mul_f32_e32 v49, 0xbfb8aa3b, v42
	v_exp_f32_e32 v49, v49
	v_mul_f32_e32 v29, v137, v29
	v_add_f32_e32 v49, 1.0, v49
	v_rcp_f32_e32 v49, v49
	s_nop 0
	v_mul_f32_e32 v42, v49, v42
	v_mul_f32_e32 v29, v42, v29
	v_cvt_pk_bf16_f32 v42, v29, v29
	v_ashrrev_i32_e32 v29, 31, v28
	v_lshlrev_b64 v[28:29], 11, v[28:29]
	v_lshl_add_u64 v[28:29], v[26:27], 0, v[28:29]
	global_store_short v[28:29], v42, off
	v_mul_f32_e32 v42, v43, v48
	s_waitcnt vmcnt(15)
	v_lshlrev_b32_e32 v43, 16, v168
	v_mul_f32_e32 v48, 0xbfb8aa3b, v43
	v_exp_f32_e32 v48, v48
	v_mul_f32_e32 v42, v159, v42
	v_add_f32_e32 v48, 1.0, v48
	v_rcp_f32_e32 v48, v48
	s_nop 0
	v_mul_f32_e32 v43, v48, v43
	v_mul_f32_e32 v42, v43, v42
	v_cvt_pk_bf16_f32 v42, v42, v42
	global_store_short v[28:29], v42, off offset:128
	ds_read2st64_b32 v[42:43], v136 offset1:1
	v_add_u32_e32 v28, s93, v135
	s_waitcnt lgkmcnt(0)
	v_pk_mul_f32 v[48:49], v[42:43], v[42:43]
	v_add_f32_e32 v29, v48, v49
	ds_bpermute_b32 v47, v47, v29
	s_waitcnt lgkmcnt(0)
	v_add_f32_e32 v29, v29, v47
	ds_bpermute_b32 v46, v46, v29
	s_waitcnt lgkmcnt(0)
	v_add_f32_e32 v29, v29, v46
	ds_bpermute_b32 v45, v45, v29
	s_waitcnt lgkmcnt(0)
	v_add_f32_e32 v29, v29, v45
	ds_bpermute_b32 v44, v44, v29
	s_waitcnt lgkmcnt(0)
	v_add_f32_e32 v29, v29, v44
	ds_bpermute_b32 v41, v41, v29
	s_waitcnt lgkmcnt(0)
	v_add_f32_e32 v29, v29, v41
	ds_bpermute_b32 v0, v0, v29
	s_waitcnt vmcnt(15)
	v_lshlrev_b32_e32 v41, 16, v169
	s_waitcnt lgkmcnt(0)
	v_add_f32_e32 v0, v29, v0
	v_fmamk_f32 v0, v0, 0x3c000000, v184
	v_cmp_gt_f32_e32 vcc, s29, v0
	v_mul_f32_e32 v29, 0x4b800000, v0
	s_nop 0
	v_cndmask_b32_e32 v0, v0, v29, vcc
	v_rsq_f32_e32 v0, v0
	s_nop 0
	v_mul_f32_e32 v29, 0x45800000, v0
	v_cndmask_b32_e32 v0, v0, v29, vcc
	v_mul_f32_e32 v29, v42, v0
	v_mul_f32_e32 v42, 0xbfb8aa3b, v41
	v_exp_f32_e32 v42, v42
	v_mul_f32_e32 v29, v137, v29
	v_mul_f32_e32 v0, v43, v0
	v_mul_f32_e32 v0, v159, v0
	v_add_f32_e32 v42, 1.0, v42
	v_rcp_f32_e32 v42, v42
	s_nop 0
	v_mul_f32_e32 v41, v42, v41
	v_mul_f32_e32 v29, v41, v29
	v_cvt_pk_bf16_f32 v41, v29, v29
	v_ashrrev_i32_e32 v29, 31, v28
	v_lshlrev_b64 v[28:29], 11, v[28:29]
	v_lshl_add_u64 v[26:27], v[26:27], 0, v[28:29]
	s_waitcnt vmcnt(14)
	v_lshlrev_b32_e32 v28, 16, v170
	v_mul_f32_e32 v29, 0xbfb8aa3b, v28
	v_exp_f32_e32 v29, v29
	global_store_short v[26:27], v41, off
	v_add_f32_e32 v29, 1.0, v29
	v_readlane_b32 s0, v252, 0
	v_readlane_b32 s1, v252, 1
	v_rcp_f32_e32 v29, v29
	s_nop 0
	v_mul_f32_e32 v28, v29, v28
	v_mul_f32_e32 v0, v28, v0
	v_cvt_pk_bf16_f32 v0, v0, v0
	global_store_short v[26:27], v0, off offset:128
	s_waitcnt lgkmcnt(0)
	s_barrier
	s_load_dword s0, s[0:1], 0x10
	s_waitcnt lgkmcnt(0)
	s_lshr_b32 s0, s0, 16
	s_cmp_lg_u32 s0, 0
	s_cselect_b64 s[0:1], -1, 0
	s_cmp_lg_u64 s[0:1], 0
	s_addc_u32 s94, s92, 0
	s_cmpk_gt_i32 s94, 0x1ff
	s_cbranch_scc1 .LBB0_1190

.LBB0_1109:
	s_waitcnt vmcnt(6)
	ds_write_b128 v138, v[2:5]
	s_waitcnt vmcnt(5)
	ds_write_b128 v139, v[6:9]
	s_waitcnt vmcnt(4)
	ds_write_b128 v140, v[10:13]
	s_waitcnt vmcnt(3)
	ds_write_b128 v141, v[14:17]
	s_waitcnt vmcnt(2)
	ds_write_b128 v142, v[18:21]
	s_waitcnt vmcnt(1)
	ds_write_b128 v143, v[22:25]
	v_cndmask_b32_e64 v0, v69, v68, s[86:87]
	s_waitcnt lgkmcnt(0)
	s_barrier
	v_mad_u64_u32 v[172:173], s[0:1], v0, s13, v[32:33]
	ds_read_u16 v0, v172 offset:256
	s_waitcnt vmcnt(0)
	v_sub_f32_e32 v178, 1.0, v64
	s_waitcnt lgkmcnt(0)
	v_lshlrev_b32_e32 v0, 16, v0
	v_mul_f32_e32 v0, 0xbfb8aa3b, v0
	v_exp_f32_e32 v0, v0
	s_nop 0
	v_add_f32_e32 v0, 1.0, v0
	v_rcp_f32_e32 v0, v0
	s_nop 0
	v_fma_f32 v26, v178, v0, v64
	v_cndmask_b32_e64 v29, v71, v70, s[86:87]
	v_log_f32_e32 v0, v26
	s_nop 1
	v_mul_f32_e32 v0, 0x3f317217, v0
	ds_read_u16 v28, v172
	ds_read_u16 v27, v172 offset:512
	v_mad_u64_u32 v[172:173], s[0:1], v29, s13, v[32:33]
	ds_read_u16 v29, v172 offset:256
	s_waitcnt lgkmcnt(0)
	v_lshlrev_b32_e32 v29, 16, v29
	v_mul_f32_e32 v29, 0xbfb8aa3b, v29
	v_exp_f32_e32 v29, v29
	s_nop 0
	v_add_f32_e32 v29, 1.0, v29
	v_rcp_f32_e32 v29, v29
	s_nop 0
	v_fma_f32 v41, v178, v29, v64
	v_log_f32_e32 v29, v41
	s_nop 1
	v_mul_f32_e32 v175, 0x3f317217, v29
	ds_read_u16 v171, v172
	ds_read_u16 v29, v172 offset:512
	v_cndmask_b32_e64 v172, v73, v72, s[86:87]
	v_mad_u64_u32 v[180:181], s[0:1], v172, s13, v[32:33]
	ds_read_u16 v172, v180 offset:256
	v_add_f32_e32 v239, v0, v175
	s_waitcnt lgkmcnt(0)
	v_lshlrev_b32_e32 v172, 16, v172
	v_mul_f32_e32 v172, 0xbfb8aa3b, v172
	v_exp_f32_e32 v172, v172
	s_nop 0
	v_add_f32_e32 v172, 1.0, v172
	v_rcp_f32_e32 v172, v172
	s_nop 0
	v_fma_f32 v172, v178, v172, v64
	v_log_f32_e32 v173, v172
	s_nop 1
	v_mul_f32_e32 v176, 0x3f317217, v173
	ds_read_u16 v174, v180
	ds_read_u16 v173, v180 offset:512
	v_cndmask_b32_e64 v180, v75, v74, s[86:87]
	v_mad_u64_u32 v[180:181], s[0:1], v180, s13, v[32:33]
	ds_read_u16 v181, v180 offset:256
	v_add_f32_e32 v238, v239, v176
	v_mov_b32_e32 v176, 0
	s_waitcnt lgkmcnt(0)
	v_lshlrev_b32_e32 v181, 16, v181
	v_mul_f32_e32 v181, 0xbfb8aa3b, v181
	v_exp_f32_e32 v181, v181
	s_nop 0
	v_add_f32_e32 v181, 1.0, v181
	v_rcp_f32_e32 v181, v181
	s_nop 0
	v_fma_f32 v181, v178, v181, v64
	v_log_f32_e32 v188, v181
	s_nop 1
	v_mul_f32_e32 v195, 0x3f317217, v188
	v_cndmask_b32_e64 v189, v77, v76, s[86:87]
	v_mad_u64_u32 v[192:193], s[0:1], v189, s13, v[32:33]
	ds_read_u16 v188, v180
	ds_read_u16 v180, v180 offset:512
	ds_read_u16 v189, v192 offset:256
	v_add_f32_e32 v237, v238, v195
	s_waitcnt lgkmcnt(0)
	v_lshlrev_b32_e32 v189, 16, v189
	v_mul_f32_e32 v189, 0xbfb8aa3b, v189
	v_exp_f32_e32 v189, v189
	s_nop 0
	v_add_f32_e32 v189, 1.0, v189
	v_rcp_f32_e32 v189, v189
	s_nop 0
	v_fma_f32 v190, v178, v189, v64
	v_log_f32_e32 v189, v190
	s_nop 1
	v_mul_f32_e32 v199, 0x3f317217, v189
	ds_read_u16 v191, v192
	ds_read_u16 v189, v192 offset:512
	v_cndmask_b32_e64 v192, v79, v78, s[86:87]
	v_mad_u64_u32 v[196:197], s[0:1], v192, s13, v[32:33]
	ds_read_u16 v192, v196 offset:256
	s_waitcnt lgkmcnt(0)
	v_lshlrev_b32_e32 v192, 16, v192
	v_mul_f32_e32 v192, 0xbfb8aa3b, v192
	v_exp_f32_e32 v192, v192
	s_nop 0
	v_add_f32_e32 v192, 1.0, v192
	v_rcp_f32_e32 v192, v192
	s_nop 0
	v_fma_f32 v192, v178, v192, v64
	v_log_f32_e32 v193, v192
	s_nop 1
	v_mul_f32_e32 v203, 0x3f317217, v193
	ds_read_u16 v194, v196
	ds_read_u16 v193, v196 offset:512
	v_cndmask_b32_e64 v196, v81, v80, s[86:87]
	v_mad_u64_u32 v[196:197], s[0:1], v196, s13, v[32:33]
	ds_read_u16 v197, v196 offset:256
	s_waitcnt lgkmcnt(0)
	v_lshlrev_b32_e32 v197, 16, v197
	v_mul_f32_e32 v197, 0xbfb8aa3b, v197
	v_exp_f32_e32 v197, v197
	s_nop 0
	v_add_f32_e32 v197, 1.0, v197
	v_rcp_f32_e32 v197, v197
	s_nop 0
	v_fma_f32 v197, v178, v197, v64
	v_log_f32_e32 v198, v197
	s_nop 1
	v_mul_f32_e32 v208, 0x3f317217, v198
	v_cndmask_b32_e64 v200, v83, v82, s[86:87]
	v_mad_u64_u32 v[204:205], s[0:1], v200, s13, v[32:33]
	ds_read_u16 v198, v196
	ds_read_u16 v196, v196 offset:512
	ds_read_u16 v200, v204 offset:256
	s_waitcnt lgkmcnt(0)
	v_lshlrev_b32_e32 v200, 16, v200
	v_mul_f32_e32 v200, 0xbfb8aa3b, v200
	v_exp_f32_e32 v200, v200
	s_nop 0
	v_add_f32_e32 v200, 1.0, v200
	v_rcp_f32_e32 v200, v200
	s_nop 0
	v_fma_f32 v200, v178, v200, v64
	v_log_f32_e32 v201, v200
	s_nop 1
	v_mul_f32_e32 v213, 0x3f317217, v201
	ds_read_u16 v201, v204
	ds_read_u16 v202, v204 offset:512
	v_cndmask_b32_e64 v204, v85, v84, s[86:87]
	v_mad_u64_u32 v[204:205], s[0:1], v204, s13, v[32:33]
	ds_read_u16 v205, v204 offset:256
	s_waitcnt lgkmcnt(0)
	v_lshlrev_b32_e32 v205, 16, v205
	v_mul_f32_e32 v205, 0xbfb8aa3b, v205
	v_exp_f32_e32 v205, v205
	s_nop 0
	v_add_f32_e32 v205, 1.0, v205
	v_rcp_f32_e32 v205, v205
	s_nop 0
	v_fma_f32 v205, v178, v205, v64
	v_log_f32_e32 v206, v205
	s_nop 1
	v_mul_f32_e32 v221, 0x3f317217, v206
	v_cndmask_b32_e64 v207, v87, v86, s[86:87]
	v_mad_u64_u32 v[214:215], s[0:1], v207, s13, v[32:33]
	ds_read_u16 v206, v204
	ds_read_u16 v204, v204 offset:512
	ds_read_u16 v207, v214 offset:256
	s_waitcnt lgkmcnt(0)
	v_lshlrev_b32_e32 v207, 16, v207
	v_mul_f32_e32 v207, 0xbfb8aa3b, v207
	v_exp_f32_e32 v207, v207
	s_nop 0
	v_add_f32_e32 v207, 1.0, v207
	v_rcp_f32_e32 v207, v207
	s_nop 0
	v_fma_f32 v209, v178, v207, v64
	v_cndmask_b32_e64 v211, v89, v88, s[86:87]
	v_log_f32_e32 v207, v209
	v_mad_u64_u32 v[216:217], s[0:1], v211, s13, v[32:33]
	v_mul_f32_e32 v225, 0x3f317217, v207
	ds_read_u16 v210, v214
	ds_read_u16 v207, v214 offset:512
	ds_read_u16 v211, v216 offset:256
	s_waitcnt lgkmcnt(0)
	v_lshlrev_b32_e32 v211, 16, v211
	v_mul_f32_e32 v211, 0xbfb8aa3b, v211
	v_exp_f32_e32 v211, v211
	s_nop 0
	v_add_f32_e32 v211, 1.0, v211
	v_rcp_f32_e32 v211, v211
	s_nop 0
	v_fma_f32 v211, v178, v211, v64
	v_cndmask_b32_e64 v215, v91, v90, s[86:87]
	v_log_f32_e32 v212, v211
	v_mad_u64_u32 v[218:219], s[0:1], v215, s13, v[32:33]
	v_mul_f32_e32 v227, 0x3f317217, v212
	ds_read_u16 v214, v216
	ds_read_u16 v212, v216 offset:512
	ds_read_u16 v215, v218 offset:256
	s_waitcnt lgkmcnt(0)
	v_lshlrev_b32_e32 v215, 16, v215
	v_mul_f32_e32 v215, 0xbfb8aa3b, v215
	v_exp_f32_e32 v215, v215
	s_nop 0
	v_add_f32_e32 v215, 1.0, v215
	v_rcp_f32_e32 v215, v215
	s_nop 0
	v_fma_f32 v216, v178, v215, v64
	v_log_f32_e32 v215, v216
	s_nop 1
	v_mul_f32_e32 v240, 0x3f317217, v215
	ds_read_u16 v217, v218
	ds_read_u16 v215, v218 offset:512
	v_cndmask_b32_e64 v218, v93, v92, s[86:87]
	v_mad_u64_u32 v[218:219], s[0:1], v218, s13, v[32:33]
	ds_read_u16 v219, v218 offset:256
	s_waitcnt lgkmcnt(0)
	v_lshlrev_b32_e32 v219, 16, v219
	v_mul_f32_e32 v219, 0xbfb8aa3b, v219
	v_exp_f32_e32 v219, v219
	s_nop 0
	v_add_f32_e32 v219, 1.0, v219
	v_rcp_f32_e32 v219, v219
	s_nop 0
	v_fma_f32 v219, v178, v219, v64
	v_log_f32_e32 v220, v219
	s_nop 1
	v_mul_f32_e32 v241, 0x3f317217, v220
	v_cndmask_b32_e64 v222, v95, v94, s[86:87]
	v_mad_u64_u32 v[228:229], s[0:1], v222, s13, v[32:33]
	ds_read_u16 v220, v218
	ds_read_u16 v218, v218 offset:512
	ds_read_u16 v222, v228 offset:256
	s_waitcnt lgkmcnt(0)
	v_lshlrev_b32_e32 v222, 16, v222
	v_mul_f32_e32 v222, 0xbfb8aa3b, v222
	v_exp_f32_e32 v222, v222
	s_nop 0
	v_add_f32_e32 v222, 1.0, v222
	v_rcp_f32_e32 v222, v222
	s_nop 0
	v_fma_f32 v222, v178, v222, v64
	v_cndmask_b32_e64 v226, v97, v96, s[86:87]
	v_log_f32_e32 v223, v222
	v_mad_u64_u32 v[232:233], s[0:1], v226, s13, v[32:33]
	v_mul_f32_e32 v242, 0x3f317217, v223
	ds_read_u16 v224, v228
	ds_read_u16 v223, v228 offset:512
	ds_read_u16 v226, v232 offset:256
	s_waitcnt lgkmcnt(0)
	v_lshlrev_b32_e32 v226, 16, v226
	v_mul_f32_e32 v226, 0xbfb8aa3b, v226
	v_exp_f32_e32 v226, v226
	s_nop 0
	v_add_f32_e32 v226, 1.0, v226
	v_rcp_f32_e32 v226, v226
	s_nop 0
	v_fma_f32 v228, v178, v226, v64
	v_log_f32_e32 v226, v228
	s_nop 1
	v_mul_f32_e32 v243, 0x3f317217, v226
	v_cndmask_b32_e64 v229, v99, v98, s[86:87]
	v_mad_u64_u32 v[234:235], s[0:1], v229, s13, v[32:33]
	ds_read_u16 v230, v232
	ds_read_u16 v226, v232 offset:512
	ds_read_u16 v229, v234 offset:256
	s_waitcnt lgkmcnt(0)
	v_lshlrev_b32_e32 v229, 16, v229
	v_mul_f32_e32 v229, 0xbfb8aa3b, v229
	v_exp_f32_e32 v229, v229
	s_nop 0
	v_add_f32_e32 v229, 1.0, v229
	v_rcp_f32_e32 v229, v229
	s_nop 0
	v_fma_f32 v232, v178, v229, v64
	v_add_f32_e32 v235, v237, v199
	ds_read_u16 v233, v234
	ds_read_u16 v236, v234 offset:512
	v_log_f32_e32 v178, v232
	v_add_f32_e32 v234, v235, v203
	v_add_f32_e32 v231, v234, v208
	v_mul_f32_e32 v244, 0x3f317217, v178
	v_add_f32_e32 v229, v231, v213
	v_add_f32_e32 v221, v229, v221
	v_add_f32_e32 v213, v221, v225
	v_add_f32_e32 v208, v213, v227
	v_add_f32_e32 v203, v208, v240
	v_add_f32_e32 v199, v203, v241
	v_add_f32_e32 v195, v199, v242
	v_add_f32_e32 v178, v195, v243
	v_add_f32_e32 v175, v178, v244
	ds_write_b32 v101, v175
	s_waitcnt lgkmcnt(0)
	s_barrier
	s_and_saveexec_b64 s[0:1], s[62:63]
	s_cbranch_execnz .LBB0_1156
	s_or_b64 exec, exec, s[0:1]
	s_and_saveexec_b64 s[0:1], s[64:65]
	s_cbranch_execnz .LBB0_1157

.LBB0_1114:
	s_or_b64 exec, exec, s[0:1]
	v_lshlrev_b32_e32 v27, 16, v27
	v_sub_f32_e32 v227, 1.0, v26
	v_lshlrev_b32_e32 v26, 16, v28
	v_mul_f32_e32 v28, 0xbfb8aa3b, v27
	v_exp_f32_e32 v28, v28
	v_add_f32_e32 v0, v0, v176
	v_add_f32_e32 v28, 1.0, v28
	v_rcp_f32_e32 v28, v28
	s_nop 0
	v_mul_f32_e32 v240, v28, v27
	v_lshlrev_b32_e32 v28, 16, v29
	v_mul_f32_e32 v29, 0xbfb8aa3b, v28
	v_exp_f32_e32 v29, v29
	v_sub_f32_e32 v225, 1.0, v41
	v_lshlrev_b32_e32 v27, 16, v171
	v_cvt_pk_bf16_f32 v26, v26, v27
	v_add_f32_e32 v29, 1.0, v29
	v_rcp_f32_e32 v29, v29
	s_nop 0
	v_mul_f32_e32 v244, v29, v28
	v_lshlrev_b32_e32 v29, 16, v173
	v_mul_f32_e32 v41, 0xbfb8aa3b, v29
	v_exp_f32_e32 v41, v41
	v_sub_f32_e32 v241, 1.0, v172
	v_lshlrev_b32_e32 v28, 16, v174
	v_sub_f32_e32 v243, 1.0, v190
	v_add_f32_e32 v41, 1.0, v41
	v_rcp_f32_e32 v41, v41
	s_nop 0
	v_mul_f32_e32 v245, v41, v29
	v_lshlrev_b32_e32 v41, 16, v180
	v_mul_f32_e32 v171, 0xbfb8aa3b, v41
	v_exp_f32_e32 v171, v171
	v_sub_f32_e32 v242, 1.0, v181
	v_lshlrev_b32_e32 v29, 16, v188
	v_cvt_pk_bf16_f32 v27, v28, v29
	v_add_f32_e32 v171, 1.0, v171
	v_rcp_f32_e32 v171, v171
	s_nop 0
	v_mul_f32_e32 v246, v171, v41
	v_lshlrev_b32_e32 v171, 16, v189
	v_mul_f32_e32 v172, 0xbfb8aa3b, v171
	v_exp_f32_e32 v172, v172
	v_lshlrev_b32_e32 v41, 16, v191
	v_sub_f32_e32 v191, 1.0, v192
	v_sub_f32_e32 v192, 1.0, v197
	v_add_f32_e32 v172, 1.0, v172
	v_rcp_f32_e32 v172, v172
	s_nop 0
	v_mul_f32_e32 v247, v172, v171
	v_lshlrev_b32_e32 v172, 16, v193
	v_mul_f32_e32 v173, 0xbfb8aa3b, v172
	v_exp_f32_e32 v173, v173
	v_lshlrev_b32_e32 v171, 16, v194
	v_sub_f32_e32 v193, 1.0, v200
	v_cvt_pk_bf16_f32 v28, v41, v171
	v_add_f32_e32 v173, 1.0, v173
	v_rcp_f32_e32 v173, v173
	s_nop 0
	v_mul_f32_e32 v248, v173, v172
	v_lshlrev_b32_e32 v173, 16, v196
	v_mul_f32_e32 v174, 0xbfb8aa3b, v173
	v_exp_f32_e32 v174, v174
	v_lshlrev_b32_e32 v172, 16, v198
	v_sub_f32_e32 v196, 1.0, v205
	v_add_f32_e32 v174, 1.0, v174
	v_rcp_f32_e32 v174, v174
	s_nop 0
	v_mul_f32_e32 v249, v174, v173
	v_lshlrev_b32_e32 v174, 16, v202
	v_mul_f32_e32 v180, 0xbfb8aa3b, v174
	v_exp_f32_e32 v180, v180
	v_lshlrev_b32_e32 v173, 16, v201
	v_cvt_pk_bf16_f32 v29, v172, v173
	v_add_f32_e32 v180, 1.0, v180
	v_rcp_f32_e32 v180, v180
	s_nop 0
	v_mul_f32_e32 v250, v180, v174
	v_lshlrev_b32_e32 v180, 16, v204
	v_mul_f32_e32 v181, 0xbfb8aa3b, v180
	v_exp_f32_e32 v181, v181
	v_lshlrev_b32_e32 v174, 16, v206
	v_add_f32_e32 v181, 1.0, v181
	v_rcp_f32_e32 v181, v181
	s_nop 0
	v_mul_f32_e32 v251, v181, v180
	v_lshlrev_b32_e32 v181, 16, v207
	v_mul_f32_e32 v188, 0xbfb8aa3b, v181
	v_exp_f32_e32 v188, v188
	v_sub_f32_e32 v197, 1.0, v209
	v_lshlrev_b32_e32 v180, 16, v210
	v_cvt_pk_bf16_f32 v172, v174, v180
	v_add_f32_e32 v188, 1.0, v188
	v_rcp_f32_e32 v188, v188
	s_nop 0
	v_mul_f32_e32 v207, v188, v181
	v_lshlrev_b32_e32 v188, 16, v212
	v_mul_f32_e32 v189, 0xbfb8aa3b, v188
	v_exp_f32_e32 v189, v189
	v_sub_f32_e32 v198, 1.0, v211
	v_lshlrev_b32_e32 v181, 16, v214
	v_add_f32_e32 v189, 1.0, v189
	v_rcp_f32_e32 v189, v189
	s_nop 0
	v_mul_f32_e32 v209, v189, v188
	v_lshlrev_b32_e32 v189, 16, v215
	v_mul_f32_e32 v190, 0xbfb8aa3b, v189
	v_exp_f32_e32 v190, v190
	v_sub_f32_e32 v200, 1.0, v216
	v_lshlrev_b32_e32 v188, 16, v217
	v_cvt_pk_bf16_f32 v173, v181, v188
	v_add_f32_e32 v190, 1.0, v190
	v_rcp_f32_e32 v190, v190
	s_nop 0
	v_mul_f32_e32 v210, v190, v189
	v_lshlrev_b32_e32 v190, 16, v218
	v_mul_f32_e32 v194, 0xbfb8aa3b, v190
	v_exp_f32_e32 v194, v194
	v_sub_f32_e32 v201, 1.0, v219
	v_lshlrev_b32_e32 v189, 16, v220
	v_add_f32_e32 v194, 1.0, v194
	v_rcp_f32_e32 v194, v194
	s_nop 0
	v_mul_f32_e32 v211, v194, v190
	v_lshlrev_b32_e32 v194, 16, v223
	v_mul_f32_e32 v204, 0xbfb8aa3b, v194
	v_exp_f32_e32 v204, v204
	v_sub_f32_e32 v202, 1.0, v222
	v_lshlrev_b32_e32 v190, 16, v224
	v_cvt_pk_bf16_f32 v174, v189, v190
	v_add_f32_e32 v204, 1.0, v204
	v_rcp_f32_e32 v204, v204
	s_nop 0
	v_mul_f32_e32 v212, v204, v194
	v_lshlrev_b32_e32 v204, 16, v226
	v_mul_f32_e32 v206, 0xbfb8aa3b, v204
	v_exp_f32_e32 v206, v206
	v_sub_f32_e32 v205, 1.0, v228
	v_lshlrev_b32_e32 v194, 16, v230
	v_add_f32_e32 v206, 1.0, v206
	s_waitcnt lgkmcnt(1)
	v_lshlrev_b32_e32 v215, 16, v236
	v_mul_f32_e32 v216, 0xbfb8aa3b, v215
	v_exp_f32_e32 v216, v216
	v_rcp_f32_e32 v206, v206
	s_nop 0
	v_mul_f32_e32 v214, v206, v204
	v_sub_f32_e32 v206, 1.0, v232
	v_add_f32_e32 v216, 1.0, v216
	v_lshlrev_b32_e32 v204, 16, v233
	v_rcp_f32_e32 v216, v216
	s_nop 0
	v_mul_f32_e32 v215, v216, v215
	ds_read2st64_b32 v[216:217], v102 offset1:2
	s_waitcnt lgkmcnt(0)
	v_add_f32_e32 v216, v216, v217
	v_mul_f32_e32 v217, 0x3fb8aa3b, v0
	v_exp_f32_e32 v217, v217
	s_nop 0
	v_mul_f32_e32 v217, v240, v217
	v_cvt_pk_bf16_f32 v217, v217, v217
	ds_write_b16 v110, v217
	v_sub_f32_e32 v217, v0, v216
	v_sub_f32_e32 v0, v216, v0
	v_mul_f32_e32 v0, 0x3fb8aa3b, v0
	v_mul_f32_e32 v217, 0x3fb8aa3b, v217
	v_exp_f32_e32 v0, v0
	v_exp_f32_e32 v217, v217
	v_mul_f32_e32 v0, v227, v0
	v_mul_f32_e32 v217, v240, v217
	v_cvt_pk_bf16_f32 v0, v0, v0
	v_cvt_pk_bf16_f32 v217, v217, v217
	ds_write_b16 v110, v0 offset:34816
	v_add_f32_e32 v0, v239, v176
	ds_write_b16 v110, v217 offset:17408
	v_mul_f32_e32 v217, 0x3fb8aa3b, v0
	v_exp_f32_e32 v217, v217
	s_nop 0
	v_mul_f32_e32 v217, v244, v217
	v_cvt_pk_bf16_f32 v217, v217, v217
	ds_write_b16 v110, v217 offset:272
	v_sub_f32_e32 v217, v0, v216
	v_sub_f32_e32 v0, v216, v0
	v_mul_f32_e32 v0, 0x3fb8aa3b, v0
	v_mul_f32_e32 v217, 0x3fb8aa3b, v217
	v_exp_f32_e32 v0, v0
	v_exp_f32_e32 v217, v217
	v_mul_f32_e32 v0, v225, v0
	v_mul_f32_e32 v217, v244, v217
	v_cvt_pk_bf16_f32 v0, v0, v0
	v_cvt_pk_bf16_f32 v217, v217, v217
	ds_write_b16 v110, v0 offset:35088
	v_add_f32_e32 v0, v238, v176
	ds_write_b16 v110, v217 offset:17680
	v_mul_f32_e32 v217, 0x3fb8aa3b, v0
	v_exp_f32_e32 v217, v217
	s_nop 0
	v_mul_f32_e32 v217, v245, v217
	v_cvt_pk_bf16_f32 v217, v217, v217
	ds_write_b16 v110, v217 offset:544
	v_sub_f32_e32 v217, v0, v216
	v_sub_f32_e32 v0, v216, v0
	v_mul_f32_e32 v0, 0x3fb8aa3b, v0
	v_mul_f32_e32 v217, 0x3fb8aa3b, v217
	v_exp_f32_e32 v0, v0
	v_exp_f32_e32 v217, v217
	v_mul_f32_e32 v0, v241, v0
	v_mul_f32_e32 v217, v245, v217
	v_cvt_pk_bf16_f32 v0, v0, v0
	v_cvt_pk_bf16_f32 v217, v217, v217
	ds_write_b16 v110, v0 offset:35360
	v_add_f32_e32 v0, v237, v176
	ds_write_b16 v110, v217 offset:17952
	v_mul_f32_e32 v217, 0x3fb8aa3b, v0
	v_exp_f32_e32 v217, v217
	s_nop 0
	v_mul_f32_e32 v217, v246, v217
	v_cvt_pk_bf16_f32 v217, v217, v217
	ds_write_b16 v110, v217 offset:816
	v_sub_f32_e32 v217, v0, v216
	v_sub_f32_e32 v0, v216, v0
	v_mul_f32_e32 v0, 0x3fb8aa3b, v0
	v_mul_f32_e32 v217, 0x3fb8aa3b, v217
	v_exp_f32_e32 v0, v0
	v_exp_f32_e32 v217, v217
	v_mul_f32_e32 v0, v242, v0
	v_mul_f32_e32 v217, v246, v217
	v_cvt_pk_bf16_f32 v0, v0, v0
	v_cvt_pk_bf16_f32 v217, v217, v217
	ds_write_b16 v110, v0 offset:35632
	v_add_f32_e32 v0, v235, v176
	ds_write_b16 v110, v217 offset:18224
	v_mul_f32_e32 v217, 0x3fb8aa3b, v0
	v_exp_f32_e32 v217, v217
	s_nop 0
	v_mul_f32_e32 v217, v247, v217
	v_cvt_pk_bf16_f32 v217, v217, v217
	ds_write_b16 v110, v217 offset:1088
	v_sub_f32_e32 v217, v0, v216
	v_sub_f32_e32 v0, v216, v0
	v_mul_f32_e32 v0, 0x3fb8aa3b, v0
	v_mul_f32_e32 v217, 0x3fb8aa3b, v217
	v_exp_f32_e32 v0, v0
	v_exp_f32_e32 v217, v217
	v_mul_f32_e32 v0, v243, v0
	v_mul_f32_e32 v217, v247, v217
	v_cvt_pk_bf16_f32 v0, v0, v0
	v_cvt_pk_bf16_f32 v217, v217, v217
	ds_write_b16 v110, v0 offset:35904
	v_add_f32_e32 v0, v234, v176
	ds_write_b16 v110, v217 offset:18496
	v_mul_f32_e32 v217, 0x3fb8aa3b, v0
	v_exp_f32_e32 v217, v217
	s_nop 0
	v_mul_f32_e32 v217, v248, v217
	v_cvt_pk_bf16_f32 v217, v217, v217
	ds_write_b16 v110, v217 offset:1360
	v_sub_f32_e32 v217, v0, v216
	v_sub_f32_e32 v0, v216, v0
	v_mul_f32_e32 v0, 0x3fb8aa3b, v0
	v_exp_f32_e32 v0, v0
	v_mul_f32_e32 v217, 0x3fb8aa3b, v217
	v_exp_f32_e32 v217, v217
	v_mul_f32_e32 v0, v191, v0
	v_cvt_pk_bf16_f32 v0, v0, v0
	ds_write_b16 v110, v0 offset:36176
	v_add_f32_e32 v0, v231, v176
	v_mul_f32_e32 v191, 0x3fb8aa3b, v0
	v_exp_f32_e32 v191, v191
	v_mul_f32_e32 v217, v248, v217
	v_cvt_pk_bf16_f32 v217, v217, v217
	ds_write_b16 v110, v217 offset:18768
	v_mul_f32_e32 v191, v249, v191
	v_cvt_pk_bf16_f32 v191, v191, v191
	ds_write_b16 v110, v191 offset:1632
	v_sub_f32_e32 v191, v0, v216
	v_sub_f32_e32 v0, v216, v0
	v_mul_f32_e32 v0, 0x3fb8aa3b, v0
	v_mul_f32_e32 v191, 0x3fb8aa3b, v191
	v_exp_f32_e32 v0, v0
	v_exp_f32_e32 v191, v191
	v_mul_f32_e32 v0, v192, v0
	v_mul_f32_e32 v191, v249, v191
	v_cvt_pk_bf16_f32 v0, v0, v0
	v_cvt_pk_bf16_f32 v191, v191, v191
	ds_write_b16 v110, v0 offset:36448
	v_add_f32_e32 v0, v229, v176
	ds_write_b16 v110, v191 offset:19040
	v_mul_f32_e32 v191, 0x3fb8aa3b, v0
	v_exp_f32_e32 v191, v191
	s_nop 0
	v_mul_f32_e32 v191, v250, v191
	v_cvt_pk_bf16_f32 v191, v191, v191
	ds_write_b16 v110, v191 offset:1904
	v_sub_f32_e32 v191, v0, v216
	v_sub_f32_e32 v0, v216, v0
	v_mul_f32_e32 v0, 0x3fb8aa3b, v0
	v_mul_f32_e32 v191, 0x3fb8aa3b, v191
	v_exp_f32_e32 v0, v0
	v_exp_f32_e32 v191, v191
	v_mul_f32_e32 v0, v193, v0
	v_mul_f32_e32 v191, v250, v191
	v_cvt_pk_bf16_f32 v0, v0, v0
	v_cvt_pk_bf16_f32 v191, v191, v191
	ds_write_b16 v110, v0 offset:36720
	v_add_f32_e32 v0, v221, v176
	ds_write_b16 v110, v191 offset:19312
	v_mul_f32_e32 v191, 0x3fb8aa3b, v0
	v_exp_f32_e32 v191, v191
	s_nop 0
	v_mul_f32_e32 v191, v251, v191
	v_cvt_pk_bf16_f32 v191, v191, v191
	ds_write_b16 v110, v191 offset:2176
	v_sub_f32_e32 v191, v0, v216
	v_sub_f32_e32 v0, v216, v0
	v_mul_f32_e32 v0, 0x3fb8aa3b, v0
	v_mul_f32_e32 v191, 0x3fb8aa3b, v191
	v_exp_f32_e32 v0, v0
	v_exp_f32_e32 v191, v191
	v_mul_f32_e32 v0, v196, v0
	v_mul_f32_e32 v191, v251, v191
	v_cvt_pk_bf16_f32 v0, v0, v0
	v_cvt_pk_bf16_f32 v191, v191, v191
	ds_write_b16 v110, v0 offset:36992
	v_add_f32_e32 v0, v213, v176
	ds_write_b16 v110, v191 offset:19584
	v_mul_f32_e32 v191, 0x3fb8aa3b, v0
	v_exp_f32_e32 v191, v191
	s_nop 0
	v_mul_f32_e32 v191, v207, v191
	v_cvt_pk_bf16_f32 v191, v191, v191
	ds_write_b16 v110, v191 offset:2448
	v_sub_f32_e32 v191, v0, v216
	v_sub_f32_e32 v0, v216, v0
	v_mul_f32_e32 v0, 0x3fb8aa3b, v0
	v_mul_f32_e32 v191, 0x3fb8aa3b, v191
	v_exp_f32_e32 v0, v0
	v_exp_f32_e32 v191, v191
	v_mul_f32_e32 v0, v197, v0
	v_mul_f32_e32 v191, v207, v191
	v_cvt_pk_bf16_f32 v0, v0, v0
	v_cvt_pk_bf16_f32 v191, v191, v191
	ds_write_b16 v110, v0 offset:37264
	v_add_f32_e32 v0, v208, v176
	ds_write_b16 v110, v191 offset:19856
	v_mul_f32_e32 v191, 0x3fb8aa3b, v0
	v_exp_f32_e32 v191, v191
	s_nop 0
	v_mul_f32_e32 v191, v209, v191
	v_cvt_pk_bf16_f32 v191, v191, v191
	ds_write_b16 v110, v191 offset:2720
	v_sub_f32_e32 v191, v0, v216
	v_sub_f32_e32 v0, v216, v0
	v_mul_f32_e32 v0, 0x3fb8aa3b, v0
	v_mul_f32_e32 v191, 0x3fb8aa3b, v191
	v_exp_f32_e32 v0, v0
	v_exp_f32_e32 v191, v191
	v_mul_f32_e32 v0, v198, v0
	v_mul_f32_e32 v191, v209, v191
	v_cvt_pk_bf16_f32 v0, v0, v0
	v_cvt_pk_bf16_f32 v191, v191, v191
	ds_write_b16 v110, v0 offset:37536
	v_add_f32_e32 v0, v203, v176
	ds_write_b16 v110, v191 offset:20128
	v_mul_f32_e32 v191, 0x3fb8aa3b, v0
	v_exp_f32_e32 v191, v191
	s_nop 0
	v_mul_f32_e32 v191, v210, v191
	v_cvt_pk_bf16_f32 v191, v191, v191
	ds_write_b16 v110, v191 offset:2992
	v_sub_f32_e32 v191, v0, v216
	v_sub_f32_e32 v0, v216, v0
	v_mul_f32_e32 v0, 0x3fb8aa3b, v0
	v_mul_f32_e32 v191, 0x3fb8aa3b, v191
	v_exp_f32_e32 v0, v0
	v_exp_f32_e32 v191, v191
	v_mul_f32_e32 v0, v200, v0
	v_mul_f32_e32 v191, v210, v191
	v_cvt_pk_bf16_f32 v0, v0, v0
	v_cvt_pk_bf16_f32 v191, v191, v191
	ds_write_b16 v110, v0 offset:37808
	v_add_f32_e32 v0, v199, v176
	ds_write_b16 v110, v191 offset:20400
	v_mul_f32_e32 v191, 0x3fb8aa3b, v0
	v_exp_f32_e32 v191, v191
	s_nop 0
	v_mul_f32_e32 v191, v211, v191
	v_cvt_pk_bf16_f32 v191, v191, v191
	ds_write_b16 v110, v191 offset:3264
	v_sub_f32_e32 v191, v0, v216
	v_sub_f32_e32 v0, v216, v0
	v_mul_f32_e32 v0, 0x3fb8aa3b, v0
	v_mul_f32_e32 v191, 0x3fb8aa3b, v191
	v_exp_f32_e32 v0, v0
	v_exp_f32_e32 v191, v191
	v_mul_f32_e32 v0, v201, v0
	v_mul_f32_e32 v191, v211, v191
	v_cvt_pk_bf16_f32 v0, v0, v0
	v_cvt_pk_bf16_f32 v191, v191, v191
	ds_write_b16 v110, v0 offset:38080
	v_add_f32_e32 v0, v195, v176
	ds_write_b16 v110, v191 offset:20672
	v_mul_f32_e32 v191, 0x3fb8aa3b, v0
	v_exp_f32_e32 v191, v191
	s_nop 0
	v_mul_f32_e32 v191, v212, v191
	v_cvt_pk_bf16_f32 v191, v191, v191
	ds_write_b16 v110, v191 offset:3536
	v_sub_f32_e32 v191, v0, v216
	v_sub_f32_e32 v0, v216, v0
	v_mul_f32_e32 v0, 0x3fb8aa3b, v0
	v_exp_f32_e32 v0, v0
	v_mul_f32_e32 v191, 0x3fb8aa3b, v191
	v_exp_f32_e32 v191, v191
	v_mul_f32_e32 v0, v202, v0
	v_cvt_pk_bf16_f32 v0, v0, v0
	ds_write_b16 v110, v0 offset:38352
	v_add_f32_e32 v0, v178, v176
	v_mul_f32_e32 v178, 0x3fb8aa3b, v0
	v_exp_f32_e32 v178, v178
	v_mul_f32_e32 v191, v212, v191
	v_cvt_pk_bf16_f32 v191, v191, v191
	ds_write_b16 v110, v191 offset:20944
	v_mul_f32_e32 v178, v214, v178
	v_cvt_pk_bf16_f32 v178, v178, v178
	ds_write_b16 v110, v178 offset:3808
	v_sub_f32_e32 v178, v0, v216
	v_sub_f32_e32 v0, v216, v0
	v_mul_f32_e32 v0, 0x3fb8aa3b, v0
	v_exp_f32_e32 v0, v0
	v_mul_f32_e32 v178, 0x3fb8aa3b, v178
	v_exp_f32_e32 v178, v178
	v_mul_f32_e32 v0, v205, v0
	v_cvt_pk_bf16_f32 v0, v0, v0
	ds_write_b16 v110, v0 offset:38624
	v_add_f32_e32 v0, v175, v176
	v_mul_f32_e32 v175, 0x3fb8aa3b, v0
	v_exp_f32_e32 v175, v175
	v_mul_f32_e32 v178, v214, v178
	v_cvt_pk_bf16_f32 v178, v178, v178
	ds_write_b16 v110, v178 offset:21216
	v_mul_f32_e32 v175, v215, v175
	v_cvt_pk_bf16_f32 v175, v175, v175
	ds_write_b16 v110, v175 offset:4080
	v_sub_f32_e32 v175, v0, v216
	v_mul_f32_e32 v175, 0x3fb8aa3b, v175
	v_sub_f32_e32 v0, v216, v0
	v_exp_f32_e32 v175, v175
	v_mul_f32_e32 v0, 0x3fb8aa3b, v0
	v_exp_f32_e32 v0, v0
	v_mul_f32_e32 v175, v215, v175
	v_cvt_pk_bf16_f32 v175, v175, v175
	v_mul_f32_e32 v0, v206, v0
	ds_write_b16 v110, v175 offset:21488
	v_cvt_pk_bf16_f32 v0, v0, v0
	ds_write_b16 v110, v0 offset:38896
	v_cvt_pk_bf16_f32 v175, v194, v204
	ds_write_b128 v144, v[26:29] offset:52224
	ds_write_b128 v144, v[172:175] offset:52240
	s_and_saveexec_b64 s[0:1], s[36:37]
	s_cbranch_execz .LBB0_1117
	s_or_b32 s24, s10, s28
	v_readlane_b32 s25, v255, 20
	s_lshl_b32 s88, s24, s25
	s_and_b64 s[24:25], s[86:87], exec
	s_cselect_b32 s24, s95, s33
	s_add_i32 s24, s88, s24
	s_ashr_i32 s25, s24, 31
	v_readlane_b32 s40, v252, 51
	s_lshl_b64 s[24:25], s[24:25], 16
	v_readlane_b32 s54, v253, 1
	v_readlane_b32 s55, v253, 2
	s_add_u32 s88, s54, s24
	s_addc_u32 s89, s55, s25
	s_mov_b64 s[24:25], 0
	v_mov_b32_e32 v26, v100
	v_mov_b32_e32 v27, v30
	v_readlane_b32 s41, v252, 52
	v_readlane_b32 s42, v252, 53
	v_readlane_b32 s43, v252, 54
	v_readlane_b32 s44, v252, 55
	v_readlane_b32 s45, v252, 56
	v_readlane_b32 s46, v252, 57
	v_readlane_b32 s47, v252, 58
	v_readlane_b32 s48, v252, 59
	v_readlane_b32 s49, v252, 60
	v_readlane_b32 s50, v252, 61
	v_readlane_b32 s51, v252, 62
	v_readlane_b32 s52, v252, 63
	v_readlane_b32 s53, v253, 0
.LBB0_1116:
	v_lshlrev_b32_e32 v0, 4, v30
	s_mov_b64 s[24:25], s[88:89]
	global_load_dwordx4 v[2:5], v0, s[24:25]
	s_add_u32 s24, s24, 0x2000
	s_addc_u32 s25, s25, 0
	global_load_dwordx4 v[6:9], v0, s[24:25]
	s_add_u32 s24, s24, 0x2000
	s_addc_u32 s25, s25, 0
	global_load_dwordx4 v[10:13], v0, s[24:25]
	s_add_u32 s24, s24, 0x2000
	s_addc_u32 s25, s25, 0
	global_load_dwordx4 v[14:17], v0, s[24:25]
	s_add_u32 s24, s24, 0x2000
	s_addc_u32 s25, s25, 0
	global_load_dwordx4 v[18:21], v0, s[24:25]
	s_add_u32 s24, s24, 0x2000
	s_addc_u32 s25, s25, 0
	global_load_dwordx4 v[22:25], v0, s[24:25]
	s_add_u32 s24, s24, 0x2000
	s_addc_u32 s25, s25, 0
	global_load_dwordx4 v[172:175], v0, s[24:25]
	s_add_u32 s24, s24, 0x2000
	s_addc_u32 s25, s25, 0
	global_load_dwordx4 v[26:29], v0, s[24:25]
	v_and_b32_e32 v171, 31, v30
	v_lshrrev_b32_e32 v41, 5, v30
	v_mul_u32_u24_e32 v171, 0x440, v171
	v_lshl_add_u32 v171, v41, 1, v171
	v_add_u32_e32 v171, s97, v171
	s_waitcnt vmcnt(7)
	v_cvt_pk_bf16_f32 v2, v2, v2
	v_cvt_pk_bf16_f32 v3, v3, v3
	v_cvt_pk_bf16_f32 v4, v4, v4
	v_cvt_pk_bf16_f32 v5, v5, v5
	ds_write_b16 v171, v2
	ds_write_b16 v171, v3 offset:272
	ds_write_b16 v171, v4 offset:544
	ds_write_b16 v171, v5 offset:816
	s_waitcnt vmcnt(6)
	v_cvt_pk_bf16_f32 v6, v6, v6
	v_cvt_pk_bf16_f32 v7, v7, v7
	v_cvt_pk_bf16_f32 v8, v8, v8
	v_cvt_pk_bf16_f32 v9, v9, v9
	ds_write_b16 v171, v6 offset:32
	ds_write_b16 v171, v7 offset:304
	ds_write_b16 v171, v8 offset:576
	ds_write_b16 v171, v9 offset:848
	s_waitcnt vmcnt(5)
	v_cvt_pk_bf16_f32 v10, v10, v10
	v_cvt_pk_bf16_f32 v11, v11, v11
	v_cvt_pk_bf16_f32 v12, v12, v12
	v_cvt_pk_bf16_f32 v13, v13, v13
	ds_write_b16 v171, v10 offset:64
	ds_write_b16 v171, v11 offset:336
	ds_write_b16 v171, v12 offset:608
	ds_write_b16 v171, v13 offset:880
	s_waitcnt vmcnt(4)
	v_cvt_pk_bf16_f32 v14, v14, v14
	v_cvt_pk_bf16_f32 v15, v15, v15
	v_cvt_pk_bf16_f32 v16, v16, v16
	v_cvt_pk_bf16_f32 v17, v17, v17
	ds_write_b16 v171, v14 offset:96
	ds_write_b16 v171, v15 offset:368
	ds_write_b16 v171, v16 offset:640
	ds_write_b16 v171, v17 offset:912
	s_waitcnt vmcnt(3)
	v_cvt_pk_bf16_f32 v18, v18, v18
	v_cvt_pk_bf16_f32 v19, v19, v19
	v_cvt_pk_bf16_f32 v20, v20, v20
	v_cvt_pk_bf16_f32 v21, v21, v21
	ds_write_b16 v171, v18 offset:128
	ds_write_b16 v171, v19 offset:400
	ds_write_b16 v171, v20 offset:672
	ds_write_b16 v171, v21 offset:944
	s_waitcnt vmcnt(2)
	v_cvt_pk_bf16_f32 v22, v22, v22
	v_cvt_pk_bf16_f32 v23, v23, v23
	v_cvt_pk_bf16_f32 v24, v24, v24
	v_cvt_pk_bf16_f32 v25, v25, v25
	ds_write_b16 v171, v22 offset:160
	ds_write_b16 v171, v23 offset:432
	ds_write_b16 v171, v24 offset:704
	ds_write_b16 v171, v25 offset:976
	s_waitcnt vmcnt(1)
	v_cvt_pk_bf16_f32 v172, v172, v172
	v_cvt_pk_bf16_f32 v173, v173, v173
	v_cvt_pk_bf16_f32 v174, v174, v174
	v_cvt_pk_bf16_f32 v175, v175, v175
	ds_write_b16 v171, v172 offset:192
	ds_write_b16 v171, v173 offset:464
	ds_write_b16 v171, v174 offset:736
	ds_write_b16 v171, v175 offset:1008
	s_waitcnt vmcnt(0)
	v_cvt_pk_bf16_f32 v26, v26, v26
	v_cvt_pk_bf16_f32 v27, v27, v27
	v_cvt_pk_bf16_f32 v28, v28, v28
	v_cvt_pk_bf16_f32 v29, v29, v29
	ds_write_b16 v171, v26 offset:224
	ds_write_b16 v171, v27 offset:496
	ds_write_b16 v171, v28 offset:768
	ds_write_b16 v171, v29 offset:1040

.LBB0_1443:
	s_or_b64 exec, exec, s[0:1]
	s_waitcnt vmcnt(23)
	v_mul_f32_e32 v168, v0, v190
	s_waitcnt vmcnt(9)
	v_lshlrev_b32_e32 v191, 16, v136
	s_waitcnt vmcnt(5)
	v_fma_f32 v168, v168, v191, v72
	v_mul_f32_e32 v191, v1, v190
	v_and_b32_e32 v136, 0xffff0000, v136
	v_fma_f32 v136, v191, v136, v73
	v_mul_f32_e32 v191, v2, v190
	v_lshlrev_b32_e32 v192, 16, v137
	v_fma_f32 v191, v191, v192, v74
	v_mul_f32_e32 v192, v3, v190
	v_and_b32_e32 v137, 0xffff0000, v137
	v_fma_f32 v137, v192, v137, v75
	v_mul_f32_e32 v192, v4, v190
	v_lshlrev_b32_e32 v193, 16, v138
	s_waitcnt vmcnt(4)
	v_fma_f32 v192, v192, v193, v76
	v_mul_f32_e32 v193, v5, v190
	v_and_b32_e32 v138, 0xffff0000, v138
	v_fma_f32 v138, v193, v138, v77
	v_mul_f32_e32 v193, v6, v190
	v_lshlrev_b32_e32 v194, 16, v139
	v_mul_f32_e32 v190, v7, v190
	v_and_b32_e32 v139, 0xffff0000, v139
	v_fma_f32 v193, v193, v194, v78
	v_fma_f32 v139, v190, v139, v79
	v_mul_f32_e32 v190, v8, v188
	v_lshlrev_b32_e32 v194, 16, v124
	v_fmac_f32_e32 v168, v190, v194
	v_mul_f32_e32 v190, v9, v188
	v_and_b32_e32 v124, 0xffff0000, v124
	v_fmac_f32_e32 v136, v190, v124
	v_mul_f32_e32 v124, v10, v188
	v_lshlrev_b32_e32 v190, 16, v125
	v_fmac_f32_e32 v191, v124, v190
	v_mul_f32_e32 v124, v11, v188
	v_and_b32_e32 v125, 0xffff0000, v125
	v_fmac_f32_e32 v137, v124, v125
	v_mul_f32_e32 v124, v12, v188
	v_lshlrev_b32_e32 v125, 16, v126
	v_fmac_f32_e32 v192, v124, v125
	v_mul_f32_e32 v124, v13, v188
	v_and_b32_e32 v125, 0xffff0000, v126
	v_fmac_f32_e32 v138, v124, v125
	v_mul_f32_e32 v124, v14, v188
	v_lshlrev_b32_e32 v125, 16, v127
	v_fmac_f32_e32 v193, v124, v125
	v_mul_f32_e32 v124, v15, v188
	v_and_b32_e32 v125, 0xffff0000, v127
	v_fmac_f32_e32 v139, v124, v125
	v_mul_f32_e32 v124, v16, v189
	v_lshlrev_b32_e32 v125, 16, v128
	v_fmac_f32_e32 v168, v124, v125
	v_mul_f32_e32 v124, v17, v189
	v_and_b32_e32 v125, 0xffff0000, v128
	v_fmac_f32_e32 v136, v124, v125
	v_mul_f32_e32 v124, v18, v189
	v_lshlrev_b32_e32 v125, 16, v129
	v_fmac_f32_e32 v191, v124, v125
	v_mul_f32_e32 v124, v19, v189
	v_and_b32_e32 v125, 0xffff0000, v129
	v_fmac_f32_e32 v137, v124, v125
	v_mul_f32_e32 v124, v20, v189
	v_lshlrev_b32_e32 v125, 16, v130
	v_fmac_f32_e32 v192, v124, v125
	v_mul_f32_e32 v124, v21, v189
	v_and_b32_e32 v125, 0xffff0000, v130
	v_fmac_f32_e32 v138, v124, v125
	v_mul_f32_e32 v124, v22, v189
	v_lshlrev_b32_e32 v125, 16, v131
	v_fmac_f32_e32 v193, v124, v125
	v_mul_f32_e32 v124, v23, v189
	v_and_b32_e32 v125, 0xffff0000, v131
	v_fmac_f32_e32 v139, v124, v125
	v_mul_f32_e32 v124, v24, v187
	s_waitcnt vmcnt(3)
	v_lshlrev_b32_e32 v125, 16, v156
	v_fmac_f32_e32 v168, v124, v125
	v_mul_f32_e32 v124, v25, v187
	v_and_b32_e32 v125, 0xffff0000, v156
	v_fmac_f32_e32 v136, v124, v125
	v_mul_f32_e32 v124, v26, v187
	v_lshlrev_b32_e32 v125, 16, v157
	v_fmac_f32_e32 v191, v124, v125
	v_mul_f32_e32 v124, v27, v187
	v_and_b32_e32 v125, 0xffff0000, v157
	v_fmac_f32_e32 v137, v124, v125
	v_mul_f32_e32 v124, v28, v187
	v_lshlrev_b32_e32 v125, 16, v158
	v_fmac_f32_e32 v192, v124, v125
	v_mul_f32_e32 v124, v29, v187
	v_and_b32_e32 v125, 0xffff0000, v158
	v_fmac_f32_e32 v138, v124, v125
	v_mul_f32_e32 v124, v30, v187
	v_lshlrev_b32_e32 v125, 16, v159
	v_fmac_f32_e32 v193, v124, v125
	v_mul_f32_e32 v124, v31, v187
	v_and_b32_e32 v125, 0xffff0000, v159
	v_fmac_f32_e32 v139, v124, v125
	s_waitcnt vmcnt(2)
	v_lshlrev_b32_e32 v124, 16, v152
	v_fmac_f32_e32 v168, v32, v124
	v_and_b32_e32 v124, 0xffff0000, v152
	v_fmac_f32_e32 v136, v33, v124
	v_lshlrev_b32_e32 v124, 16, v153
	v_fmac_f32_e32 v191, v34, v124
	v_and_b32_e32 v124, 0xffff0000, v153
	v_fmac_f32_e32 v137, v35, v124
	v_lshlrev_b32_e32 v124, 16, v154
	v_fmac_f32_e32 v192, v36, v124
	v_and_b32_e32 v124, 0xffff0000, v154
	v_fmac_f32_e32 v138, v37, v124
	v_lshlrev_b32_e32 v124, 16, v155
	v_fmac_f32_e32 v193, v38, v124
	v_and_b32_e32 v124, 0xffff0000, v155
	v_fmac_f32_e32 v139, v39, v124
	v_mul_f32_e32 v124, v40, v184
	s_waitcnt vmcnt(1)
	v_lshlrev_b32_e32 v125, 16, v148
	v_fmac_f32_e32 v168, v124, v125
	v_mul_f32_e32 v124, v41, v184
	v_and_b32_e32 v125, 0xffff0000, v148
	v_fmac_f32_e32 v136, v124, v125
	v_mul_f32_e32 v124, v42, v184
	v_lshlrev_b32_e32 v125, 16, v149
	v_fmac_f32_e32 v191, v124, v125
	v_mul_f32_e32 v124, v43, v184
	v_and_b32_e32 v125, 0xffff0000, v149
	v_fmac_f32_e32 v137, v124, v125
	v_mul_f32_e32 v124, v44, v184
	v_lshlrev_b32_e32 v125, 16, v150
	v_fmac_f32_e32 v192, v124, v125
	v_mul_f32_e32 v124, v45, v184
	v_and_b32_e32 v125, 0xffff0000, v150
	v_fmac_f32_e32 v138, v124, v125
	v_mul_f32_e32 v124, v46, v184
	v_lshlrev_b32_e32 v125, 16, v151
	v_fmac_f32_e32 v193, v124, v125
	v_mul_f32_e32 v124, v47, v184
	v_and_b32_e32 v125, 0xffff0000, v151
	v_fmac_f32_e32 v139, v124, v125
	v_mul_f32_e32 v124, v48, v186
	v_lshlrev_b32_e32 v125, 16, v120
	v_fmac_f32_e32 v168, v124, v125
	v_mul_f32_e32 v124, v49, v186
	v_and_b32_e32 v120, 0xffff0000, v120
	v_fmac_f32_e32 v136, v124, v120
	v_mul_f32_e32 v120, v50, v186
	v_lshlrev_b32_e32 v124, 16, v121
	v_fmac_f32_e32 v191, v120, v124
	v_mul_f32_e32 v120, v51, v186
	v_and_b32_e32 v121, 0xffff0000, v121
	v_fmac_f32_e32 v137, v120, v121
	v_mul_f32_e32 v120, v52, v186
	v_lshlrev_b32_e32 v121, 16, v122
	v_fmac_f32_e32 v192, v120, v121
	v_mul_f32_e32 v120, v53, v186
	v_and_b32_e32 v121, 0xffff0000, v122
	v_fmac_f32_e32 v138, v120, v121
	v_mul_f32_e32 v120, v54, v186
	v_lshlrev_b32_e32 v121, 16, v123
	v_fmac_f32_e32 v193, v120, v121
	v_mul_f32_e32 v120, v55, v186
	v_and_b32_e32 v121, 0xffff0000, v123
	v_fmac_f32_e32 v139, v120, v121
	v_mul_f32_e32 v120, v56, v183
	v_lshlrev_b32_e32 v121, 16, v112
	v_fmac_f32_e32 v168, v120, v121
	v_mul_f32_e32 v120, v57, v183
	v_and_b32_e32 v112, 0xffff0000, v112
	v_fmac_f32_e32 v136, v120, v112
	v_mul_f32_e32 v112, v58, v183
	v_lshlrev_b32_e32 v120, 16, v113
	v_fmac_f32_e32 v191, v112, v120
	v_mul_f32_e32 v112, v59, v183
	v_and_b32_e32 v113, 0xffff0000, v113
	v_fmac_f32_e32 v137, v112, v113
	v_mul_f32_e32 v112, v60, v183
	v_lshlrev_b32_e32 v113, 16, v114
	v_fmac_f32_e32 v192, v112, v113
	v_mul_f32_e32 v112, v61, v183
	v_and_b32_e32 v113, 0xffff0000, v114
	v_fmac_f32_e32 v138, v112, v113
	v_mul_f32_e32 v112, v62, v183
	v_lshlrev_b32_e32 v113, 16, v115
	v_fmac_f32_e32 v193, v112, v113
	v_mul_f32_e32 v112, v63, v183
	v_and_b32_e32 v113, 0xffff0000, v115
	v_fmac_f32_e32 v139, v112, v113
	v_mul_f32_e32 v112, v64, v180
	v_lshlrev_b32_e32 v113, 16, v96
	v_fmac_f32_e32 v168, v112, v113
	v_mul_f32_e32 v112, v65, v180
	v_and_b32_e32 v96, 0xffff0000, v96
	v_fmac_f32_e32 v136, v112, v96
	v_mul_f32_e32 v96, v66, v180
	v_lshlrev_b32_e32 v112, 16, v97
	v_fmac_f32_e32 v191, v96, v112
	v_mul_f32_e32 v96, v67, v180
	v_and_b32_e32 v97, 0xffff0000, v97
	v_fmac_f32_e32 v137, v96, v97
	v_mul_f32_e32 v96, v68, v180
	v_lshlrev_b32_e32 v97, 16, v98
	v_fmac_f32_e32 v192, v96, v97
	v_mul_f32_e32 v96, v69, v180
	v_and_b32_e32 v97, 0xffff0000, v98
	v_fmac_f32_e32 v138, v96, v97
	v_mul_f32_e32 v96, 0x3d372713, v168
	v_mul_f32_e32 v96, v168, v96
	v_fma_f32 v96, v168, v96, v168
	v_mul_f32_e32 v96, 0x3f4c422a, v96
	v_add_f32_e32 v96, v96, v96
	v_mul_f32_e32 v96, 0x3fb8aa3b, v96
	v_exp_f32_e32 v96, v96
	v_mul_f32_e32 v97, v70, v180
	v_lshlrev_b32_e32 v98, 16, v99
	v_fmac_f32_e32 v193, v97, v98
	v_add_f32_e32 v96, 1.0, v96
	v_mul_f32_e32 v112, v71, v180
	v_and_b32_e32 v99, 0xffff0000, v99
	v_fmac_f32_e32 v139, v112, v99
	v_mul_f32_e32 v99, 0x3d372713, v136
	v_mul_f32_e32 v99, v136, v99
	v_fma_f32 v99, v136, v99, v136
	v_mul_f32_e32 v99, 0x3f4c422a, v99
	v_add_f32_e32 v99, v99, v99
	v_mul_f32_e32 v99, 0x3fb8aa3b, v99
	v_exp_f32_e32 v99, v99
	v_rcp_f32_e32 v97, v96
	s_nop 0
	v_mul_f32_e32 v96, v168, v97
	v_sub_f32_e32 v96, v168, v96
	v_add_f32_e32 v97, 1.0, v99
	s_waitcnt vmcnt(0)
	v_lshlrev_b32_e32 v112, 16, v100
	v_mul_f32_e32 v96, v96, v112
	v_and_b32_e32 v100, 0xffff0000, v100
	v_mul_f32_e32 v112, 0x3d372713, v191
	v_mul_f32_e32 v112, v191, v112
	v_fma_f32 v112, v191, v112, v191
	v_mul_f32_e32 v112, 0x3f4c422a, v112
	v_add_f32_e32 v112, v112, v112
	v_mul_f32_e32 v112, 0x3fb8aa3b, v112
	v_exp_f32_e32 v112, v112
	v_rcp_f32_e32 v98, v97
	s_nop 0
	v_mul_f32_e32 v97, v136, v98
	v_sub_f32_e32 v97, v136, v97
	v_add_f32_e32 v98, 1.0, v112
	v_mul_f32_e32 v97, v97, v100
	v_cvt_pk_bf16_f32 v96, v96, v97
	v_mad_u64_u32 v[132:133], s[0:1], v86, s15, v[166:167]
	v_mul_f32_e32 v99, 0x3d372713, v137
	v_mul_f32_e32 v99, v137, v99
	v_fma_f32 v99, v137, v99, v137
	v_mul_f32_e32 v99, 0x3f4c422a, v99
	v_add_f32_e32 v99, v99, v99
	v_mul_f32_e32 v99, 0x3fb8aa3b, v99
	v_exp_f32_e32 v99, v99
	v_rcp_f32_e32 v97, v98
	s_nop 0
	v_mul_f32_e32 v97, v191, v97
	v_sub_f32_e32 v97, v191, v97
	v_add_f32_e32 v98, 1.0, v99
	v_lshlrev_b32_e32 v112, 16, v101
	v_mul_f32_e32 v97, v97, v112
	v_mov_b32_e32 v86, v133
	v_mul_f32_e32 v112, 0x3d372713, v192
	v_mul_f32_e32 v112, v192, v112
	v_fma_f32 v112, v192, v112, v192
	v_mad_u64_u32 v[86:87], s[0:1], v87, s15, v[86:87]
	v_mul_f32_e32 v112, 0x3f4c422a, v112
	v_mov_b32_e32 v133, v86
	v_mad_u64_u32 v[86:87], s[0:1], v84, s15, v[166:167]
	v_mul_lo_u32 v134, v85, s15
	v_cndmask_b32_e64 v85, 0, 1, s[8:9]
	v_add_f32_e32 v112, v112, v112
	v_add_u32_e32 v87, v134, v87
	v_add_u32_e32 v85, v84, v85
	v_mul_f32_e32 v112, 0x3fb8aa3b, v112
	global_load_dwordx4 v[144:147], v[132:133], off
	global_load_dwordx4 v[140:143], v[86:87], off
	v_mad_i64_i32 v[86:87], s[0:1], v85, s15, v[166:167]
	v_mad_u64_u32 v[84:85], s[0:1], v84, s15, v[164:165]
	v_exp_f32_e32 v112, v112
	v_add_u32_e32 v85, v134, v85
	global_load_dwordx4 v[132:135], v[86:87], off
	global_load_dwordx4 v[84:87], v[84:85], off
	v_rcp_f32_e32 v99, v98
	s_nop 0
	v_mul_f32_e32 v98, v137, v99
	v_add_f32_e32 v99, 1.0, v112
	v_sub_f32_e32 v98, v137, v98
	v_and_b32_e32 v101, 0xffff0000, v101
	v_mul_f32_e32 v98, v98, v101
	v_cvt_pk_bf16_f32 v97, v97, v98
	v_mul_f32_e32 v100, 0x3d372713, v138
	v_mul_f32_e32 v100, v138, v100
	v_fma_f32 v100, v138, v100, v138
	v_mul_f32_e32 v100, 0x3f4c422a, v100
	v_add_f32_e32 v100, v100, v100
	v_mul_f32_e32 v100, 0x3fb8aa3b, v100
	v_exp_f32_e32 v100, v100
	v_rcp_f32_e32 v98, v99
	s_nop 0
	v_mul_f32_e32 v98, v192, v98
	v_sub_f32_e32 v98, v192, v98
	v_add_f32_e32 v99, 1.0, v100
	v_lshlrev_b32_e32 v112, 16, v102
	v_mul_f32_e32 v98, v98, v112
	v_and_b32_e32 v102, 0xffff0000, v102
	v_mul_f32_e32 v112, 0x3d372713, v193
	v_mul_f32_e32 v112, v193, v112
	v_fma_f32 v112, v193, v112, v193
	v_mul_f32_e32 v112, 0x3f4c422a, v112
	v_add_f32_e32 v112, v112, v112
	v_mul_f32_e32 v112, 0x3fb8aa3b, v112
	v_exp_f32_e32 v112, v112
	v_rcp_f32_e32 v100, v99
	s_nop 0
	v_mul_f32_e32 v99, v138, v100
	v_sub_f32_e32 v99, v138, v99
	v_add_f32_e32 v100, 1.0, v112
	v_mul_f32_e32 v99, v99, v102
	v_cvt_pk_bf16_f32 v98, v98, v99
	v_mul_f32_e32 v101, 0x3d372713, v139
	v_mul_f32_e32 v101, v139, v101
	v_fma_f32 v101, v139, v101, v139
	v_mul_f32_e32 v101, 0x3f4c422a, v101
	v_add_f32_e32 v101, v101, v101
	v_mul_f32_e32 v101, 0x3fb8aa3b, v101
	v_exp_f32_e32 v101, v101
	v_rcp_f32_e32 v99, v100
	s_nop 0
	v_mul_f32_e32 v99, v193, v99
	v_sub_f32_e32 v99, v193, v99
	v_add_f32_e32 v100, 1.0, v101
	v_lshlrev_b32_e32 v112, 16, v103
	v_mul_f32_e32 v99, v99, v112
	v_rcp_f32_e32 v101, v100
	s_nop 0
	v_mul_f32_e32 v100, v139, v101
	v_sub_f32_e32 v100, v139, v100
	v_and_b32_e32 v101, 0xffff0000, v103
	v_mul_f32_e32 v100, v100, v101
	v_cvt_pk_bf16_f32 v99, v99, v100
	s_and_saveexec_b64 s[0:1], s[40:41]
	s_cbranch_execz .LBB0_1445
	v_mad_i64_i32 v[100:101], s[8:9], v172, s15, v[164:165]
	global_store_dwordx4 v[100:101], v[96:99], off sc1
